# GEMM K-loops: one static priority raise (s_setprio 1 for waves 0-3 for the whole tile K-loop, back to 0 after it) instead of per-phase toggles
# speedup vs baseline: 1.0055x; 1.0055x over previous
; #define PG8_STAGE(bufoff, gbase, voff) do { _Pragma("unroll") for (int _i = 0; _i < 2; ++_i) \
;         __builtin_amdgcn_global_load_lds((const unsigned*)((const char*)(gbase) + (voff)[_i]), (LAS unsigned*)(lds + (bufoff) + ldsw + _i * 8192), 16, 0, 0); } while (0)
; #define PG8_LDA(dst, b, h) do { _Pragma("unroll") for (int m = 0; m < 4; ++m) _Pragma("unroll") for (int k = 0; k < 2; ++k) dst[m][k] = *(const LAS bf16x8*)(lds + PG8_SA(b, h) + aoff + m * 2048 + k * 1024); } while (0)
; #define PG8_LDB(dst, b, h) do { _Pragma("unroll") for (int n = 0; n < 2; ++n) _Pragma("unroll") for (int k = 0; k < 2; ++k) dst[n][k] = *(const LAS bf16x8*)(lds + PG8_SB(b, h) + boff + n * 2048 + k * 1024); } while (0)
; #define PG8_MMA(ai, bj, At, Bt) do { __builtin_amdgcn_s_setprio(1); _Pragma("unroll") for (int m = 0; m < 4; ++m) _Pragma("unroll") for (int n = 0; n < 2; ++n) _Pragma("unroll") for (int k = 0; k < 2; ++k) \
;         acc[ai][bj][m][n] = __builtin_amdgcn_mfma_f32_16x16x32_bf16(Bt[n][k], At[m][k], acc[ai][bj][m][n], 0, 0, 0); __builtin_amdgcn_s_setprio(0); } while (0)
; #define PG8_WAIT_L(n) asm volatile("s_waitcnt lgkmcnt(" #n ")" ::: "memory")
; #define PG8_BAR __builtin_amdgcn_s_barrier()
; #define PG8_SCHED __builtin_amdgcn_sched_barrier(0)
; template <class Epi>
; __device__ __forceinline__ void gemm_phase(LAS unsigned char* lds, const Gemm g, const StaticOrder& S, const Epi& E) {
;     ...
;         for (int t = 0; t < nt; t += 2) {
;             const bool last = (t == nt - 2);
;             const char* a1 = cA + (size_t)(t + 1) * kstep;
;             const char* a2 = last ? nA : cA + (size_t)(t + 2) * kstep; const char* b2 = last ? nB : cB + (size_t)(t + 2) * kstep;
;             const char* a3 = a2 + kstep; const char* b3 = b2 + kstep;
;             PG8_LDB(B0, 0, 0); PG8_SCHED; PG8_LDA(At, 0, 0); PG8_STAGE(PG8_SA(1, 1), a1 + hstep, voffA);
;             PG8_WAIT_L(8); PG8_BAR; PG8_WAIT_L(0); PG8_MMA(0, 0, At, B0); PG8_BAR; PG8_SCHED;
;             PG8_LDB(B1, 0, 1); PG8_STAGE(PG8_SB(0, 0), b2, voffB);
;             PG8_BAR; PG8_WAIT_L(0); PG8_MMA(0, 1, At, B1); PG8_BAR;
;             PG8_LDA(At, 0, 1); PG8_STAGE(PG8_SA(0, 0), a2, voffA);
;             PG8_BAR; PG8_WAIT_L(0); PG8_MMA(1, 0, At, B0); PG8_BAR; PG8_SCHED;
.LBB0_2078:
	s_ashr_i32 s15, s14, 31
	v_cmp_lt_i64_e32 vcc, s[16:17], v[156:157]
	s_lshl_b64 s[16:17], s[14:15], 19
	s_add_u32 s16, s29, s16
	s_addc_u32 s17, s30, s17
	s_and_b64 s[18:19], vcc, exec
	s_cselect_b32 s15, s17, s23
	s_cselect_b32 s57, s16, s22
	s_ashr_i32 s13, s12, 31
	s_lshl_b64 s[18:19], s[12:13], 19
	s_add_u32 s18, s31, s18
	s_addc_u32 s19, s34, s19
	s_and_b64 s[26:27], vcc, exec
	s_cselect_b32 s13, s19, s25
	s_cselect_b32 s58, s18, s24
	s_add_u32 s22, s22, 0x40080
	s_addc_u32 s23, s23, 0
	s_add_u32 s59, s24, 0x100
	s_addc_u32 s60, s25, 0
	s_mov_b32 s61, -2
	v_cmp_lt_u32_e32 vcc, 0xff, v228
	s_cbranch_vccnz .Lsp_skip_5
	s_setprio 1
.Lsp_skip_5:
	s_add_u32 s0, s22, 0xfffc0080
	s_addc_u32 s1, s23, -1
	s_add_i32 s62, 0, 0x10000
	v_add_u32_e32 v142, s62, v161
	ds_read_b128 v[122:125], v142
	ds_read_b128 v[126:129], v142 offset:1024
	ds_read_b128 v[138:141], v142 offset:2048
	ds_read_b128 v[142:145], v142 offset:3072
	s_cmp_eq_u32 s61, 12
	s_cselect_b32 s27, s15, s1
	s_cselect_b32 s26, s57, s0
	s_cselect_b32 s25, s13, s60
	s_cselect_b32 s24, s58, s59
	v_lshl_add_u64 v[186:187], s[22:23], 0, v[152:153]
	s_add_i32 m0, s21, 0xc000
	ds_read_b128 v[166:169], v165
	ds_read_b128 v[170:173], v165 offset:1024
	ds_read_b128 v[174:177], v165 offset:2048
	ds_read_b128 v[190:193], v165 offset:3072
	ds_read_b128 v[194:197], v165 offset:4096
	ds_read_b128 v[198:201], v165 offset:5120
	ds_read_b128 v[202:205], v165 offset:6144
	ds_read_b128 v[206:209], v165 offset:7168
	global_load_lds_dwordx4 v[186:187], off
	s_add_i32 m0, s21, 0xe000
	v_lshl_add_u64 v[186:187], s[22:23], 0, v[154:155]
	global_load_lds_dwordx4 v[186:187], off
	s_waitcnt lgkmcnt(8)
	s_barrier
	s_waitcnt lgkmcnt(0)
	v_mfma_f32_16x16x32_bf16 v[134:137], v[122:125], v[166:169], 0
	v_mfma_f32_16x16x32_bf16 v[130:133], v[138:141], v[166:169], 0
	v_mfma_f32_16x16x32_bf16 v[118:121], v[122:125], v[174:177], 0
	v_mfma_f32_16x16x32_bf16 v[114:117], v[138:141], v[174:177], 0
	v_mfma_f32_16x16x32_bf16 v[110:113], v[122:125], v[194:197], 0
	v_mfma_f32_16x16x32_bf16 v[106:109], v[138:141], v[194:197], 0
	v_mfma_f32_16x16x32_bf16 v[102:105], v[122:125], v[202:205], 0
	v_mfma_f32_16x16x32_bf16 v[98:101], v[138:141], v[202:205], 0
	v_mfma_f32_16x16x32_bf16 v[134:137], v[126:129], v[170:173], v[134:137]
	v_mfma_f32_16x16x32_bf16 v[130:133], v[142:145], v[170:173], v[130:133]
	v_mfma_f32_16x16x32_bf16 v[118:121], v[126:129], v[190:193], v[118:121]
	v_mfma_f32_16x16x32_bf16 v[114:117], v[142:145], v[190:193], v[114:117]
	v_mfma_f32_16x16x32_bf16 v[110:113], v[126:129], v[198:201], v[110:113]
	v_mfma_f32_16x16x32_bf16 v[106:109], v[142:145], v[198:201], v[106:109]
	v_mfma_f32_16x16x32_bf16 v[102:105], v[126:129], v[206:209], v[102:105]
	v_mfma_f32_16x16x32_bf16 v[98:101], v[142:145], v[206:209], v[98:101]
	s_barrier
	s_add_i32 s0, 0, 0x14000
	s_add_i32 s1, s62, s36
	v_add_u32_e32 v158, s0, v161
	v_lshl_add_u64 v[186:187], s[24:25], 0, v[4:5]
	s_mov_b32 m0, s1
	ds_read_b128 v[210:213], v158
	ds_read_b128 v[214:217], v158 offset:1024
	ds_read_b128 v[218:221], v158 offset:2048
	ds_read_b128 v[222:225], v158 offset:3072
	global_load_lds_dwordx4 v[186:187], off
	s_add_i32 m0, s1, 0x2000
	v_lshl_add_u64 v[226:227], s[24:25], 0, v[146:147]
	global_load_lds_dwordx4 v[226:227], off
	s_barrier
	s_waitcnt lgkmcnt(0)
	v_mfma_f32_16x16x32_bf16 v[70:73], v[210:213], v[166:169], 0
	v_mfma_f32_16x16x32_bf16 v[66:69], v[218:221], v[166:169], 0
	v_mfma_f32_16x16x32_bf16 v[54:57], v[210:213], v[174:177], 0
	v_mfma_f32_16x16x32_bf16 v[50:53], v[218:221], v[174:177], 0
	v_mfma_f32_16x16x32_bf16 v[46:49], v[210:213], v[194:197], 0
	v_mfma_f32_16x16x32_bf16 v[42:45], v[218:221], v[194:197], 0
	v_mfma_f32_16x16x32_bf16 v[38:41], v[210:213], v[202:205], 0
	v_mfma_f32_16x16x32_bf16 v[34:37], v[218:221], v[202:205], 0
	v_mfma_f32_16x16x32_bf16 v[70:73], v[214:217], v[170:173], v[70:73]
	v_mfma_f32_16x16x32_bf16 v[66:69], v[222:225], v[170:173], v[66:69]
	v_mfma_f32_16x16x32_bf16 v[54:57], v[214:217], v[190:193], v[54:57]
	v_mfma_f32_16x16x32_bf16 v[50:53], v[222:225], v[190:193], v[50:53]
	v_mfma_f32_16x16x32_bf16 v[46:49], v[214:217], v[198:201], v[46:49]
	v_mfma_f32_16x16x32_bf16 v[42:45], v[222:225], v[198:201], v[42:45]
	v_mfma_f32_16x16x32_bf16 v[38:41], v[214:217], v[206:209], v[38:41]
	v_mfma_f32_16x16x32_bf16 v[34:37], v[222:225], v[206:209], v[34:37]
	s_mov_b32 m0, s21
	v_lshl_add_u64 v[242:243], s[26:27], 0, v[150:151]
	s_barrier
	ds_read_b128 v[166:169], v165 offset:16384
	ds_read_b128 v[170:173], v165 offset:17408
	ds_read_b128 v[174:177], v165 offset:18432
	ds_read_b128 v[190:193], v165 offset:19456
	ds_read_b128 v[194:197], v165 offset:20480
	ds_read_b128 v[198:201], v165 offset:21504
	ds_read_b128 v[202:205], v165 offset:22528
	ds_read_b128 v[206:209], v165 offset:23552
	global_load_lds_dwordx4 v[242:243], off
	s_mov_b32 m0, s42
	v_lshl_add_u64 v[244:245], s[26:27], 0, v[148:149]
	global_load_lds_dwordx4 v[244:245], off
	s_barrier
	s_waitcnt lgkmcnt(0)
	v_mfma_f32_16x16x32_bf16 v[94:97], v[122:125], v[166:169], 0
	v_mfma_f32_16x16x32_bf16 v[90:93], v[138:141], v[166:169], 0
	v_mfma_f32_16x16x32_bf16 v[86:89], v[122:125], v[174:177], 0
	v_mfma_f32_16x16x32_bf16 v[82:85], v[138:141], v[174:177], 0
	v_mfma_f32_16x16x32_bf16 v[78:81], v[122:125], v[194:197], 0
	v_mfma_f32_16x16x32_bf16 v[74:77], v[138:141], v[194:197], 0
	v_mfma_f32_16x16x32_bf16 v[62:65], v[122:125], v[202:205], 0
	v_mfma_f32_16x16x32_bf16 v[58:61], v[138:141], v[202:205], 0
	v_mfma_f32_16x16x32_bf16 v[94:97], v[126:129], v[170:173], v[94:97]
	v_mfma_f32_16x16x32_bf16 v[90:93], v[142:145], v[170:173], v[90:93]
	v_mfma_f32_16x16x32_bf16 v[86:89], v[126:129], v[190:193], v[86:89]
	v_mfma_f32_16x16x32_bf16 v[82:85], v[142:145], v[190:193], v[82:85]
	v_mfma_f32_16x16x32_bf16 v[78:81], v[126:129], v[198:201], v[78:81]
	v_mfma_f32_16x16x32_bf16 v[74:77], v[142:145], v[198:201], v[74:77]
	v_mfma_f32_16x16x32_bf16 v[62:65], v[126:129], v[206:209], v[62:65]
	v_mfma_f32_16x16x32_bf16 v[58:61], v[142:145], v[206:209], v[58:61]
	s_barrier
; #define PG8_STAGE(bufoff, gbase, voff) do { _Pragma("unroll") for (int _i = 0; _i < 2; ++_i) \
;         __builtin_amdgcn_global_load_lds((const unsigned*)((const char*)(gbase) + (voff)[_i]), (LAS unsigned*)(lds + (bufoff) + ldsw + _i * 8192), 16, 0, 0); } while (0)
; #define PG8_LDA(dst, b, h) do { _Pragma("unroll") for (int m = 0; m < 4; ++m) _Pragma("unroll") for (int k = 0; k < 2; ++k) dst[m][k] = *(const LAS bf16x8*)(lds + PG8_SA(b, h) + aoff + m * 2048 + k * 1024); } while (0)
; #define PG8_LDB(dst, b, h) do { _Pragma("unroll") for (int n = 0; n < 2; ++n) _Pragma("unroll") for (int k = 0; k < 2; ++k) dst[n][k] = *(const LAS bf16x8*)(lds + PG8_SB(b, h) + boff + n * 2048 + k * 1024); } while (0)
; #define PG8_MMA(ai, bj, At, Bt) do { __builtin_amdgcn_s_setprio(1); _Pragma("unroll") for (int m = 0; m < 4; ++m) _Pragma("unroll") for (int n = 0; n < 2; ++n) _Pragma("unroll") for (int k = 0; k < 2; ++k) \
;         acc[ai][bj][m][n] = __builtin_amdgcn_mfma_f32_16x16x32_bf16(Bt[n][k], At[m][k], acc[ai][bj][m][n], 0, 0, 0); __builtin_amdgcn_s_setprio(0); } while (0)
; #define PG8_WAIT_V(n) asm volatile("s_waitcnt vmcnt(" #n ")" ::: "memory")
; #define PG8_WAIT_L(n) asm volatile("s_waitcnt lgkmcnt(" #n ")" ::: "memory")
; #define PG8_BAR __builtin_amdgcn_s_barrier()
; #define PG8_SCHED __builtin_amdgcn_sched_barrier(0)
; template <class Epi>
; __device__ __forceinline__ void gemm_phase(LAS unsigned char* lds, const Gemm g, const StaticOrder& S, const Epi& E) {
;     ...
;             PG8_STAGE(PG8_SB(0, 1), b2 + hstep, voffB);
;             PG8_WAIT_V(6); PG8_BAR; PG8_MMA(1, 1, At, B1); PG8_BAR;
;             PG8_LDB(B0, 1, 0); PG8_SCHED; PG8_LDA(At, 1, 0); PG8_STAGE(PG8_SA(0, 1), a2 + hstep, voffA);
;             PG8_WAIT_L(8); PG8_BAR; PG8_WAIT_L(0); PG8_MMA(0, 0, At, B0); PG8_BAR; PG8_SCHED;
;             PG8_LDB(B1, 1, 1); PG8_STAGE(PG8_SB(1, 0), b3, voffB);
;             PG8_BAR; PG8_WAIT_L(0); PG8_MMA(0, 1, At, B1); PG8_BAR;
	s_add_u32 s62, s24, 0x40000
	s_addc_u32 s63, s25, 0
	s_add_i32 s0, s0, s36
	s_mov_b32 m0, s0
	v_lshl_add_u64 v[122:123], s[62:63], 0, v[4:5]
	global_load_lds_dwordx4 v[122:123], off
	s_add_i32 m0, s0, 0x2000
	v_lshl_add_u64 v[122:123], s[62:63], 0, v[146:147]
	global_load_lds_dwordx4 v[122:123], off
	s_waitcnt vmcnt(6)
	s_barrier
	v_mfma_f32_16x16x32_bf16 v[30:33], v[210:213], v[166:169], 0
	v_mfma_f32_16x16x32_bf16 v[26:29], v[218:221], v[166:169], 0
	v_mfma_f32_16x16x32_bf16 v[22:25], v[210:213], v[174:177], 0
	v_mfma_f32_16x16x32_bf16 v[18:21], v[218:221], v[174:177], 0
	v_mfma_f32_16x16x32_bf16 v[14:17], v[210:213], v[194:197], 0
	v_mfma_f32_16x16x32_bf16 v[10:13], v[218:221], v[194:197], 0
	v_mfma_f32_16x16x32_bf16 v[6:9], v[210:213], v[202:205], 0
	v_mfma_f32_16x16x32_bf16 v[0:3], v[218:221], v[202:205], 0
	v_mfma_f32_16x16x32_bf16 v[30:33], v[214:217], v[170:173], v[30:33]
	v_mfma_f32_16x16x32_bf16 v[26:29], v[222:225], v[170:173], v[26:29]
	v_mfma_f32_16x16x32_bf16 v[22:25], v[214:217], v[190:193], v[22:25]
	v_mfma_f32_16x16x32_bf16 v[18:21], v[222:225], v[190:193], v[18:21]
	v_mfma_f32_16x16x32_bf16 v[14:17], v[214:217], v[198:201], v[14:17]
	v_mfma_f32_16x16x32_bf16 v[10:13], v[222:225], v[198:201], v[10:13]
	v_mfma_f32_16x16x32_bf16 v[6:9], v[214:217], v[206:209], v[6:9]
	v_mfma_f32_16x16x32_bf16 v[0:3], v[222:225], v[206:209], v[0:3]
	s_add_i32 s0, 0, 0x18000
	v_add_u32_e32 v142, s0, v161
	s_barrier
	ds_read_b128 v[122:125], v142
	ds_read_b128 v[126:129], v142 offset:1024
	ds_read_b128 v[138:141], v142 offset:2048
	ds_read_b128 v[142:145], v142 offset:3072
	s_add_u32 s26, s26, 0x40000
	s_addc_u32 s27, s27, 0
	s_mov_b32 m0, s43
	v_lshl_add_u64 v[210:211], s[26:27], 0, v[150:151]
	ds_read_b128 v[166:169], v165 offset:32768
	ds_read_b128 v[170:173], v165 offset:33792
	ds_read_b128 v[174:177], v165 offset:34816
	ds_read_b128 v[190:193], v165 offset:35840
	ds_read_b128 v[194:197], v165 offset:36864
	ds_read_b128 v[198:201], v165 offset:37888
	ds_read_b128 v[202:205], v165 offset:38912
	ds_read_b128 v[206:209], v165 offset:39936
	global_load_lds_dwordx4 v[210:211], off
	s_mov_b32 m0, s48
	v_lshl_add_u64 v[210:211], s[26:27], 0, v[148:149]
	global_load_lds_dwordx4 v[210:211], off
	s_waitcnt lgkmcnt(8)
	s_barrier
	s_waitcnt lgkmcnt(0)
	v_mfma_f32_16x16x32_bf16 v[134:137], v[122:125], v[166:169], v[134:137]
	v_mfma_f32_16x16x32_bf16 v[130:133], v[138:141], v[166:169], v[130:133]
	v_mfma_f32_16x16x32_bf16 v[118:121], v[122:125], v[174:177], v[118:121]
	v_mfma_f32_16x16x32_bf16 v[114:117], v[138:141], v[174:177], v[114:117]
	v_mfma_f32_16x16x32_bf16 v[110:113], v[122:125], v[194:197], v[110:113]
	v_mfma_f32_16x16x32_bf16 v[106:109], v[138:141], v[194:197], v[106:109]
	v_mfma_f32_16x16x32_bf16 v[102:105], v[122:125], v[202:205], v[102:105]
	v_mfma_f32_16x16x32_bf16 v[98:101], v[138:141], v[202:205], v[98:101]
	v_mfma_f32_16x16x32_bf16 v[134:137], v[126:129], v[170:173], v[134:137]
	v_mfma_f32_16x16x32_bf16 v[130:133], v[142:145], v[170:173], v[130:133]
	v_mfma_f32_16x16x32_bf16 v[118:121], v[126:129], v[190:193], v[118:121]
	v_mfma_f32_16x16x32_bf16 v[114:117], v[142:145], v[190:193], v[114:117]
	v_mfma_f32_16x16x32_bf16 v[110:113], v[126:129], v[198:201], v[110:113]
	v_mfma_f32_16x16x32_bf16 v[106:109], v[142:145], v[198:201], v[106:109]
	v_mfma_f32_16x16x32_bf16 v[102:105], v[126:129], v[206:209], v[102:105]
	v_mfma_f32_16x16x32_bf16 v[98:101], v[142:145], v[206:209], v[98:101]
	s_barrier
	s_add_i32 s1, 0, 0x1c000
	s_add_i32 s0, s0, s36
	v_add_u32_e32 v158, s1, v161
	v_lshl_add_u64 v[186:187], v[186:187], 0, s[86:87]
	s_mov_b32 m0, s0
	ds_read_b128 v[210:213], v158
	ds_read_b128 v[214:217], v158 offset:1024
	ds_read_b128 v[218:221], v158 offset:2048
	ds_read_b128 v[222:225], v158 offset:3072
	global_load_lds_dwordx4 v[186:187], off
	s_add_i32 m0, s0, 0x2000
	v_lshl_add_u64 v[186:187], v[226:227], 0, s[86:87]
	global_load_lds_dwordx4 v[186:187], off
	s_barrier
; #define PG8_STAGE(bufoff, gbase, voff) do { _Pragma("unroll") for (int _i = 0; _i < 2; ++_i) \
;         __builtin_amdgcn_global_load_lds((const unsigned*)((const char*)(gbase) + (voff)[_i]), (LAS unsigned*)(lds + (bufoff) + ldsw + _i * 8192), 16, 0, 0); } while (0)
; #define PG8_LDA(dst, b, h) do { _Pragma("unroll") for (int m = 0; m < 4; ++m) _Pragma("unroll") for (int k = 0; k < 2; ++k) dst[m][k] = *(const LAS bf16x8*)(lds + PG8_SA(b, h) + aoff + m * 2048 + k * 1024); } while (0)
; #define PG8_LDB(dst, b, h) do { _Pragma("unroll") for (int n = 0; n < 2; ++n) _Pragma("unroll") for (int k = 0; k < 2; ++k) dst[n][k] = *(const LAS bf16x8*)(lds + PG8_SB(b, h) + boff + n * 2048 + k * 1024); } while (0)
; #define PG8_MMA(ai, bj, At, Bt) do { __builtin_amdgcn_s_setprio(1); _Pragma("unroll") for (int m = 0; m < 4; ++m) _Pragma("unroll") for (int n = 0; n < 2; ++n) _Pragma("unroll") for (int k = 0; k < 2; ++k) \
;         acc[ai][bj][m][n] = __builtin_amdgcn_mfma_f32_16x16x32_bf16(Bt[n][k], At[m][k], acc[ai][bj][m][n], 0, 0, 0); __builtin_amdgcn_s_setprio(0); } while (0)
; #define PG8_WAIT_V(n) asm volatile("s_waitcnt vmcnt(" #n ")" ::: "memory")
; #define PG8_WAIT_L(n) asm volatile("s_waitcnt lgkmcnt(" #n ")" ::: "memory")
; #define PG8_BAR __builtin_amdgcn_s_barrier()
; #define PG8_SCHED __builtin_amdgcn_sched_barrier(0)
; template <class Epi>
; __device__ __forceinline__ void gemm_phase(LAS unsigned char* lds, const Gemm g, const StaticOrder& S, const Epi& E) {
;     ...
;             PG8_LDB(B1, 1, 1); PG8_STAGE(PG8_SB(1, 0), b3, voffB);
;             PG8_BAR; PG8_WAIT_L(0); PG8_MMA(0, 1, At, B1); PG8_BAR;
;             PG8_LDA(At, 1, 1); PG8_STAGE(PG8_SA(1, 0), a3, voffA);
;             PG8_BAR; PG8_WAIT_L(0); PG8_MMA(1, 0, At, B0); PG8_BAR; PG8_SCHED;
;             PG8_STAGE(PG8_SB(1, 1), b3 + hstep, voffB);
;             PG8_WAIT_V(6); PG8_BAR; PG8_MMA(1, 1, At, B1); PG8_BAR;
	s_waitcnt lgkmcnt(0)
	v_mfma_f32_16x16x32_bf16 v[70:73], v[210:213], v[166:169], v[70:73]
	v_mfma_f32_16x16x32_bf16 v[66:69], v[218:221], v[166:169], v[66:69]
	v_mfma_f32_16x16x32_bf16 v[54:57], v[210:213], v[174:177], v[54:57]
	v_mfma_f32_16x16x32_bf16 v[50:53], v[218:221], v[174:177], v[50:53]
	v_mfma_f32_16x16x32_bf16 v[46:49], v[210:213], v[194:197], v[46:49]
	v_mfma_f32_16x16x32_bf16 v[42:45], v[218:221], v[194:197], v[42:45]
	v_mfma_f32_16x16x32_bf16 v[38:41], v[210:213], v[202:205], v[38:41]
	v_mfma_f32_16x16x32_bf16 v[34:37], v[218:221], v[202:205], v[34:37]
	v_mfma_f32_16x16x32_bf16 v[70:73], v[214:217], v[170:173], v[70:73]
	v_mfma_f32_16x16x32_bf16 v[66:69], v[222:225], v[170:173], v[66:69]
	v_mfma_f32_16x16x32_bf16 v[54:57], v[214:217], v[190:193], v[54:57]
	v_mfma_f32_16x16x32_bf16 v[50:53], v[222:225], v[190:193], v[50:53]
	v_mfma_f32_16x16x32_bf16 v[46:49], v[214:217], v[198:201], v[46:49]
	v_mfma_f32_16x16x32_bf16 v[42:45], v[222:225], v[198:201], v[42:45]
	v_mfma_f32_16x16x32_bf16 v[38:41], v[214:217], v[206:209], v[38:41]
	v_mfma_f32_16x16x32_bf16 v[34:37], v[222:225], v[206:209], v[34:37]
	s_mov_b32 m0, s51
	v_lshl_add_u64 v[186:187], v[242:243], 0, s[86:87]
	s_barrier
	ds_read_b128 v[166:169], v165 offset:49152
	ds_read_b128 v[170:173], v165 offset:50176
	ds_read_b128 v[174:177], v165 offset:51200
	ds_read_b128 v[190:193], v165 offset:52224
	ds_read_b128 v[194:197], v165 offset:53248
	ds_read_b128 v[198:201], v165 offset:54272
	ds_read_b128 v[202:205], v165 offset:55296
	ds_read_b128 v[206:209], v165 offset:56320
	global_load_lds_dwordx4 v[186:187], off
	s_mov_b32 m0, s54
	v_lshl_add_u64 v[186:187], v[244:245], 0, s[86:87]
	global_load_lds_dwordx4 v[186:187], off
	s_barrier
	s_waitcnt lgkmcnt(0)
	v_mfma_f32_16x16x32_bf16 v[94:97], v[122:125], v[166:169], v[94:97]
	v_mfma_f32_16x16x32_bf16 v[90:93], v[138:141], v[166:169], v[90:93]
	v_mfma_f32_16x16x32_bf16 v[86:89], v[122:125], v[174:177], v[86:89]
	v_mfma_f32_16x16x32_bf16 v[82:85], v[138:141], v[174:177], v[82:85]
	v_mfma_f32_16x16x32_bf16 v[78:81], v[122:125], v[194:197], v[78:81]
	v_mfma_f32_16x16x32_bf16 v[74:77], v[138:141], v[194:197], v[74:77]
	v_mfma_f32_16x16x32_bf16 v[62:65], v[122:125], v[202:205], v[62:65]
	v_mfma_f32_16x16x32_bf16 v[58:61], v[138:141], v[202:205], v[58:61]
	v_mfma_f32_16x16x32_bf16 v[94:97], v[126:129], v[170:173], v[94:97]
	v_mfma_f32_16x16x32_bf16 v[90:93], v[142:145], v[170:173], v[90:93]
	v_mfma_f32_16x16x32_bf16 v[86:89], v[126:129], v[190:193], v[86:89]
	v_mfma_f32_16x16x32_bf16 v[82:85], v[142:145], v[190:193], v[82:85]
	v_mfma_f32_16x16x32_bf16 v[78:81], v[126:129], v[198:201], v[78:81]
	v_mfma_f32_16x16x32_bf16 v[74:77], v[142:145], v[198:201], v[74:77]
	v_mfma_f32_16x16x32_bf16 v[62:65], v[126:129], v[206:209], v[62:65]
	v_mfma_f32_16x16x32_bf16 v[58:61], v[142:145], v[206:209], v[58:61]
	s_barrier
	s_add_u32 s24, s24, 0x40080
	s_addc_u32 s25, s25, 0
	s_add_i32 s0, s1, s36
	s_mov_b32 m0, s0
	v_lshl_add_u64 v[122:123], s[24:25], 0, v[4:5]
	global_load_lds_dwordx4 v[122:123], off
	s_add_i32 m0, s0, 0x2000
	v_lshl_add_u64 v[122:123], s[24:25], 0, v[146:147]
	global_load_lds_dwordx4 v[122:123], off
	s_waitcnt vmcnt(6)
	s_barrier
	v_mfma_f32_16x16x32_bf16 v[30:33], v[210:213], v[166:169], v[30:33]
	v_mfma_f32_16x16x32_bf16 v[26:29], v[218:221], v[166:169], v[26:29]
	v_mfma_f32_16x16x32_bf16 v[22:25], v[210:213], v[174:177], v[22:25]
	v_mfma_f32_16x16x32_bf16 v[18:21], v[218:221], v[174:177], v[18:21]
	v_mfma_f32_16x16x32_bf16 v[14:17], v[210:213], v[194:197], v[14:17]
	v_mfma_f32_16x16x32_bf16 v[10:13], v[218:221], v[194:197], v[10:13]
	v_mfma_f32_16x16x32_bf16 v[6:9], v[210:213], v[202:205], v[6:9]
	v_mfma_f32_16x16x32_bf16 v[0:3], v[218:221], v[202:205], v[0:3]
	v_mfma_f32_16x16x32_bf16 v[30:33], v[214:217], v[170:173], v[30:33]
	v_mfma_f32_16x16x32_bf16 v[26:29], v[222:225], v[170:173], v[26:29]
	v_mfma_f32_16x16x32_bf16 v[22:25], v[214:217], v[190:193], v[22:25]
	v_mfma_f32_16x16x32_bf16 v[18:21], v[222:225], v[190:193], v[18:21]
	v_mfma_f32_16x16x32_bf16 v[14:17], v[214:217], v[198:201], v[14:17]
	v_mfma_f32_16x16x32_bf16 v[10:13], v[222:225], v[198:201], v[10:13]
	v_mfma_f32_16x16x32_bf16 v[6:9], v[214:217], v[206:209], v[6:9]
	v_mfma_f32_16x16x32_bf16 v[0:3], v[222:225], v[206:209], v[0:3]
	s_add_i32 s61, s61, 2
	s_add_u32 s22, s22, 0x100
	s_addc_u32 s23, s23, 0
	s_add_u32 s59, s59, 0x100
	s_addc_u32 s60, s60, 0
	s_cmp_gt_u32 s61, 13
	s_barrier
	s_cbranch_scc1 .Lpeel_exit_5

; __device__ __forceinline__ unsigned cvt_pk_bf16(float lo, float hi) { unsigned r; asm volatile("s_nop 0\n\tv_cvt_pk_bf16_f32 %0, %1, %2" : "=v"(r) : "v"(lo), "v"(hi)); return r; }
; __device__ __forceinline__ void load_rstd(const float* ss, int row0, f32x4& ra, f32x4& rb) {
;     float t[8];
; #pragma unroll
;     for (int i = 0; i < 8; ++i) t[i] = ss[row0 + (i >> 2) * 128 + (i & 3) * 16];
; #pragma unroll
;     for (int i = 0; i < 4; ++i) { ra[i] = __builtin_amdgcn_rsqf(t[i] * (1.f / 1024.f) + 1e-6f); rb[i] = __builtin_amdgcn_rsqf(t[4 + i] * (1.f / 1024.f) + 1e-6f); }
; }
;     __device__ __forceinline__ void operator()(const f32x4 (&acc)[2][2][4][2], const Unit& u, int wr, int wc, int fr, int fq) const {
;         const int row0 = u.pm * 256 + wr * 64 + fr, col0 = u.pn * 256 + wc * 32 + 8 * fq;
;         f32x4 ra = (f32x4){1.f, 1.f, 1.f, 1.f}, rb = ra;
;         f32x4 swv[4] = {(f32x4){0.f, 0.f, 0.f, 0.f}, (f32x4){0.f, 0.f, 0.f, 0.f}, (f32x4){0.f, 0.f, 0.f, 0.f}, (f32x4){0.f, 0.f, 0.f, 0.f}};
;         if (ss) { load_rstd(ss, row0, ra, rb); const float* swp = sw + (size_t)(u.pm >> 3) * ldc + col0;
;             swv[0] = *(const f32x4*)(swp); swv[1] = *(const f32x4*)(swp + 4); swv[2] = *(const f32x4*)(swp + 128); swv[3] = *(const f32x4*)(swp + 132); }
; #pragma unroll
;         for (int bj = 0; bj < 2; ++bj) {
;             const f32x4 s0 = swv[2 * bj], s1 = swv[2 * bj + 1];
; #pragma unroll
;             for (int ai = 0; ai < 2; ++ai)
; #pragma unroll
;                 for (int m = 0; m < 4; ++m) { const int r = row0 + ai * 128 + m * 16;
;                     const float rstd = ai ? rb[m] : ra[m];
;                     const f32x4 v0 = acc[ai][bj][m][0] * rstd + s0, v1 = acc[ai][bj][m][1] * rstd + s1;
;                     uint4 st; st.x = cvt_pk_bf16(v0[0], v0[1]); st.y = cvt_pk_bf16(v0[2], v0[3]); st.z = cvt_pk_bf16(v1[0], v1[1]); st.w = cvt_pk_bf16(v1[2], v1[3]);
;                     *(uint4*)(O + (size_t)r * ldc + col0 + bj * 128) = st; }
.Lpeel_exit_5:
	s_setprio 0
	v_lshl_add_u32 v174, s20, 8, v159
	v_ashrrev_i32_e32 v175, 31, v174
	v_lshl_add_u64 v[122:123], v[174:175], 2, s[10:11]
	global_load_dword v190, v[122:123], off
	global_load_dword v191, v[122:123], off offset:64
	global_load_dword v192, v[122:123], off offset:128
	global_load_dword v193, v[122:123], off offset:192
	global_load_dword v194, v[122:123], off offset:512
	global_load_dword v195, v[122:123], off offset:576
	global_load_dword v196, v[122:123], off offset:640
	global_load_dword v197, v[122:123], off offset:704
	s_ashr_i32 s0, s20, 3
	s_mul_hi_i32 s23, s0, s52
	s_mul_i32 s22, s0, s52
	s_lshl_b64 s[22:23], s[22:23], 2
	v_lshl_or_b32 v176, s56, 8, v163
	s_add_u32 s22, s49, s22
	s_addc_u32 s23, s50, s23
	v_ashrrev_i32_e32 v177, 31, v176
	v_lshl_add_u64 v[200:201], v[176:177], 2, s[22:23]
	global_load_dwordx4 v[138:141], v[200:201], off offset:16
	global_load_dwordx4 v[142:145], v[200:201], off
	global_load_dwordx4 v[122:125], v[200:201], off offset:528
	global_load_dwordx4 v[126:129], v[200:201], off offset:512
	s_and_b64 vcc, exec, s[4:5]
	s_mov_b32 s56, s12
	s_mov_b32 s20, s14
	s_mov_b64 s[24:25], s[18:19]
	s_waitcnt vmcnt(4)
	v_fmamk_f32 v202, v190, 0x3a800000, v229
	v_rsq_f32_e32 v172, v202
	v_fmamk_f32 v202, v194, 0x3a800000, v229
	v_rsq_f32_e32 v164, v202
	v_fmamk_f32 v202, v191, 0x3a800000, v229
	v_rsq_f32_e32 v170, v202
	v_fmamk_f32 v202, v195, 0x3a800000, v229
	v_rsq_f32_e32 v162, v202
	v_fmamk_f32 v202, v192, 0x3a800000, v229
	v_rsq_f32_e32 v168, v202
	v_fmamk_f32 v202, v196, 0x3a800000, v229
	v_rsq_f32_e32 v160, v202
	v_fmamk_f32 v202, v193, 0x3a800000, v229
	v_fmamk_f32 v203, v197, 0x3a800000, v229
	v_rsq_f32_e32 v166, v202
	v_rsq_f32_e32 v158, v203
	s_waitcnt vmcnt(0)
	v_pk_fma_f32 v[130:131], v[130:131], v[172:173], v[138:139] op_sel_hi:[1,0,1]
	v_pk_fma_f32 v[136:137], v[136:137], v[172:173], v[144:145] op_sel_hi:[1,0,1]
	v_pk_fma_f32 v[134:135], v[134:135], v[172:173], v[142:143] op_sel_hi:[1,0,1]
	v_pk_fma_f32 v[132:133], v[132:133], v[172:173], v[140:141] op_sel_hi:[1,0,1]
	s_nop 0
	v_cvt_pk_bf16_f32 v134, v134, v135
	s_nop 0
	v_cvt_pk_bf16_f32 v135, v136, v137
	s_nop 0
	v_cvt_pk_bf16_f32 v136, v130, v131
	v_mad_i64_i32 v[130:131], s[22:23], v174, s52, 0
	s_nop 0
	v_cvt_pk_bf16_f32 v137, v132, v133
	v_lshl_add_u64 v[130:131], v[130:131], 1, s[8:9]
	v_lshlrev_b64 v[132:133], 1, v[176:177]
	v_lshl_add_u64 v[130:131], v[130:131], 0, v[132:133]
	global_store_dwordx4 v[130:131], v[134:137], off
	v_pk_fma_f32 v[118:119], v[118:119], v[170:171], v[142:143] op_sel_hi:[1,0,1]
	v_pk_fma_f32 v[114:115], v[114:115], v[170:171], v[138:139] op_sel_hi:[1,0,1]
	v_or_b32_e32 v136, 16, v174
	v_pk_fma_f32 v[120:121], v[120:121], v[170:171], v[144:145] op_sel_hi:[1,0,1]
	v_pk_fma_f32 v[134:135], v[116:117], v[170:171], v[140:141] op_sel_hi:[1,0,1]
	s_nop 0
	v_cvt_pk_bf16_f32 v116, v118, v119
	s_nop 0
	v_cvt_pk_bf16_f32 v117, v120, v121
	s_nop 0
	v_cvt_pk_bf16_f32 v118, v114, v115
	v_mad_i64_i32 v[114:115], s[22:23], v136, s52, 0
	v_lshl_add_u64 v[114:115], v[114:115], 1, s[8:9]
	v_lshl_add_u64 v[114:115], v[114:115], 0, v[132:133]
	s_nop 0
	v_cvt_pk_bf16_f32 v119, v134, v135
	global_store_dwordx4 v[114:115], v[116:119], off
	v_pk_fma_f32 v[110:111], v[110:111], v[168:169], v[142:143] op_sel_hi:[1,0,1]
	v_pk_fma_f32 v[106:107], v[106:107], v[168:169], v[138:139] op_sel_hi:[1,0,1]
	v_or_b32_e32 v118, 32, v174
	v_pk_fma_f32 v[112:113], v[112:113], v[168:169], v[144:145] op_sel_hi:[1,0,1]
	v_pk_fma_f32 v[116:117], v[108:109], v[168:169], v[140:141] op_sel_hi:[1,0,1]
	s_nop 0
	v_cvt_pk_bf16_f32 v108, v110, v111
	s_nop 0
	v_cvt_pk_bf16_f32 v109, v112, v113
	s_nop 0
	v_cvt_pk_bf16_f32 v110, v106, v107
	v_mad_i64_i32 v[106:107], s[22:23], v118, s52, 0
	v_lshl_add_u64 v[106:107], v[106:107], 1, s[8:9]
	v_lshl_add_u64 v[106:107], v[106:107], 0, v[132:133]
	s_nop 0
	v_cvt_pk_bf16_f32 v111, v116, v117
	global_store_dwordx4 v[106:107], v[108:111], off
	v_pk_fma_f32 v[102:103], v[102:103], v[166:167], v[142:143] op_sel_hi:[1,0,1]
	v_pk_fma_f32 v[104:105], v[104:105], v[166:167], v[144:145] op_sel_hi:[1,0,1]
	v_or_b32_e32 v110, 48, v174
	v_pk_fma_f32 v[108:109], v[100:101], v[166:167], v[140:141] op_sel_hi:[1,0,1]
	v_pk_fma_f32 v[100:101], v[98:99], v[166:167], v[138:139] op_sel_hi:[1,0,1]
	s_nop 0
	v_cvt_pk_bf16_f32 v98, v102, v103
	v_mad_i64_i32 v[102:103], s[22:23], v110, s52, 0
	v_lshl_add_u64 v[102:103], v[102:103], 1, s[8:9]
	s_nop 0
	v_cvt_pk_bf16_f32 v99, v104, v105
	s_nop 0
	v_cvt_pk_bf16_f32 v100, v100, v101
	v_lshl_add_u64 v[102:103], v[102:103], 0, v[132:133]
	s_nop 0
	v_cvt_pk_bf16_f32 v101, v108, v109
	global_store_dwordx4 v[102:103], v[98:101], off
	v_pk_fma_f32 v[94:95], v[94:95], v[164:165], v[142:143] op_sel_hi:[1,0,1]
	v_pk_fma_f32 v[96:97], v[96:97], v[164:165], v[144:145] op_sel_hi:[1,0,1]
	v_add_u32_e32 v100, 0x80, v174
	v_pk_fma_f32 v[98:99], v[92:93], v[164:165], v[140:141] op_sel_hi:[1,0,1]
	v_pk_fma_f32 v[92:93], v[90:91], v[164:165], v[138:139] op_sel_hi:[1,0,1]
	s_nop 0
	v_cvt_pk_bf16_f32 v90, v94, v95
	v_mad_i64_i32 v[94:95], s[22:23], v100, s52, 0
	v_lshl_add_u64 v[94:95], v[94:95], 1, s[8:9]
	s_nop 0
	v_cvt_pk_bf16_f32 v91, v96, v97
	s_nop 0
	v_cvt_pk_bf16_f32 v92, v92, v93
	v_lshl_add_u64 v[94:95], v[94:95], 0, v[132:133]
	s_nop 0
	v_cvt_pk_bf16_f32 v93, v98, v99
	global_store_dwordx4 v[94:95], v[90:93], off
	v_pk_fma_f32 v[86:87], v[86:87], v[162:163], v[142:143] op_sel_hi:[1,0,1]
	v_pk_fma_f32 v[88:89], v[88:89], v[162:163], v[144:145] op_sel_hi:[1,0,1]
	v_add_u32_e32 v92, 0x90, v174
	v_pk_fma_f32 v[90:91], v[84:85], v[162:163], v[140:141] op_sel_hi:[1,0,1]
; __device__ __forceinline__ unsigned cvt_pk_bf16(float lo, float hi) { unsigned r; asm volatile("s_nop 0\n\tv_cvt_pk_bf16_f32 %0, %1, %2" : "=v"(r) : "v"(lo), "v"(hi)); return r; }
; #define PG8_WAIT_V(n) asm volatile("s_waitcnt vmcnt(" #n ")" ::: "memory")
; #define PG8_BAR __builtin_amdgcn_s_barrier()
; template <class Epi>
; __device__ __forceinline__ void gemm_phase(LAS unsigned char* lds, const Gemm g, const StaticOrder& S, const Epi& E) {
;     ...
;     PG8_WAIT_V(0);
;     if (wr == 0) PG8_BAR;
;     PG8_BAR;
;     __device__ __forceinline__ void operator()(const f32x4 (&acc)[2][2][4][2], const Unit& u, int wr, int wc, int fr, int fq) const {
;     ...
;                 for (int m = 0; m < 4; ++m) { const int r = row0 + ai * 128 + m * 16;
;                     const float rstd = ai ? rb[m] : ra[m];
;                     const f32x4 v0 = acc[ai][bj][m][0] * rstd + s0, v1 = acc[ai][bj][m][1] * rstd + s1;
;                     uint4 st; st.x = cvt_pk_bf16(v0[0], v0[1]); st.y = cvt_pk_bf16(v0[2], v0[3]); st.z = cvt_pk_bf16(v1[0], v1[1]); st.w = cvt_pk_bf16(v1[2], v1[3]);
;                     *(uint4*)(O + (size_t)r * ldc + col0 + bj * 128) = st; }
	v_pk_fma_f32 v[84:85], v[82:83], v[162:163], v[138:139] op_sel_hi:[1,0,1]
	s_nop 0
	v_cvt_pk_bf16_f32 v82, v86, v87
	v_mad_i64_i32 v[86:87], s[22:23], v92, s52, 0
	v_lshl_add_u64 v[86:87], v[86:87], 1, s[8:9]
	s_nop 0
	v_cvt_pk_bf16_f32 v83, v88, v89
	s_nop 0
	v_cvt_pk_bf16_f32 v84, v84, v85
	v_lshl_add_u64 v[86:87], v[86:87], 0, v[132:133]
	s_nop 0
	v_cvt_pk_bf16_f32 v85, v90, v91
	global_store_dwordx4 v[86:87], v[82:85], off
	v_pk_fma_f32 v[78:79], v[78:79], v[160:161], v[142:143] op_sel_hi:[1,0,1]
	v_pk_fma_f32 v[80:81], v[80:81], v[160:161], v[144:145] op_sel_hi:[1,0,1]
	v_add_u32_e32 v84, 0xa0, v174
	v_pk_fma_f32 v[82:83], v[76:77], v[160:161], v[140:141] op_sel_hi:[1,0,1]
	v_pk_fma_f32 v[76:77], v[74:75], v[160:161], v[138:139] op_sel_hi:[1,0,1]
	s_nop 0
	v_cvt_pk_bf16_f32 v74, v78, v79
	v_mad_i64_i32 v[78:79], s[22:23], v84, s52, 0
	v_lshl_add_u64 v[78:79], v[78:79], 1, s[8:9]
	s_nop 0
	v_cvt_pk_bf16_f32 v75, v80, v81
	s_nop 0
	v_cvt_pk_bf16_f32 v76, v76, v77
	v_lshl_add_u64 v[78:79], v[78:79], 0, v[132:133]
	s_nop 0
	v_cvt_pk_bf16_f32 v77, v82, v83
	global_store_dwordx4 v[78:79], v[74:77], off
	v_pk_fma_f32 v[62:63], v[62:63], v[158:159], v[142:143] op_sel_hi:[1,0,1]
	v_pk_fma_f32 v[64:65], v[64:65], v[158:159], v[144:145] op_sel_hi:[1,0,1]
	v_add_u32_e32 v76, 0xb0, v174
	v_pk_fma_f32 v[74:75], v[60:61], v[158:159], v[140:141] op_sel_hi:[1,0,1]
	v_pk_fma_f32 v[60:61], v[58:59], v[158:159], v[138:139] op_sel_hi:[1,0,1]
	s_nop 0
	v_cvt_pk_bf16_f32 v58, v62, v63
	v_mad_i64_i32 v[62:63], s[22:23], v76, s52, 0
	v_lshl_add_u64 v[62:63], v[62:63], 1, s[8:9]
	s_nop 0
	v_cvt_pk_bf16_f32 v59, v64, v65
	v_lshl_add_u64 v[62:63], v[62:63], 0, v[132:133]
	s_nop 0
	v_cvt_pk_bf16_f32 v60, v60, v61
	s_nop 0
	v_cvt_pk_bf16_f32 v61, v74, v75
	global_store_dwordx4 v[62:63], v[58:61], off
	v_pk_fma_f32 v[64:65], v[68:69], v[172:173], v[124:125] op_sel_hi:[1,0,1]
	v_pk_fma_f32 v[66:67], v[66:67], v[172:173], v[122:123] op_sel_hi:[1,0,1]
	v_pk_fma_f32 v[58:59], v[70:71], v[172:173], v[126:127] op_sel_hi:[1,0,1]
	v_pk_fma_f32 v[60:61], v[72:73], v[172:173], v[128:129] op_sel_hi:[1,0,1]
	s_nop 0
	v_cvt_pk_bf16_f32 v58, v58, v59
	v_pk_fma_f32 v[56:57], v[56:57], v[170:171], v[128:129] op_sel_hi:[1,0,1]
	s_nop 0
	v_cvt_pk_bf16_f32 v59, v60, v61
	s_nop 0
	v_cvt_pk_bf16_f32 v60, v66, v67
	s_nop 0
	v_cvt_pk_bf16_f32 v61, v64, v65
	global_store_dwordx4 v[130:131], v[58:61], off offset:256
	v_pk_fma_f32 v[54:55], v[54:55], v[170:171], v[126:127] op_sel_hi:[1,0,1]
	v_pk_fma_f32 v[48:49], v[48:49], v[168:169], v[128:129] op_sel_hi:[1,0,1]
	v_pk_fma_f32 v[58:59], v[52:53], v[170:171], v[124:125] op_sel_hi:[1,0,1]
	v_pk_fma_f32 v[52:53], v[50:51], v[170:171], v[122:123] op_sel_hi:[1,0,1]
	s_nop 0
	v_cvt_pk_bf16_f32 v50, v54, v55
	s_nop 0
	v_cvt_pk_bf16_f32 v51, v56, v57
	v_pk_fma_f32 v[46:47], v[46:47], v[168:169], v[126:127] op_sel_hi:[1,0,1]
	s_nop 0
	v_cvt_pk_bf16_f32 v52, v52, v53
	s_nop 0
	v_cvt_pk_bf16_f32 v53, v58, v59
	global_store_dwordx4 v[114:115], v[50:53], off offset:256
	v_pk_fma_f32 v[40:41], v[40:41], v[166:167], v[128:129] op_sel_hi:[1,0,1]
	v_pk_fma_f32 v[38:39], v[38:39], v[166:167], v[126:127] op_sel_hi:[1,0,1]
	v_pk_fma_f32 v[50:51], v[44:45], v[168:169], v[124:125] op_sel_hi:[1,0,1]
	v_pk_fma_f32 v[44:45], v[42:43], v[168:169], v[122:123] op_sel_hi:[1,0,1]
	s_nop 0
	v_cvt_pk_bf16_f32 v42, v46, v47
	s_nop 0
	v_cvt_pk_bf16_f32 v43, v48, v49
	v_pk_fma_f32 v[32:33], v[32:33], v[164:165], v[128:129] op_sel_hi:[1,0,1]
	s_nop 0
	v_cvt_pk_bf16_f32 v44, v44, v45
	s_nop 0
	v_cvt_pk_bf16_f32 v45, v50, v51
	global_store_dwordx4 v[106:107], v[42:45], off offset:256
	v_pk_fma_f32 v[30:31], v[30:31], v[164:165], v[126:127] op_sel_hi:[1,0,1]
	v_pk_fma_f32 v[24:25], v[24:25], v[162:163], v[128:129] op_sel_hi:[1,0,1]
	v_pk_fma_f32 v[42:43], v[36:37], v[166:167], v[124:125] op_sel_hi:[1,0,1]
	v_pk_fma_f32 v[36:37], v[34:35], v[166:167], v[122:123] op_sel_hi:[1,0,1]
	s_nop 0
	v_cvt_pk_bf16_f32 v34, v38, v39
	s_nop 0
	v_cvt_pk_bf16_f32 v35, v40, v41
	v_pk_fma_f32 v[22:23], v[22:23], v[162:163], v[126:127] op_sel_hi:[1,0,1]
	s_nop 0
	v_cvt_pk_bf16_f32 v36, v36, v37
	s_nop 0
	v_cvt_pk_bf16_f32 v37, v42, v43
	global_store_dwordx4 v[102:103], v[34:37], off offset:256
	v_pk_fma_f32 v[16:17], v[16:17], v[160:161], v[128:129] op_sel_hi:[1,0,1]
	v_pk_fma_f32 v[14:15], v[14:15], v[160:161], v[126:127] op_sel_hi:[1,0,1]
	v_pk_fma_f32 v[34:35], v[28:29], v[164:165], v[124:125] op_sel_hi:[1,0,1]
	v_pk_fma_f32 v[28:29], v[26:27], v[164:165], v[122:123] op_sel_hi:[1,0,1]
	s_nop 0
	v_cvt_pk_bf16_f32 v26, v30, v31
	s_nop 0
	v_cvt_pk_bf16_f32 v27, v32, v33
	s_mov_b64 s[22:23], s[16:17]
	s_nop 0
	v_cvt_pk_bf16_f32 v28, v28, v29
	s_nop 0
	v_cvt_pk_bf16_f32 v29, v34, v35
	global_store_dwordx4 v[94:95], v[26:29], off offset:256
	v_pk_fma_f32 v[8:9], v[8:9], v[158:159], v[128:129] op_sel_hi:[1,0,1]
	v_pk_fma_f32 v[6:7], v[6:7], v[158:159], v[126:127] op_sel_hi:[1,0,1]
	v_pk_fma_f32 v[26:27], v[20:21], v[162:163], v[124:125] op_sel_hi:[1,0,1]
	v_pk_fma_f32 v[20:21], v[18:19], v[162:163], v[122:123] op_sel_hi:[1,0,1]
	s_nop 0
	v_cvt_pk_bf16_f32 v18, v22, v23
	s_nop 0
	v_cvt_pk_bf16_f32 v19, v24, v25
	s_nop 0
	s_nop 0
	v_cvt_pk_bf16_f32 v20, v20, v21
	s_nop 0
	v_cvt_pk_bf16_f32 v21, v26, v27
	global_store_dwordx4 v[86:87], v[18:21], off offset:256
	s_nop 1
	v_pk_fma_f32 v[18:19], v[12:13], v[160:161], v[124:125] op_sel_hi:[1,0,1]
	v_pk_fma_f32 v[12:13], v[10:11], v[160:161], v[122:123] op_sel_hi:[1,0,1]
	s_nop 0
	v_cvt_pk_bf16_f32 v10, v14, v15
	s_nop 0
	v_cvt_pk_bf16_f32 v11, v16, v17
	s_nop 0
	s_nop 0
	v_cvt_pk_bf16_f32 v12, v12, v13
	s_nop 0
	v_cvt_pk_bf16_f32 v13, v18, v19
	global_store_dwordx4 v[78:79], v[10:13], off offset:256
	s_nop 1
	v_pk_fma_f32 v[10:11], v[2:3], v[158:159], v[124:125] op_sel_hi:[1,0,1]
	v_pk_fma_f32 v[2:3], v[0:1], v[158:159], v[122:123] op_sel_hi:[1,0,1]
	s_nop 0
	v_cvt_pk_bf16_f32 v0, v6, v7
	s_nop 0
	v_cvt_pk_bf16_f32 v1, v8, v9
	s_nop 0
	s_nop 0
	v_cvt_pk_bf16_f32 v2, v2, v3
	s_nop 0
	v_cvt_pk_bf16_f32 v3, v10, v11
	global_store_dwordx4 v[62:63], v[0:3], off offset:256
	s_cbranch_vccz .LBB0_2076
	s_waitcnt vmcnt(0)
	s_cmpk_gt_u32 s28, 0xff
	s_cbranch_scc1 .LBB0_2083
	s_barrier

; #define PG8_STAGE(bufoff, gbase, voff) do { _Pragma("unroll") for (int _i = 0; _i < 2; ++_i) \
;         __builtin_amdgcn_global_load_lds((const unsigned*)((const char*)(gbase) + (voff)[_i]), (LAS unsigned*)(lds + (bufoff) + ldsw + _i * 8192), 16, 0, 0); } while (0)
; #define PG8_LDA(dst, b, h) do { _Pragma("unroll") for (int m = 0; m < 4; ++m) _Pragma("unroll") for (int k = 0; k < 2; ++k) dst[m][k] = *(const LAS bf16x8*)(lds + PG8_SA(b, h) + aoff + m * 2048 + k * 1024); } while (0)
; #define PG8_LDB(dst, b, h) do { _Pragma("unroll") for (int n = 0; n < 2; ++n) _Pragma("unroll") for (int k = 0; k < 2; ++k) dst[n][k] = *(const LAS bf16x8*)(lds + PG8_SB(b, h) + boff + n * 2048 + k * 1024); } while (0)
; #define PG8_MMA(ai, bj, At, Bt) do { __builtin_amdgcn_s_setprio(1); _Pragma("unroll") for (int m = 0; m < 4; ++m) _Pragma("unroll") for (int n = 0; n < 2; ++n) _Pragma("unroll") for (int k = 0; k < 2; ++k) \
;         acc[ai][bj][m][n] = __builtin_amdgcn_mfma_f32_16x16x32_bf16(Bt[n][k], At[m][k], acc[ai][bj][m][n], 0, 0, 0); __builtin_amdgcn_s_setprio(0); } while (0)
; #define PG8_WAIT_L(n) asm volatile("s_waitcnt lgkmcnt(" #n ")" ::: "memory")
; #define PG8_BAR __builtin_amdgcn_s_barrier()
; #define PG8_SCHED __builtin_amdgcn_sched_barrier(0)
; template <class Epi>
; __device__ __forceinline__ void gemm_phase(LAS unsigned char* lds, const Gemm g, const StaticOrder& S, const Epi& E) {
;     ...
;         for (int t = 0; t < nt; t += 2) {
;             const bool last = (t == nt - 2);
;             const char* a1 = cA + (size_t)(t + 1) * kstep;
;             const char* a2 = last ? nA : cA + (size_t)(t + 2) * kstep; const char* b2 = last ? nB : cB + (size_t)(t + 2) * kstep;
;             const char* a3 = a2 + kstep; const char* b3 = b2 + kstep;
;             PG8_LDB(B0, 0, 0); PG8_SCHED; PG8_LDA(At, 0, 0); PG8_STAGE(PG8_SA(1, 1), a1 + hstep, voffA);
;             PG8_WAIT_L(8); PG8_BAR; PG8_WAIT_L(0); PG8_MMA(0, 0, At, B0); PG8_BAR; PG8_SCHED;
;             PG8_LDB(B1, 0, 1); PG8_STAGE(PG8_SB(0, 0), b2, voffB);
;             PG8_BAR; PG8_WAIT_L(0); PG8_MMA(0, 1, At, B1); PG8_BAR;
;             PG8_LDA(At, 0, 1); PG8_STAGE(PG8_SA(0, 0), a2, voffA);
;             PG8_BAR; PG8_WAIT_L(0); PG8_MMA(1, 0, At, B0); PG8_BAR; PG8_SCHED;
.LBB0_2402:
	s_add_u32 s39, s14, 0x100
	s_addc_u32 s40, s15, 0
	s_mov_b32 s41, -2
	v_cmp_lt_u32_e32 vcc, 0xff, v228
	s_cbranch_vccnz .Lsp_skip_4
	s_setprio 1
.Lsp_skip_4:
	s_add_u32 s14, s12, 0x100
	s_addc_u32 s15, s13, 0
	s_add_i32 s0, 0, 0x10000
	v_add_u32_e32 v156, s0, v141
	ds_read_b128 v[144:147], v156
	ds_read_b128 v[148:151], v156 offset:1024
	ds_read_b128 v[152:155], v156 offset:2048
	ds_read_b128 v[156:159], v156 offset:3072
	s_cmp_eq_u32 s41, 2
	s_cselect_b32 s19, s7, s15
	s_cselect_b32 s18, s6, s14
	s_cselect_b32 s17, s9, s40
	s_cselect_b32 s16, s8, s39
	v_lshl_add_u64 v[176:177], s[12:13], 0, v[136:137]
	s_add_i32 m0, s26, 0xc000
	ds_read_b128 v[160:163], v143
	ds_read_b128 v[164:167], v143 offset:1024
	ds_read_b128 v[168:171], v143 offset:2048
	ds_read_b128 v[172:175], v143 offset:3072
	ds_read_b128 v[190:193], v143 offset:4096
	ds_read_b128 v[194:197], v143 offset:5120
	ds_read_b128 v[198:201], v143 offset:6144
	ds_read_b128 v[202:205], v143 offset:7168
	global_load_lds_dwordx4 v[176:177], off
	s_add_i32 m0, s26, 0xe000
	v_lshl_add_u64 v[176:177], s[12:13], 0, v[138:139]
	global_load_lds_dwordx4 v[176:177], off
	s_waitcnt lgkmcnt(8)
	s_barrier
	s_waitcnt lgkmcnt(0)
	v_mfma_f32_16x16x32_bf16 v[126:129], v[144:147], v[160:163], 0
	v_mfma_f32_16x16x32_bf16 v[122:125], v[152:155], v[160:163], 0
	v_mfma_f32_16x16x32_bf16 v[118:121], v[144:147], v[168:171], 0
	v_mfma_f32_16x16x32_bf16 v[114:117], v[152:155], v[168:171], 0
	v_mfma_f32_16x16x32_bf16 v[110:113], v[144:147], v[190:193], 0
	v_mfma_f32_16x16x32_bf16 v[106:109], v[152:155], v[190:193], 0
	v_mfma_f32_16x16x32_bf16 v[102:105], v[144:147], v[198:201], 0
	v_mfma_f32_16x16x32_bf16 v[98:101], v[152:155], v[198:201], 0
	v_mfma_f32_16x16x32_bf16 v[126:129], v[148:151], v[164:167], v[126:129]
	v_mfma_f32_16x16x32_bf16 v[122:125], v[156:159], v[164:167], v[122:125]
	v_mfma_f32_16x16x32_bf16 v[118:121], v[148:151], v[172:175], v[118:121]
	v_mfma_f32_16x16x32_bf16 v[114:117], v[156:159], v[172:175], v[114:117]
	v_mfma_f32_16x16x32_bf16 v[110:113], v[148:151], v[194:197], v[110:113]
	v_mfma_f32_16x16x32_bf16 v[106:109], v[156:159], v[194:197], v[106:109]
	v_mfma_f32_16x16x32_bf16 v[102:105], v[148:151], v[202:205], v[102:105]
	v_mfma_f32_16x16x32_bf16 v[98:101], v[156:159], v[202:205], v[98:101]
	s_barrier
	s_add_i32 s1, 0, 0x14000
	v_add_u32_e32 v176, s1, v141
	s_add_i32 s0, s0, s25
	ds_read_b128 v[206:209], v176
	ds_read_b128 v[210:213], v176 offset:1024
	ds_read_b128 v[214:217], v176 offset:2048
	ds_read_b128 v[218:221], v176 offset:3072
	v_lshl_add_u64 v[176:177], s[16:17], 0, v[4:5]
	s_mov_b32 m0, s0
	v_lshl_add_u64 v[186:187], s[16:17], 0, v[130:131]
	global_load_lds_dwordx4 v[176:177], off
	s_add_i32 m0, s0, 0x2000
	s_nop 0
	global_load_lds_dwordx4 v[186:187], off
	s_barrier
	s_waitcnt lgkmcnt(0)
	v_mfma_f32_16x16x32_bf16 v[74:77], v[206:209], v[160:163], 0
	v_mfma_f32_16x16x32_bf16 v[66:69], v[214:217], v[160:163], 0
	v_mfma_f32_16x16x32_bf16 v[58:61], v[206:209], v[168:171], 0
	v_mfma_f32_16x16x32_bf16 v[50:53], v[214:217], v[168:171], 0
	v_mfma_f32_16x16x32_bf16 v[46:49], v[206:209], v[190:193], 0
	v_mfma_f32_16x16x32_bf16 v[42:45], v[214:217], v[190:193], 0
	v_mfma_f32_16x16x32_bf16 v[38:41], v[206:209], v[198:201], 0
	v_mfma_f32_16x16x32_bf16 v[34:37], v[214:217], v[198:201], 0
	v_mfma_f32_16x16x32_bf16 v[74:77], v[210:213], v[164:167], v[74:77]
	v_mfma_f32_16x16x32_bf16 v[66:69], v[218:221], v[164:167], v[66:69]
	v_mfma_f32_16x16x32_bf16 v[58:61], v[210:213], v[172:175], v[58:61]
	v_mfma_f32_16x16x32_bf16 v[50:53], v[218:221], v[172:175], v[50:53]
	v_mfma_f32_16x16x32_bf16 v[46:49], v[210:213], v[194:197], v[46:49]
	v_mfma_f32_16x16x32_bf16 v[42:45], v[218:221], v[194:197], v[42:45]
	v_mfma_f32_16x16x32_bf16 v[38:41], v[210:213], v[202:205], v[38:41]
	v_mfma_f32_16x16x32_bf16 v[34:37], v[218:221], v[202:205], v[34:37]
	s_mov_b32 m0, s26
	v_lshl_add_u64 v[222:223], s[18:19], 0, v[134:135]
	s_barrier
	ds_read_b128 v[160:163], v143 offset:16384
	ds_read_b128 v[164:167], v143 offset:17408
	ds_read_b128 v[168:171], v143 offset:18432
	ds_read_b128 v[172:175], v143 offset:19456
	ds_read_b128 v[190:193], v143 offset:20480
	ds_read_b128 v[194:197], v143 offset:21504
	ds_read_b128 v[198:201], v143 offset:22528
	ds_read_b128 v[202:205], v143 offset:23552
	global_load_lds_dwordx4 v[222:223], off
	s_mov_b32 m0, s27
	v_lshl_add_u64 v[224:225], s[18:19], 0, v[132:133]
	global_load_lds_dwordx4 v[224:225], off
	s_barrier
	s_waitcnt lgkmcnt(0)
	v_mfma_f32_16x16x32_bf16 v[94:97], v[144:147], v[160:163], 0
	v_mfma_f32_16x16x32_bf16 v[90:93], v[152:155], v[160:163], 0
	v_mfma_f32_16x16x32_bf16 v[86:89], v[144:147], v[168:171], 0
	v_mfma_f32_16x16x32_bf16 v[82:85], v[152:155], v[168:171], 0
	v_mfma_f32_16x16x32_bf16 v[78:81], v[144:147], v[190:193], 0
	v_mfma_f32_16x16x32_bf16 v[70:73], v[152:155], v[190:193], 0
	v_mfma_f32_16x16x32_bf16 v[62:65], v[144:147], v[198:201], 0
	v_mfma_f32_16x16x32_bf16 v[54:57], v[152:155], v[198:201], 0
	v_mfma_f32_16x16x32_bf16 v[94:97], v[148:151], v[164:167], v[94:97]
	v_mfma_f32_16x16x32_bf16 v[90:93], v[156:159], v[164:167], v[90:93]
	v_mfma_f32_16x16x32_bf16 v[86:89], v[148:151], v[172:175], v[86:89]
	v_mfma_f32_16x16x32_bf16 v[82:85], v[156:159], v[172:175], v[82:85]
	v_mfma_f32_16x16x32_bf16 v[78:81], v[148:151], v[194:197], v[78:81]
	v_mfma_f32_16x16x32_bf16 v[70:73], v[156:159], v[194:197], v[70:73]
	v_mfma_f32_16x16x32_bf16 v[62:65], v[148:151], v[202:205], v[62:65]
	v_mfma_f32_16x16x32_bf16 v[54:57], v[156:159], v[202:205], v[54:57]
	s_barrier
; #define PG8_STAGE(bufoff, gbase, voff) do { _Pragma("unroll") for (int _i = 0; _i < 2; ++_i) \
;         __builtin_amdgcn_global_load_lds((const unsigned*)((const char*)(gbase) + (voff)[_i]), (LAS unsigned*)(lds + (bufoff) + ldsw + _i * 8192), 16, 0, 0); } while (0)
; #define PG8_LDA(dst, b, h) do { _Pragma("unroll") for (int m = 0; m < 4; ++m) _Pragma("unroll") for (int k = 0; k < 2; ++k) dst[m][k] = *(const LAS bf16x8*)(lds + PG8_SA(b, h) + aoff + m * 2048 + k * 1024); } while (0)
; #define PG8_LDB(dst, b, h) do { _Pragma("unroll") for (int n = 0; n < 2; ++n) _Pragma("unroll") for (int k = 0; k < 2; ++k) dst[n][k] = *(const LAS bf16x8*)(lds + PG8_SB(b, h) + boff + n * 2048 + k * 1024); } while (0)
; #define PG8_MMA(ai, bj, At, Bt) do { __builtin_amdgcn_s_setprio(1); _Pragma("unroll") for (int m = 0; m < 4; ++m) _Pragma("unroll") for (int n = 0; n < 2; ++n) _Pragma("unroll") for (int k = 0; k < 2; ++k) \
;         acc[ai][bj][m][n] = __builtin_amdgcn_mfma_f32_16x16x32_bf16(Bt[n][k], At[m][k], acc[ai][bj][m][n], 0, 0, 0); __builtin_amdgcn_s_setprio(0); } while (0)
; #define PG8_WAIT_V(n) asm volatile("s_waitcnt vmcnt(" #n ")" ::: "memory")
; #define PG8_WAIT_L(n) asm volatile("s_waitcnt lgkmcnt(" #n ")" ::: "memory")
; #define PG8_BAR __builtin_amdgcn_s_barrier()
; #define PG8_SCHED __builtin_amdgcn_sched_barrier(0)
; template <class Epi>
; __device__ __forceinline__ void gemm_phase(LAS unsigned char* lds, const Gemm g, const StaticOrder& S, const Epi& E) {
;     ...
;             PG8_STAGE(PG8_SB(0, 1), b2 + hstep, voffB);
;             PG8_WAIT_V(6); PG8_BAR; PG8_MMA(1, 1, At, B1); PG8_BAR;
;             PG8_LDB(B0, 1, 0); PG8_SCHED; PG8_LDA(At, 1, 0); PG8_STAGE(PG8_SA(0, 1), a2 + hstep, voffA);
;             PG8_WAIT_L(8); PG8_BAR; PG8_WAIT_L(0); PG8_MMA(0, 0, At, B0); PG8_BAR; PG8_SCHED;
;             PG8_LDB(B1, 1, 1); PG8_STAGE(PG8_SB(1, 0), b3, voffB);
;             PG8_BAR; PG8_WAIT_L(0); PG8_MMA(0, 1, At, B1); PG8_BAR;
	s_add_u32 s12, s16, 0x18000
	s_addc_u32 s13, s17, 0
	s_add_i32 s0, s1, s25
	s_mov_b32 m0, s0
	v_lshl_add_u64 v[144:145], s[12:13], 0, v[4:5]
	global_load_lds_dwordx4 v[144:145], off
	s_add_i32 m0, s0, 0x2000
	v_lshl_add_u64 v[144:145], s[12:13], 0, v[130:131]
	global_load_lds_dwordx4 v[144:145], off
	s_waitcnt vmcnt(6)
	s_barrier
	v_mfma_f32_16x16x32_bf16 v[30:33], v[206:209], v[160:163], 0
	v_mfma_f32_16x16x32_bf16 v[26:29], v[214:217], v[160:163], 0
	v_mfma_f32_16x16x32_bf16 v[22:25], v[206:209], v[168:171], 0
	v_mfma_f32_16x16x32_bf16 v[18:21], v[214:217], v[168:171], 0
	v_mfma_f32_16x16x32_bf16 v[14:17], v[206:209], v[190:193], 0
	v_mfma_f32_16x16x32_bf16 v[10:13], v[214:217], v[190:193], 0
	v_mfma_f32_16x16x32_bf16 v[6:9], v[206:209], v[198:201], 0
	v_mfma_f32_16x16x32_bf16 v[0:3], v[214:217], v[198:201], 0
	v_mfma_f32_16x16x32_bf16 v[30:33], v[210:213], v[164:167], v[30:33]
	v_mfma_f32_16x16x32_bf16 v[26:29], v[218:221], v[164:167], v[26:29]
	v_mfma_f32_16x16x32_bf16 v[22:25], v[210:213], v[172:175], v[22:25]
	v_mfma_f32_16x16x32_bf16 v[18:21], v[218:221], v[172:175], v[18:21]
	v_mfma_f32_16x16x32_bf16 v[14:17], v[210:213], v[194:197], v[14:17]
	v_mfma_f32_16x16x32_bf16 v[10:13], v[218:221], v[194:197], v[10:13]
	v_mfma_f32_16x16x32_bf16 v[6:9], v[210:213], v[202:205], v[6:9]
	v_mfma_f32_16x16x32_bf16 v[0:3], v[218:221], v[202:205], v[0:3]
	s_add_i32 s0, 0, 0x18000
	v_add_u32_e32 v156, s0, v141
	s_barrier
	ds_read_b128 v[144:147], v156
	ds_read_b128 v[148:151], v156 offset:1024
	ds_read_b128 v[152:155], v156 offset:2048
	ds_read_b128 v[156:159], v156 offset:3072
	s_add_u32 s12, s18, 0x18000
	s_addc_u32 s13, s19, 0
	s_mov_b32 m0, s28
	v_lshl_add_u64 v[206:207], s[12:13], 0, v[134:135]
	ds_read_b128 v[160:163], v143 offset:32768
	ds_read_b128 v[164:167], v143 offset:33792
	ds_read_b128 v[168:171], v143 offset:34816
	ds_read_b128 v[172:175], v143 offset:35840
	ds_read_b128 v[190:193], v143 offset:36864
	ds_read_b128 v[194:197], v143 offset:37888
	ds_read_b128 v[198:201], v143 offset:38912
	ds_read_b128 v[202:205], v143 offset:39936
	global_load_lds_dwordx4 v[206:207], off
	s_mov_b32 m0, s29
	v_lshl_add_u64 v[206:207], s[12:13], 0, v[132:133]
	global_load_lds_dwordx4 v[206:207], off
	s_waitcnt lgkmcnt(8)
	s_barrier
	s_waitcnt lgkmcnt(0)
	v_mfma_f32_16x16x32_bf16 v[126:129], v[144:147], v[160:163], v[126:129]
	v_mfma_f32_16x16x32_bf16 v[122:125], v[152:155], v[160:163], v[122:125]
	v_mfma_f32_16x16x32_bf16 v[118:121], v[144:147], v[168:171], v[118:121]
	v_mfma_f32_16x16x32_bf16 v[114:117], v[152:155], v[168:171], v[114:117]
	v_mfma_f32_16x16x32_bf16 v[110:113], v[144:147], v[190:193], v[110:113]
	v_mfma_f32_16x16x32_bf16 v[106:109], v[152:155], v[190:193], v[106:109]
	v_mfma_f32_16x16x32_bf16 v[102:105], v[144:147], v[198:201], v[102:105]
	v_mfma_f32_16x16x32_bf16 v[98:101], v[152:155], v[198:201], v[98:101]
	v_mfma_f32_16x16x32_bf16 v[126:129], v[148:151], v[164:167], v[126:129]
	v_mfma_f32_16x16x32_bf16 v[122:125], v[156:159], v[164:167], v[122:125]
	v_mfma_f32_16x16x32_bf16 v[118:121], v[148:151], v[172:175], v[118:121]
	v_mfma_f32_16x16x32_bf16 v[114:117], v[156:159], v[172:175], v[114:117]
	v_mfma_f32_16x16x32_bf16 v[110:113], v[148:151], v[194:197], v[110:113]
	v_mfma_f32_16x16x32_bf16 v[106:109], v[156:159], v[194:197], v[106:109]
	v_mfma_f32_16x16x32_bf16 v[102:105], v[148:151], v[202:205], v[102:105]
	v_mfma_f32_16x16x32_bf16 v[98:101], v[156:159], v[202:205], v[98:101]
	s_barrier
	s_add_i32 s1, 0, 0x1c000
	s_add_i32 s0, s0, s25
	v_add_u32_e32 v218, s1, v141
	v_lshl_add_u64 v[176:177], v[176:177], 0, s[86:87]
	s_mov_b32 m0, s0
	ds_read_b128 v[206:209], v218
	ds_read_b128 v[210:213], v218 offset:1024
	ds_read_b128 v[214:217], v218 offset:2048
	ds_read_b128 v[218:221], v218 offset:3072
	global_load_lds_dwordx4 v[176:177], off
	s_add_i32 m0, s0, 0x2000
	v_lshl_add_u64 v[176:177], v[186:187], 0, s[86:87]
	global_load_lds_dwordx4 v[176:177], off
	s_barrier
; #define PG8_STAGE(bufoff, gbase, voff) do { _Pragma("unroll") for (int _i = 0; _i < 2; ++_i) \
;         __builtin_amdgcn_global_load_lds((const unsigned*)((const char*)(gbase) + (voff)[_i]), (LAS unsigned*)(lds + (bufoff) + ldsw + _i * 8192), 16, 0, 0); } while (0)
; #define PG8_LDA(dst, b, h) do { _Pragma("unroll") for (int m = 0; m < 4; ++m) _Pragma("unroll") for (int k = 0; k < 2; ++k) dst[m][k] = *(const LAS bf16x8*)(lds + PG8_SA(b, h) + aoff + m * 2048 + k * 1024); } while (0)
; #define PG8_LDB(dst, b, h) do { _Pragma("unroll") for (int n = 0; n < 2; ++n) _Pragma("unroll") for (int k = 0; k < 2; ++k) dst[n][k] = *(const LAS bf16x8*)(lds + PG8_SB(b, h) + boff + n * 2048 + k * 1024); } while (0)
; #define PG8_MMA(ai, bj, At, Bt) do { __builtin_amdgcn_s_setprio(1); _Pragma("unroll") for (int m = 0; m < 4; ++m) _Pragma("unroll") for (int n = 0; n < 2; ++n) _Pragma("unroll") for (int k = 0; k < 2; ++k) \
;         acc[ai][bj][m][n] = __builtin_amdgcn_mfma_f32_16x16x32_bf16(Bt[n][k], At[m][k], acc[ai][bj][m][n], 0, 0, 0); __builtin_amdgcn_s_setprio(0); } while (0)
; #define PG8_WAIT_V(n) asm volatile("s_waitcnt vmcnt(" #n ")" ::: "memory")
; #define PG8_WAIT_L(n) asm volatile("s_waitcnt lgkmcnt(" #n ")" ::: "memory")
; #define PG8_BAR __builtin_amdgcn_s_barrier()
; #define PG8_SCHED __builtin_amdgcn_sched_barrier(0)
; template <class Epi>
; __device__ __forceinline__ void gemm_phase(LAS unsigned char* lds, const Gemm g, const StaticOrder& S, const Epi& E) {
;     ...
;             PG8_LDB(B1, 1, 1); PG8_STAGE(PG8_SB(1, 0), b3, voffB);
;             PG8_BAR; PG8_WAIT_L(0); PG8_MMA(0, 1, At, B1); PG8_BAR;
;             PG8_LDA(At, 1, 1); PG8_STAGE(PG8_SA(1, 0), a3, voffA);
;             PG8_BAR; PG8_WAIT_L(0); PG8_MMA(1, 0, At, B0); PG8_BAR; PG8_SCHED;
;             PG8_STAGE(PG8_SB(1, 1), b3 + hstep, voffB);
;             PG8_WAIT_V(6); PG8_BAR; PG8_MMA(1, 1, At, B1); PG8_BAR;
	s_waitcnt lgkmcnt(0)
	v_mfma_f32_16x16x32_bf16 v[74:77], v[206:209], v[160:163], v[74:77]
	v_mfma_f32_16x16x32_bf16 v[66:69], v[214:217], v[160:163], v[66:69]
	v_mfma_f32_16x16x32_bf16 v[58:61], v[206:209], v[168:171], v[58:61]
	v_mfma_f32_16x16x32_bf16 v[50:53], v[214:217], v[168:171], v[50:53]
	v_mfma_f32_16x16x32_bf16 v[46:49], v[206:209], v[190:193], v[46:49]
	v_mfma_f32_16x16x32_bf16 v[42:45], v[214:217], v[190:193], v[42:45]
	v_mfma_f32_16x16x32_bf16 v[38:41], v[206:209], v[198:201], v[38:41]
	v_mfma_f32_16x16x32_bf16 v[34:37], v[214:217], v[198:201], v[34:37]
	v_mfma_f32_16x16x32_bf16 v[74:77], v[210:213], v[164:167], v[74:77]
	v_mfma_f32_16x16x32_bf16 v[66:69], v[218:221], v[164:167], v[66:69]
	v_mfma_f32_16x16x32_bf16 v[58:61], v[210:213], v[172:175], v[58:61]
	v_mfma_f32_16x16x32_bf16 v[50:53], v[218:221], v[172:175], v[50:53]
	v_mfma_f32_16x16x32_bf16 v[46:49], v[210:213], v[194:197], v[46:49]
	v_mfma_f32_16x16x32_bf16 v[42:45], v[218:221], v[194:197], v[42:45]
	v_mfma_f32_16x16x32_bf16 v[38:41], v[210:213], v[202:205], v[38:41]
	v_mfma_f32_16x16x32_bf16 v[34:37], v[218:221], v[202:205], v[34:37]
	s_mov_b32 m0, s30
	v_lshl_add_u64 v[176:177], v[222:223], 0, s[86:87]
	s_barrier
	ds_read_b128 v[160:163], v143 offset:49152
	ds_read_b128 v[164:167], v143 offset:50176
	ds_read_b128 v[168:171], v143 offset:51200
	ds_read_b128 v[172:175], v143 offset:52224
	ds_read_b128 v[190:193], v143 offset:53248
	ds_read_b128 v[194:197], v143 offset:54272
	ds_read_b128 v[198:201], v143 offset:55296
	ds_read_b128 v[202:205], v143 offset:56320
	global_load_lds_dwordx4 v[176:177], off
	s_mov_b32 m0, s31
	v_lshl_add_u64 v[176:177], v[224:225], 0, s[86:87]
	global_load_lds_dwordx4 v[176:177], off
	s_barrier
	s_waitcnt lgkmcnt(0)
	v_mfma_f32_16x16x32_bf16 v[94:97], v[144:147], v[160:163], v[94:97]
	v_mfma_f32_16x16x32_bf16 v[90:93], v[152:155], v[160:163], v[90:93]
	v_mfma_f32_16x16x32_bf16 v[86:89], v[144:147], v[168:171], v[86:89]
	v_mfma_f32_16x16x32_bf16 v[82:85], v[152:155], v[168:171], v[82:85]
	v_mfma_f32_16x16x32_bf16 v[78:81], v[144:147], v[190:193], v[78:81]
	v_mfma_f32_16x16x32_bf16 v[70:73], v[152:155], v[190:193], v[70:73]
	v_mfma_f32_16x16x32_bf16 v[62:65], v[144:147], v[198:201], v[62:65]
	v_mfma_f32_16x16x32_bf16 v[54:57], v[152:155], v[198:201], v[54:57]
	v_mfma_f32_16x16x32_bf16 v[94:97], v[148:151], v[164:167], v[94:97]
	v_mfma_f32_16x16x32_bf16 v[90:93], v[156:159], v[164:167], v[90:93]
	v_mfma_f32_16x16x32_bf16 v[86:89], v[148:151], v[172:175], v[86:89]
	v_mfma_f32_16x16x32_bf16 v[82:85], v[156:159], v[172:175], v[82:85]
	v_mfma_f32_16x16x32_bf16 v[78:81], v[148:151], v[194:197], v[78:81]
	v_mfma_f32_16x16x32_bf16 v[70:73], v[156:159], v[194:197], v[70:73]
	v_mfma_f32_16x16x32_bf16 v[62:65], v[148:151], v[202:205], v[62:65]
	v_mfma_f32_16x16x32_bf16 v[54:57], v[156:159], v[202:205], v[54:57]
	s_barrier
	s_add_u32 s12, s16, 0x18080
	s_addc_u32 s13, s17, 0
	s_add_i32 s0, s1, s25
	s_mov_b32 m0, s0
	v_lshl_add_u64 v[144:145], s[12:13], 0, v[4:5]
	global_load_lds_dwordx4 v[144:145], off
	s_add_i32 m0, s0, 0x2000
	v_lshl_add_u64 v[144:145], s[12:13], 0, v[130:131]
	global_load_lds_dwordx4 v[144:145], off
	s_waitcnt vmcnt(6)
	s_barrier
	v_mfma_f32_16x16x32_bf16 v[30:33], v[206:209], v[160:163], v[30:33]
	v_mfma_f32_16x16x32_bf16 v[26:29], v[214:217], v[160:163], v[26:29]
	v_mfma_f32_16x16x32_bf16 v[22:25], v[206:209], v[168:171], v[22:25]
	v_mfma_f32_16x16x32_bf16 v[18:21], v[214:217], v[168:171], v[18:21]
	v_mfma_f32_16x16x32_bf16 v[14:17], v[206:209], v[190:193], v[14:17]
	v_mfma_f32_16x16x32_bf16 v[10:13], v[214:217], v[190:193], v[10:13]
	v_mfma_f32_16x16x32_bf16 v[6:9], v[206:209], v[198:201], v[6:9]
	v_mfma_f32_16x16x32_bf16 v[0:3], v[214:217], v[198:201], v[0:3]
	v_mfma_f32_16x16x32_bf16 v[30:33], v[210:213], v[164:167], v[30:33]
	v_mfma_f32_16x16x32_bf16 v[26:29], v[218:221], v[164:167], v[26:29]
	v_mfma_f32_16x16x32_bf16 v[22:25], v[210:213], v[172:175], v[22:25]
	v_mfma_f32_16x16x32_bf16 v[18:21], v[218:221], v[172:175], v[18:21]
	v_mfma_f32_16x16x32_bf16 v[14:17], v[210:213], v[194:197], v[14:17]
	v_mfma_f32_16x16x32_bf16 v[10:13], v[218:221], v[194:197], v[10:13]
	v_mfma_f32_16x16x32_bf16 v[6:9], v[210:213], v[202:205], v[6:9]
	v_mfma_f32_16x16x32_bf16 v[0:3], v[218:221], v[202:205], v[0:3]
	s_add_i32 s41, s41, 2
	s_add_u32 s39, s39, 0x100
	s_addc_u32 s40, s40, 0
	s_cmp_gt_u32 s41, 3
	s_mov_b64 s[12:13], s[14:15]
	s_barrier
	s_cbranch_scc1 .Lpeel_exit_4

; __device__ __forceinline__ unsigned cvt_pk_bf16(float lo, float hi) { unsigned r; asm volatile("s_nop 0\n\tv_cvt_pk_bf16_f32 %0, %1, %2" : "=v"(r) : "v"(lo), "v"(hi)); return r; }
;     __device__ __forceinline__ void operator()(const f32x4 (&acc)[2][2][4][2], const Unit& u, int wr, int wc, int fr, int fq) const {
;         const int row0 = u.pm * 256 + wr * 64 + fr, col0 = u.pn * 256 + wc * 32 + 8 * fq;
;         f32x4 ra = (f32x4){1.f, 1.f, 1.f, 1.f}, rb = ra;
;         f32x4 swv[4] = {(f32x4){0.f, 0.f, 0.f, 0.f}, (f32x4){0.f, 0.f, 0.f, 0.f}, (f32x4){0.f, 0.f, 0.f, 0.f}, (f32x4){0.f, 0.f, 0.f, 0.f}};
;         if (ss) { load_rstd(ss, row0, ra, rb); const float* swp = sw + (size_t)(u.pm >> 3) * ldc + col0;
;             swv[0] = *(const f32x4*)(swp); swv[1] = *(const f32x4*)(swp + 4); swv[2] = *(const f32x4*)(swp + 128); swv[3] = *(const f32x4*)(swp + 132); }
; #pragma unroll
;         for (int bj = 0; bj < 2; ++bj) {
;             const f32x4 s0 = swv[2 * bj], s1 = swv[2 * bj + 1];
; #pragma unroll
;             for (int ai = 0; ai < 2; ++ai)
; #pragma unroll
;                 for (int m = 0; m < 4; ++m) { const int r = row0 + ai * 128 + m * 16;
;                     const float rstd = ai ? rb[m] : ra[m];
;                     const f32x4 v0 = acc[ai][bj][m][0] * rstd + s0, v1 = acc[ai][bj][m][1] * rstd + s1;
;                     uint4 st; st.x = cvt_pk_bf16(v0[0], v0[1]); st.y = cvt_pk_bf16(v0[2], v0[3]); st.z = cvt_pk_bf16(v1[0], v1[1]); st.w = cvt_pk_bf16(v1[2], v1[3]);
;                     *(uint4*)(O + (size_t)r * ldc + col0 + bj * 128) = st; }
.Lpeel_exit_4:
	s_setprio 0
	v_lshl_or_b32 v144, s37, 8, v142
	v_pk_add_f32 v[126:127], v[126:127], 0 op_sel_hi:[1,0]
	v_lshl_add_u32 v148, s38, 8, v140
	v_ashrrev_i32_e32 v145, 31, v144
	v_pk_add_f32 v[128:129], v[128:129], 0 op_sel_hi:[1,0]
	v_pk_add_f32 v[146:147], v[124:125], 0 op_sel_hi:[1,0]
	v_pk_add_f32 v[124:125], v[122:123], 0 op_sel_hi:[1,0]
	s_nop 0
	v_cvt_pk_bf16_f32 v122, v126, v127
	v_mov_b64_e32 v[126:127], s[10:11]
	s_nop 0
	v_cvt_pk_bf16_f32 v123, v128, v129
	v_mad_i64_i32 v[128:129], s[12:13], v148, s83, v[126:127]
	v_lshlrev_b64 v[144:145], 1, v[144:145]
	s_nop 0
	v_cvt_pk_bf16_f32 v124, v124, v125
	v_lshl_add_u64 v[128:129], v[128:129], 0, v[144:145]
	s_nop 0
	v_cvt_pk_bf16_f32 v125, v146, v147
	global_store_dwordx4 v[128:129], v[122:125], off
	v_pk_add_f32 v[118:119], v[118:119], 0 op_sel_hi:[1,0]
	v_pk_add_f32 v[120:121], v[120:121], 0 op_sel_hi:[1,0]
	v_or_b32_e32 v124, 16, v148
	v_pk_add_f32 v[122:123], v[116:117], 0 op_sel_hi:[1,0]
	v_pk_add_f32 v[116:117], v[114:115], 0 op_sel_hi:[1,0]
	s_nop 0
	v_cvt_pk_bf16_f32 v114, v118, v119
	v_mad_i64_i32 v[118:119], s[12:13], v124, s83, v[126:127]
	s_nop 0
	v_cvt_pk_bf16_f32 v115, v120, v121
	s_nop 0
	v_cvt_pk_bf16_f32 v116, v116, v117
	v_lshl_add_u64 v[118:119], v[118:119], 0, v[144:145]
	s_nop 0
	v_cvt_pk_bf16_f32 v117, v122, v123
	global_store_dwordx4 v[118:119], v[114:117], off
	v_pk_add_f32 v[110:111], v[110:111], 0 op_sel_hi:[1,0]
	v_pk_add_f32 v[112:113], v[112:113], 0 op_sel_hi:[1,0]
	v_or_b32_e32 v116, 32, v148
	v_pk_add_f32 v[114:115], v[108:109], 0 op_sel_hi:[1,0]
	v_pk_add_f32 v[108:109], v[106:107], 0 op_sel_hi:[1,0]
	s_nop 0
	v_cvt_pk_bf16_f32 v106, v110, v111
	v_mad_i64_i32 v[110:111], s[12:13], v116, s83, v[126:127]
	s_nop 0
	v_cvt_pk_bf16_f32 v107, v112, v113
	s_nop 0
	v_cvt_pk_bf16_f32 v108, v108, v109
	v_lshl_add_u64 v[110:111], v[110:111], 0, v[144:145]
	s_nop 0
	v_cvt_pk_bf16_f32 v109, v114, v115
	global_store_dwordx4 v[110:111], v[106:109], off
	v_pk_add_f32 v[102:103], v[102:103], 0 op_sel_hi:[1,0]
	v_pk_add_f32 v[104:105], v[104:105], 0 op_sel_hi:[1,0]
	v_or_b32_e32 v108, 48, v148
	v_pk_add_f32 v[106:107], v[100:101], 0 op_sel_hi:[1,0]
	v_pk_add_f32 v[100:101], v[98:99], 0 op_sel_hi:[1,0]
	s_nop 0
	v_cvt_pk_bf16_f32 v98, v102, v103
	v_mad_i64_i32 v[102:103], s[12:13], v108, s83, v[126:127]
	s_nop 0
	v_cvt_pk_bf16_f32 v99, v104, v105
	s_nop 0
	v_cvt_pk_bf16_f32 v100, v100, v101
	v_lshl_add_u64 v[102:103], v[102:103], 0, v[144:145]
	s_nop 0
	v_cvt_pk_bf16_f32 v101, v106, v107
	global_store_dwordx4 v[102:103], v[98:101], off
	v_pk_add_f32 v[94:95], v[94:95], 0 op_sel_hi:[1,0]
	v_pk_add_f32 v[96:97], v[96:97], 0 op_sel_hi:[1,0]
	v_add_u32_e32 v100, 0x80, v148
	v_pk_add_f32 v[98:99], v[92:93], 0 op_sel_hi:[1,0]
	v_pk_add_f32 v[92:93], v[90:91], 0 op_sel_hi:[1,0]
	s_nop 0
	v_cvt_pk_bf16_f32 v90, v94, v95
	v_mad_i64_i32 v[94:95], s[12:13], v100, s83, v[126:127]
	s_nop 0
	v_cvt_pk_bf16_f32 v91, v96, v97
	s_nop 0
	v_cvt_pk_bf16_f32 v92, v92, v93
	v_lshl_add_u64 v[94:95], v[94:95], 0, v[144:145]
	s_nop 0
	v_cvt_pk_bf16_f32 v93, v98, v99
	global_store_dwordx4 v[94:95], v[90:93], off
	v_pk_add_f32 v[86:87], v[86:87], 0 op_sel_hi:[1,0]
	v_pk_add_f32 v[88:89], v[88:89], 0 op_sel_hi:[1,0]
	v_add_u32_e32 v92, 0x90, v148
	v_pk_add_f32 v[90:91], v[84:85], 0 op_sel_hi:[1,0]
	v_pk_add_f32 v[84:85], v[82:83], 0 op_sel_hi:[1,0]
	s_nop 0
	v_cvt_pk_bf16_f32 v82, v86, v87
	v_mad_i64_i32 v[86:87], s[12:13], v92, s83, v[126:127]
	s_nop 0
	v_cvt_pk_bf16_f32 v83, v88, v89
	s_nop 0
	v_cvt_pk_bf16_f32 v84, v84, v85
	v_lshl_add_u64 v[86:87], v[86:87], 0, v[144:145]
	s_nop 0
	v_cvt_pk_bf16_f32 v85, v90, v91
	global_store_dwordx4 v[86:87], v[82:85], off
	v_pk_add_f32 v[78:79], v[78:79], 0 op_sel_hi:[1,0]
	v_pk_add_f32 v[80:81], v[80:81], 0 op_sel_hi:[1,0]
	v_add_u32_e32 v84, 0xa0, v148
	v_pk_add_f32 v[82:83], v[72:73], 0 op_sel_hi:[1,0]
	v_pk_add_f32 v[72:73], v[70:71], 0 op_sel_hi:[1,0]
	s_nop 0
	v_cvt_pk_bf16_f32 v70, v78, v79
	v_mad_i64_i32 v[78:79], s[12:13], v84, s83, v[126:127]
	s_nop 0
	v_cvt_pk_bf16_f32 v71, v80, v81
	s_nop 0
	v_cvt_pk_bf16_f32 v72, v72, v73
	v_lshl_add_u64 v[78:79], v[78:79], 0, v[144:145]
	s_nop 0
	v_cvt_pk_bf16_f32 v73, v82, v83
	global_store_dwordx4 v[78:79], v[70:73], off
; __device__ __forceinline__ unsigned cvt_pk_bf16(float lo, float hi) { unsigned r; asm volatile("s_nop 0\n\tv_cvt_pk_bf16_f32 %0, %1, %2" : "=v"(r) : "v"(lo), "v"(hi)); return r; }
; #define PG8_WAIT_V(n) asm volatile("s_waitcnt vmcnt(" #n ")" ::: "memory")
; #define PG8_BAR __builtin_amdgcn_s_barrier()
; template <class Epi>
; __device__ __forceinline__ void gemm_phase(LAS unsigned char* lds, const Gemm g, const StaticOrder& S, const Epi& E) {
;     ...
;     PG8_WAIT_V(0);
;     if (wr == 0) PG8_BAR;
;     PG8_BAR;
;     __device__ __forceinline__ void operator()(const f32x4 (&acc)[2][2][4][2], const Unit& u, int wr, int wc, int fr, int fq) const {
;     ...
;                 for (int m = 0; m < 4; ++m) { const int r = row0 + ai * 128 + m * 16;
;                     const float rstd = ai ? rb[m] : ra[m];
;                     const f32x4 v0 = acc[ai][bj][m][0] * rstd + s0, v1 = acc[ai][bj][m][1] * rstd + s1;
;                     uint4 st; st.x = cvt_pk_bf16(v0[0], v0[1]); st.y = cvt_pk_bf16(v0[2], v0[3]); st.z = cvt_pk_bf16(v1[0], v1[1]); st.w = cvt_pk_bf16(v1[2], v1[3]);
;                     *(uint4*)(O + (size_t)r * ldc + col0 + bj * 128) = st; }
	v_pk_add_f32 v[62:63], v[62:63], 0 op_sel_hi:[1,0]
	v_pk_add_f32 v[64:65], v[64:65], 0 op_sel_hi:[1,0]
	v_add_u32_e32 v72, 0xb0, v148
	v_pk_add_f32 v[70:71], v[56:57], 0 op_sel_hi:[1,0]
	v_pk_add_f32 v[56:57], v[54:55], 0 op_sel_hi:[1,0]
	s_nop 0
	v_cvt_pk_bf16_f32 v54, v62, v63
	v_mad_i64_i32 v[62:63], s[12:13], v72, s83, v[126:127]
	s_nop 0
	v_cvt_pk_bf16_f32 v55, v64, v65
	s_nop 0
	v_cvt_pk_bf16_f32 v56, v56, v57
	s_nop 0
	v_cvt_pk_bf16_f32 v57, v70, v71
	v_lshl_add_u64 v[62:63], v[62:63], 0, v[144:145]
	global_store_dwordx4 v[62:63], v[54:57], off
	v_pk_add_f32 v[64:65], v[68:69], 0 op_sel_hi:[1,0]
	v_pk_add_f32 v[66:67], v[66:67], 0 op_sel_hi:[1,0]
	v_pk_add_f32 v[56:57], v[76:77], 0 op_sel_hi:[1,0]
	v_pk_add_f32 v[54:55], v[74:75], 0 op_sel_hi:[1,0]
	v_pk_add_f32 v[48:49], v[48:49], 0 op_sel_hi:[1,0]
	s_nop 0
	v_cvt_pk_bf16_f32 v54, v54, v55
	s_nop 0
	v_cvt_pk_bf16_f32 v55, v56, v57
	s_nop 0
	v_cvt_pk_bf16_f32 v56, v66, v67
	s_nop 0
	v_cvt_pk_bf16_f32 v57, v64, v65
	global_store_dwordx4 v[128:129], v[54:57], off offset:256
	v_pk_add_f32 v[46:47], v[46:47], 0 op_sel_hi:[1,0]
	v_pk_add_f32 v[40:41], v[40:41], 0 op_sel_hi:[1,0]
	v_pk_add_f32 v[54:55], v[60:61], 0 op_sel_hi:[1,0]
	v_pk_add_f32 v[56:57], v[58:59], 0 op_sel_hi:[1,0]
	v_pk_add_f32 v[58:59], v[52:53], 0 op_sel_hi:[1,0]
	v_pk_add_f32 v[52:53], v[50:51], 0 op_sel_hi:[1,0]
	s_nop 0
	v_cvt_pk_bf16_f32 v50, v56, v57
	s_nop 0
	v_cvt_pk_bf16_f32 v51, v54, v55
	v_pk_add_f32 v[38:39], v[38:39], 0 op_sel_hi:[1,0]
	s_nop 0
	v_cvt_pk_bf16_f32 v52, v52, v53
	s_nop 0
	v_cvt_pk_bf16_f32 v53, v58, v59
	global_store_dwordx4 v[118:119], v[50:53], off offset:256
	v_pk_add_f32 v[32:33], v[32:33], 0 op_sel_hi:[1,0]
	v_pk_add_f32 v[30:31], v[30:31], 0 op_sel_hi:[1,0]
	v_pk_add_f32 v[50:51], v[44:45], 0 op_sel_hi:[1,0]
	v_pk_add_f32 v[44:45], v[42:43], 0 op_sel_hi:[1,0]
	s_nop 0
	v_cvt_pk_bf16_f32 v42, v46, v47
	s_nop 0
	v_cvt_pk_bf16_f32 v43, v48, v49
	v_pk_add_f32 v[24:25], v[24:25], 0 op_sel_hi:[1,0]
	s_nop 0
	v_cvt_pk_bf16_f32 v44, v44, v45
	s_nop 0
	v_cvt_pk_bf16_f32 v45, v50, v51
	global_store_dwordx4 v[110:111], v[42:45], off offset:256
	v_pk_add_f32 v[22:23], v[22:23], 0 op_sel_hi:[1,0]
	v_pk_add_f32 v[16:17], v[16:17], 0 op_sel_hi:[1,0]
	v_pk_add_f32 v[42:43], v[36:37], 0 op_sel_hi:[1,0]
	v_pk_add_f32 v[36:37], v[34:35], 0 op_sel_hi:[1,0]
	s_nop 0
	v_cvt_pk_bf16_f32 v34, v38, v39
	s_nop 0
	v_cvt_pk_bf16_f32 v35, v40, v41
	v_pk_add_f32 v[14:15], v[14:15], 0 op_sel_hi:[1,0]
	s_nop 0
	v_cvt_pk_bf16_f32 v36, v36, v37
	s_nop 0
	v_cvt_pk_bf16_f32 v37, v42, v43
	global_store_dwordx4 v[102:103], v[34:37], off offset:256
	s_and_b64 vcc, exec, s[4:5]
	s_mov_b32 s37, s35
	v_pk_add_f32 v[34:35], v[28:29], 0 op_sel_hi:[1,0]
	v_pk_add_f32 v[28:29], v[26:27], 0 op_sel_hi:[1,0]
	s_nop 0
	v_cvt_pk_bf16_f32 v26, v30, v31
	s_nop 0
	v_cvt_pk_bf16_f32 v27, v32, v33
	s_mov_b32 s38, s36
	s_nop 0
	v_cvt_pk_bf16_f32 v28, v28, v29
	s_nop 0
	v_cvt_pk_bf16_f32 v29, v34, v35
	global_store_dwordx4 v[94:95], v[26:29], off offset:256
	s_mov_b64 s[14:15], s[8:9]
	s_mov_b64 s[12:13], s[6:7]
	v_pk_add_f32 v[26:27], v[20:21], 0 op_sel_hi:[1,0]
	v_pk_add_f32 v[20:21], v[18:19], 0 op_sel_hi:[1,0]
	s_nop 0
	v_cvt_pk_bf16_f32 v18, v22, v23
	s_nop 0
	v_cvt_pk_bf16_f32 v19, v24, v25
	v_pk_add_f32 v[8:9], v[8:9], 0 op_sel_hi:[1,0]
	s_nop 0
	v_cvt_pk_bf16_f32 v20, v20, v21
	s_nop 0
	v_cvt_pk_bf16_f32 v21, v26, v27
	global_store_dwordx4 v[86:87], v[18:21], off offset:256
	v_pk_add_f32 v[6:7], v[6:7], 0 op_sel_hi:[1,0]
	s_nop 0
	v_pk_add_f32 v[18:19], v[12:13], 0 op_sel_hi:[1,0]
	v_pk_add_f32 v[12:13], v[10:11], 0 op_sel_hi:[1,0]
	s_nop 0
	v_cvt_pk_bf16_f32 v10, v14, v15
	s_nop 0
	v_cvt_pk_bf16_f32 v11, v16, v17
	s_nop 0
	s_nop 0
	v_cvt_pk_bf16_f32 v12, v12, v13
	s_nop 0
	v_cvt_pk_bf16_f32 v13, v18, v19
	global_store_dwordx4 v[78:79], v[10:13], off offset:256
	s_nop 1
	v_pk_add_f32 v[10:11], v[2:3], 0 op_sel_hi:[1,0]
	v_pk_add_f32 v[2:3], v[0:1], 0 op_sel_hi:[1,0]
	s_nop 0
	v_cvt_pk_bf16_f32 v0, v6, v7
	s_nop 0
	v_cvt_pk_bf16_f32 v1, v8, v9
	s_nop 0
	s_nop 0
	v_cvt_pk_bf16_f32 v2, v2, v3
	s_nop 0
	v_cvt_pk_bf16_f32 v3, v10, v11
	global_store_dwordx4 v[62:63], v[0:3], off offset:256
	s_cbranch_vccz .LBB0_2396
	s_waitcnt vmcnt(0)
	s_cmpk_gt_u32 s20, 0xff
	s_cbranch_scc1 .LBB0_2407
	s_barrier

; #define PG8_STAGE(bufoff, gbase, voff) do { _Pragma("unroll") for (int _i = 0; _i < 2; ++_i) \
;         __builtin_amdgcn_global_load_lds((const unsigned*)((const char*)(gbase) + (voff)[_i]), (LAS unsigned*)(lds + (bufoff) + ldsw + _i * 8192), 16, 0, 0); } while (0)
; #define PG8_LDA(dst, b, h) do { _Pragma("unroll") for (int m = 0; m < 4; ++m) _Pragma("unroll") for (int k = 0; k < 2; ++k) dst[m][k] = *(const LAS bf16x8*)(lds + PG8_SA(b, h) + aoff + m * 2048 + k * 1024); } while (0)
; #define PG8_LDB(dst, b, h) do { _Pragma("unroll") for (int n = 0; n < 2; ++n) _Pragma("unroll") for (int k = 0; k < 2; ++k) dst[n][k] = *(const LAS bf16x8*)(lds + PG8_SB(b, h) + boff + n * 2048 + k * 1024); } while (0)
; #define PG8_MMA(ai, bj, At, Bt) do { __builtin_amdgcn_s_setprio(1); _Pragma("unroll") for (int m = 0; m < 4; ++m) _Pragma("unroll") for (int n = 0; n < 2; ++n) _Pragma("unroll") for (int k = 0; k < 2; ++k) \
;         acc[ai][bj][m][n] = __builtin_amdgcn_mfma_f32_16x16x32_bf16(Bt[n][k], At[m][k], acc[ai][bj][m][n], 0, 0, 0); __builtin_amdgcn_s_setprio(0); } while (0)
; #define PG8_WAIT_L(n) asm volatile("s_waitcnt lgkmcnt(" #n ")" ::: "memory")
; #define PG8_BAR __builtin_amdgcn_s_barrier()
; #define PG8_SCHED __builtin_amdgcn_sched_barrier(0)
; template <class Epi>
; __device__ __forceinline__ void gemm_phase(LAS unsigned char* lds, const Gemm g, const StaticOrder& S, const Epi& E) {
;     ...
;         for (int t = 0; t < nt; t += 2) {
;             const bool last = (t == nt - 2);
;             const char* a1 = cA + (size_t)(t + 1) * kstep;
;             const char* a2 = last ? nA : cA + (size_t)(t + 2) * kstep; const char* b2 = last ? nB : cB + (size_t)(t + 2) * kstep;
;             const char* a3 = a2 + kstep; const char* b3 = b2 + kstep;
;             PG8_LDB(B0, 0, 0); PG8_SCHED; PG8_LDA(At, 0, 0); PG8_STAGE(PG8_SA(1, 1), a1 + hstep, voffA);
;             PG8_WAIT_L(8); PG8_BAR; PG8_WAIT_L(0); PG8_MMA(0, 0, At, B0); PG8_BAR; PG8_SCHED;
;             PG8_LDB(B1, 0, 1); PG8_STAGE(PG8_SB(0, 0), b2, voffB);
;             PG8_BAR; PG8_WAIT_L(0); PG8_MMA(0, 1, At, B1); PG8_BAR;
;             PG8_LDA(At, 0, 1); PG8_STAGE(PG8_SA(0, 0), a2, voffA);
;             PG8_BAR; PG8_WAIT_L(0); PG8_MMA(1, 0, At, B0); PG8_BAR; PG8_SCHED;
.LBB0_2731:
	s_ashr_i32 s11, s10, 31
	s_lshl_b64 s[0:1], s[10:11], 18
	v_cmp_lt_i64_e32 vcc, s[12:13], v[184:185]
	s_add_u32 s12, s23, s0
	s_addc_u32 s13, s24, s1
	s_and_b64 s[0:1], vcc, exec
	s_cselect_b32 s11, s13, s17
	s_cselect_b32 s39, s12, s16
	s_ashr_i32 s9, s8, 31
	s_lshl_b64 s[0:1], s[8:9], 18
	s_add_u32 s14, s25, s0
	s_addc_u32 s15, s26, s1
	s_and_b64 s[0:1], vcc, exec
	s_cselect_b32 s9, s15, s19
	s_cselect_b32 s40, s14, s18
	s_add_u32 s16, s16, 0x20080
	s_addc_u32 s17, s17, 0
	s_add_u32 s41, s18, 0x100
	s_addc_u32 s42, s19, 0
	s_mov_b32 s43, -2
	v_cmp_lt_u32_e32 vcc, 0xff, v228
	s_cbranch_vccnz .Lsp_skip_3
	s_setprio 1
.Lsp_skip_3:
	s_add_u32 s0, s16, 0xfffe0080
	s_addc_u32 s1, s17, -1
	s_add_i32 s48, 0, 0x10000
	v_add_u32_e32 v156, s48, v141
	ds_read_b128 v[144:147], v156
	ds_read_b128 v[148:151], v156 offset:1024
	ds_read_b128 v[152:155], v156 offset:2048
	ds_read_b128 v[156:159], v156 offset:3072
	s_cmp_eq_u32 s43, 4
	s_cselect_b32 s21, s11, s1
	s_cselect_b32 s20, s39, s0
	s_cselect_b32 s19, s9, s42
	s_cselect_b32 s18, s40, s41
	v_lshl_add_u64 v[176:177], s[16:17], 0, v[136:137]
	s_add_i32 m0, s28, 0xc000
	ds_read_b128 v[160:163], v143
	ds_read_b128 v[164:167], v143 offset:1024
	ds_read_b128 v[168:171], v143 offset:2048
	ds_read_b128 v[172:175], v143 offset:3072
	ds_read_b128 v[190:193], v143 offset:4096
	ds_read_b128 v[194:197], v143 offset:5120
	ds_read_b128 v[198:201], v143 offset:6144
	ds_read_b128 v[202:205], v143 offset:7168
	global_load_lds_dwordx4 v[176:177], off
	s_add_i32 m0, s28, 0xe000
	v_lshl_add_u64 v[176:177], s[16:17], 0, v[138:139]
	global_load_lds_dwordx4 v[176:177], off
	s_waitcnt lgkmcnt(8)
	s_barrier
	s_waitcnt lgkmcnt(0)
	v_mfma_f32_16x16x32_bf16 v[126:129], v[144:147], v[160:163], 0
	v_mfma_f32_16x16x32_bf16 v[122:125], v[152:155], v[160:163], 0
	v_mfma_f32_16x16x32_bf16 v[118:121], v[144:147], v[168:171], 0
	v_mfma_f32_16x16x32_bf16 v[114:117], v[152:155], v[168:171], 0
	v_mfma_f32_16x16x32_bf16 v[110:113], v[144:147], v[190:193], 0
	v_mfma_f32_16x16x32_bf16 v[106:109], v[152:155], v[190:193], 0
	v_mfma_f32_16x16x32_bf16 v[102:105], v[144:147], v[198:201], 0
	v_mfma_f32_16x16x32_bf16 v[98:101], v[152:155], v[198:201], 0
	v_mfma_f32_16x16x32_bf16 v[126:129], v[148:151], v[164:167], v[126:129]
	v_mfma_f32_16x16x32_bf16 v[122:125], v[156:159], v[164:167], v[122:125]
	v_mfma_f32_16x16x32_bf16 v[118:121], v[148:151], v[172:175], v[118:121]
	v_mfma_f32_16x16x32_bf16 v[114:117], v[156:159], v[172:175], v[114:117]
	v_mfma_f32_16x16x32_bf16 v[110:113], v[148:151], v[194:197], v[110:113]
	v_mfma_f32_16x16x32_bf16 v[106:109], v[156:159], v[194:197], v[106:109]
	v_mfma_f32_16x16x32_bf16 v[102:105], v[148:151], v[202:205], v[102:105]
	v_mfma_f32_16x16x32_bf16 v[98:101], v[156:159], v[202:205], v[98:101]
	s_barrier
	s_add_i32 s49, 0, 0x14000
	v_add_u32_e32 v176, s49, v141
	s_add_i32 s0, s48, s27
	ds_read_b128 v[206:209], v176
	ds_read_b128 v[210:213], v176 offset:1024
	ds_read_b128 v[214:217], v176 offset:2048
	ds_read_b128 v[218:221], v176 offset:3072
	v_lshl_add_u64 v[176:177], s[18:19], 0, v[4:5]
	s_mov_b32 m0, s0
	v_lshl_add_u64 v[186:187], s[18:19], 0, v[130:131]
	global_load_lds_dwordx4 v[176:177], off
	s_add_i32 m0, s0, 0x2000
	s_nop 0
	global_load_lds_dwordx4 v[186:187], off
	s_barrier
	s_waitcnt lgkmcnt(0)
	v_mfma_f32_16x16x32_bf16 v[70:73], v[206:209], v[160:163], 0
	v_mfma_f32_16x16x32_bf16 v[66:69], v[214:217], v[160:163], 0
	v_mfma_f32_16x16x32_bf16 v[54:57], v[206:209], v[168:171], 0
	v_mfma_f32_16x16x32_bf16 v[50:53], v[214:217], v[168:171], 0
	v_mfma_f32_16x16x32_bf16 v[46:49], v[206:209], v[190:193], 0
	v_mfma_f32_16x16x32_bf16 v[42:45], v[214:217], v[190:193], 0
	v_mfma_f32_16x16x32_bf16 v[38:41], v[206:209], v[198:201], 0
	v_mfma_f32_16x16x32_bf16 v[34:37], v[214:217], v[198:201], 0
	v_mfma_f32_16x16x32_bf16 v[70:73], v[210:213], v[164:167], v[70:73]
	v_mfma_f32_16x16x32_bf16 v[66:69], v[218:221], v[164:167], v[66:69]
	v_mfma_f32_16x16x32_bf16 v[54:57], v[210:213], v[172:175], v[54:57]
	v_mfma_f32_16x16x32_bf16 v[50:53], v[218:221], v[172:175], v[50:53]
	v_mfma_f32_16x16x32_bf16 v[46:49], v[210:213], v[194:197], v[46:49]
	v_mfma_f32_16x16x32_bf16 v[42:45], v[218:221], v[194:197], v[42:45]
	v_mfma_f32_16x16x32_bf16 v[38:41], v[210:213], v[202:205], v[38:41]
	v_mfma_f32_16x16x32_bf16 v[34:37], v[218:221], v[202:205], v[34:37]
	s_mov_b32 m0, s28
	v_lshl_add_u64 v[222:223], s[20:21], 0, v[134:135]
	s_barrier
	ds_read_b128 v[160:163], v143 offset:16384
	ds_read_b128 v[164:167], v143 offset:17408
	ds_read_b128 v[168:171], v143 offset:18432
	ds_read_b128 v[172:175], v143 offset:19456
	ds_read_b128 v[190:193], v143 offset:20480
	ds_read_b128 v[194:197], v143 offset:21504
	ds_read_b128 v[198:201], v143 offset:22528
	ds_read_b128 v[202:205], v143 offset:23552
	global_load_lds_dwordx4 v[222:223], off
	s_mov_b32 m0, s29
	v_lshl_add_u64 v[224:225], s[20:21], 0, v[132:133]
	global_load_lds_dwordx4 v[224:225], off
	s_barrier
	s_waitcnt lgkmcnt(0)
	v_mfma_f32_16x16x32_bf16 v[94:97], v[144:147], v[160:163], 0
	v_mfma_f32_16x16x32_bf16 v[90:93], v[152:155], v[160:163], 0
	v_mfma_f32_16x16x32_bf16 v[86:89], v[144:147], v[168:171], 0
	v_mfma_f32_16x16x32_bf16 v[82:85], v[152:155], v[168:171], 0
	v_mfma_f32_16x16x32_bf16 v[78:81], v[144:147], v[190:193], 0
	v_mfma_f32_16x16x32_bf16 v[74:77], v[152:155], v[190:193], 0
	v_mfma_f32_16x16x32_bf16 v[62:65], v[144:147], v[198:201], 0
	v_mfma_f32_16x16x32_bf16 v[58:61], v[152:155], v[198:201], 0
	v_mfma_f32_16x16x32_bf16 v[94:97], v[148:151], v[164:167], v[94:97]
	v_mfma_f32_16x16x32_bf16 v[90:93], v[156:159], v[164:167], v[90:93]
	v_mfma_f32_16x16x32_bf16 v[86:89], v[148:151], v[172:175], v[86:89]
	v_mfma_f32_16x16x32_bf16 v[82:85], v[156:159], v[172:175], v[82:85]
	v_mfma_f32_16x16x32_bf16 v[78:81], v[148:151], v[194:197], v[78:81]
	v_mfma_f32_16x16x32_bf16 v[74:77], v[156:159], v[194:197], v[74:77]
	v_mfma_f32_16x16x32_bf16 v[62:65], v[148:151], v[202:205], v[62:65]
	v_mfma_f32_16x16x32_bf16 v[58:61], v[156:159], v[202:205], v[58:61]
	s_barrier
; #define PG8_STAGE(bufoff, gbase, voff) do { _Pragma("unroll") for (int _i = 0; _i < 2; ++_i) \
;         __builtin_amdgcn_global_load_lds((const unsigned*)((const char*)(gbase) + (voff)[_i]), (LAS unsigned*)(lds + (bufoff) + ldsw + _i * 8192), 16, 0, 0); } while (0)
; #define PG8_LDA(dst, b, h) do { _Pragma("unroll") for (int m = 0; m < 4; ++m) _Pragma("unroll") for (int k = 0; k < 2; ++k) dst[m][k] = *(const LAS bf16x8*)(lds + PG8_SA(b, h) + aoff + m * 2048 + k * 1024); } while (0)
; #define PG8_LDB(dst, b, h) do { _Pragma("unroll") for (int n = 0; n < 2; ++n) _Pragma("unroll") for (int k = 0; k < 2; ++k) dst[n][k] = *(const LAS bf16x8*)(lds + PG8_SB(b, h) + boff + n * 2048 + k * 1024); } while (0)
; #define PG8_MMA(ai, bj, At, Bt) do { __builtin_amdgcn_s_setprio(1); _Pragma("unroll") for (int m = 0; m < 4; ++m) _Pragma("unroll") for (int n = 0; n < 2; ++n) _Pragma("unroll") for (int k = 0; k < 2; ++k) \
;         acc[ai][bj][m][n] = __builtin_amdgcn_mfma_f32_16x16x32_bf16(Bt[n][k], At[m][k], acc[ai][bj][m][n], 0, 0, 0); __builtin_amdgcn_s_setprio(0); } while (0)
; #define PG8_WAIT_V(n) asm volatile("s_waitcnt vmcnt(" #n ")" ::: "memory")
; #define PG8_WAIT_L(n) asm volatile("s_waitcnt lgkmcnt(" #n ")" ::: "memory")
; #define PG8_BAR __builtin_amdgcn_s_barrier()
; #define PG8_SCHED __builtin_amdgcn_sched_barrier(0)
; template <class Epi>
; __device__ __forceinline__ void gemm_phase(LAS unsigned char* lds, const Gemm g, const StaticOrder& S, const Epi& E) {
;     ...
;             PG8_STAGE(PG8_SB(0, 1), b2 + hstep, voffB);
;             PG8_WAIT_V(6); PG8_BAR; PG8_MMA(1, 1, At, B1); PG8_BAR;
;             PG8_LDB(B0, 1, 0); PG8_SCHED; PG8_LDA(At, 1, 0); PG8_STAGE(PG8_SA(0, 1), a2 + hstep, voffA);
;             PG8_WAIT_L(8); PG8_BAR; PG8_WAIT_L(0); PG8_MMA(0, 0, At, B0); PG8_BAR; PG8_SCHED;
;             PG8_LDB(B1, 1, 1); PG8_STAGE(PG8_SB(1, 0), b3, voffB);
;             PG8_BAR; PG8_WAIT_L(0); PG8_MMA(0, 1, At, B1); PG8_BAR;
	s_add_u32 s0, s18, 0x20000
	s_addc_u32 s1, s19, 0
	s_add_i32 s48, s49, s27
	s_mov_b32 m0, s48
	v_lshl_add_u64 v[144:145], s[0:1], 0, v[4:5]
	global_load_lds_dwordx4 v[144:145], off
	s_add_i32 m0, s48, 0x2000
	v_lshl_add_u64 v[144:145], s[0:1], 0, v[130:131]
	global_load_lds_dwordx4 v[144:145], off
	s_waitcnt vmcnt(6)
	s_barrier
	v_mfma_f32_16x16x32_bf16 v[30:33], v[206:209], v[160:163], 0
	v_mfma_f32_16x16x32_bf16 v[26:29], v[214:217], v[160:163], 0
	v_mfma_f32_16x16x32_bf16 v[22:25], v[206:209], v[168:171], 0
	v_mfma_f32_16x16x32_bf16 v[18:21], v[214:217], v[168:171], 0
	v_mfma_f32_16x16x32_bf16 v[14:17], v[206:209], v[190:193], 0
	v_mfma_f32_16x16x32_bf16 v[10:13], v[214:217], v[190:193], 0
	v_mfma_f32_16x16x32_bf16 v[6:9], v[206:209], v[198:201], 0
	v_mfma_f32_16x16x32_bf16 v[0:3], v[214:217], v[198:201], 0
	v_mfma_f32_16x16x32_bf16 v[30:33], v[210:213], v[164:167], v[30:33]
	v_mfma_f32_16x16x32_bf16 v[26:29], v[218:221], v[164:167], v[26:29]
	v_mfma_f32_16x16x32_bf16 v[22:25], v[210:213], v[172:175], v[22:25]
	v_mfma_f32_16x16x32_bf16 v[18:21], v[218:221], v[172:175], v[18:21]
	v_mfma_f32_16x16x32_bf16 v[14:17], v[210:213], v[194:197], v[14:17]
	v_mfma_f32_16x16x32_bf16 v[10:13], v[218:221], v[194:197], v[10:13]
	v_mfma_f32_16x16x32_bf16 v[6:9], v[210:213], v[202:205], v[6:9]
	v_mfma_f32_16x16x32_bf16 v[0:3], v[218:221], v[202:205], v[0:3]
	s_add_i32 s48, 0, 0x18000
	v_add_u32_e32 v156, s48, v141
	s_barrier
	ds_read_b128 v[144:147], v156
	ds_read_b128 v[148:151], v156 offset:1024
	ds_read_b128 v[152:155], v156 offset:2048
	ds_read_b128 v[156:159], v156 offset:3072
	s_add_u32 s0, s20, 0x20000
	s_addc_u32 s1, s21, 0
	s_mov_b32 m0, s30
	v_lshl_add_u64 v[206:207], s[0:1], 0, v[134:135]
	ds_read_b128 v[160:163], v143 offset:32768
	ds_read_b128 v[164:167], v143 offset:33792
	ds_read_b128 v[168:171], v143 offset:34816
	ds_read_b128 v[172:175], v143 offset:35840
	ds_read_b128 v[190:193], v143 offset:36864
	ds_read_b128 v[194:197], v143 offset:37888
	ds_read_b128 v[198:201], v143 offset:38912
	ds_read_b128 v[202:205], v143 offset:39936
	global_load_lds_dwordx4 v[206:207], off
	s_mov_b32 m0, s31
	v_lshl_add_u64 v[206:207], s[0:1], 0, v[132:133]
	global_load_lds_dwordx4 v[206:207], off
	s_waitcnt lgkmcnt(8)
	s_barrier
	s_waitcnt lgkmcnt(0)
	v_mfma_f32_16x16x32_bf16 v[126:129], v[144:147], v[160:163], v[126:129]
	v_mfma_f32_16x16x32_bf16 v[122:125], v[152:155], v[160:163], v[122:125]
	v_mfma_f32_16x16x32_bf16 v[118:121], v[144:147], v[168:171], v[118:121]
	v_mfma_f32_16x16x32_bf16 v[114:117], v[152:155], v[168:171], v[114:117]
	v_mfma_f32_16x16x32_bf16 v[110:113], v[144:147], v[190:193], v[110:113]
	v_mfma_f32_16x16x32_bf16 v[106:109], v[152:155], v[190:193], v[106:109]
	v_mfma_f32_16x16x32_bf16 v[102:105], v[144:147], v[198:201], v[102:105]
	v_mfma_f32_16x16x32_bf16 v[98:101], v[152:155], v[198:201], v[98:101]
	v_mfma_f32_16x16x32_bf16 v[126:129], v[148:151], v[164:167], v[126:129]
	v_mfma_f32_16x16x32_bf16 v[122:125], v[156:159], v[164:167], v[122:125]
	v_mfma_f32_16x16x32_bf16 v[118:121], v[148:151], v[172:175], v[118:121]
	v_mfma_f32_16x16x32_bf16 v[114:117], v[156:159], v[172:175], v[114:117]
	v_mfma_f32_16x16x32_bf16 v[110:113], v[148:151], v[194:197], v[110:113]
	v_mfma_f32_16x16x32_bf16 v[106:109], v[156:159], v[194:197], v[106:109]
	v_mfma_f32_16x16x32_bf16 v[102:105], v[148:151], v[202:205], v[102:105]
	v_mfma_f32_16x16x32_bf16 v[98:101], v[156:159], v[202:205], v[98:101]
	s_barrier
	s_add_i32 s20, 0, 0x1c000
	s_add_i32 s0, s48, s27
	v_add_u32_e32 v218, s20, v141
	v_lshl_add_u64 v[176:177], v[176:177], 0, s[86:87]
	s_mov_b32 m0, s0
	ds_read_b128 v[206:209], v218
	ds_read_b128 v[210:213], v218 offset:1024
	ds_read_b128 v[214:217], v218 offset:2048
	ds_read_b128 v[218:221], v218 offset:3072
	global_load_lds_dwordx4 v[176:177], off
	s_add_i32 m0, s0, 0x2000
	v_lshl_add_u64 v[176:177], v[186:187], 0, s[86:87]
	global_load_lds_dwordx4 v[176:177], off
	s_barrier
; #define PG8_STAGE(bufoff, gbase, voff) do { _Pragma("unroll") for (int _i = 0; _i < 2; ++_i) \
;         __builtin_amdgcn_global_load_lds((const unsigned*)((const char*)(gbase) + (voff)[_i]), (LAS unsigned*)(lds + (bufoff) + ldsw + _i * 8192), 16, 0, 0); } while (0)
; #define PG8_LDA(dst, b, h) do { _Pragma("unroll") for (int m = 0; m < 4; ++m) _Pragma("unroll") for (int k = 0; k < 2; ++k) dst[m][k] = *(const LAS bf16x8*)(lds + PG8_SA(b, h) + aoff + m * 2048 + k * 1024); } while (0)
; #define PG8_LDB(dst, b, h) do { _Pragma("unroll") for (int n = 0; n < 2; ++n) _Pragma("unroll") for (int k = 0; k < 2; ++k) dst[n][k] = *(const LAS bf16x8*)(lds + PG8_SB(b, h) + boff + n * 2048 + k * 1024); } while (0)
; #define PG8_MMA(ai, bj, At, Bt) do { __builtin_amdgcn_s_setprio(1); _Pragma("unroll") for (int m = 0; m < 4; ++m) _Pragma("unroll") for (int n = 0; n < 2; ++n) _Pragma("unroll") for (int k = 0; k < 2; ++k) \
;         acc[ai][bj][m][n] = __builtin_amdgcn_mfma_f32_16x16x32_bf16(Bt[n][k], At[m][k], acc[ai][bj][m][n], 0, 0, 0); __builtin_amdgcn_s_setprio(0); } while (0)
; #define PG8_WAIT_V(n) asm volatile("s_waitcnt vmcnt(" #n ")" ::: "memory")
; #define PG8_WAIT_L(n) asm volatile("s_waitcnt lgkmcnt(" #n ")" ::: "memory")
; #define PG8_BAR __builtin_amdgcn_s_barrier()
; #define PG8_SCHED __builtin_amdgcn_sched_barrier(0)
; template <class Epi>
; __device__ __forceinline__ void gemm_phase(LAS unsigned char* lds, const Gemm g, const StaticOrder& S, const Epi& E) {
;     ...
;             PG8_LDB(B1, 1, 1); PG8_STAGE(PG8_SB(1, 0), b3, voffB);
;             PG8_BAR; PG8_WAIT_L(0); PG8_MMA(0, 1, At, B1); PG8_BAR;
;             PG8_LDA(At, 1, 1); PG8_STAGE(PG8_SA(1, 0), a3, voffA);
;             PG8_BAR; PG8_WAIT_L(0); PG8_MMA(1, 0, At, B0); PG8_BAR; PG8_SCHED;
;             PG8_STAGE(PG8_SB(1, 1), b3 + hstep, voffB);
;             PG8_WAIT_V(6); PG8_BAR; PG8_MMA(1, 1, At, B1); PG8_BAR;
	s_waitcnt lgkmcnt(0)
	v_mfma_f32_16x16x32_bf16 v[70:73], v[206:209], v[160:163], v[70:73]
	v_mfma_f32_16x16x32_bf16 v[66:69], v[214:217], v[160:163], v[66:69]
	v_mfma_f32_16x16x32_bf16 v[54:57], v[206:209], v[168:171], v[54:57]
	v_mfma_f32_16x16x32_bf16 v[50:53], v[214:217], v[168:171], v[50:53]
	v_mfma_f32_16x16x32_bf16 v[46:49], v[206:209], v[190:193], v[46:49]
	v_mfma_f32_16x16x32_bf16 v[42:45], v[214:217], v[190:193], v[42:45]
	v_mfma_f32_16x16x32_bf16 v[38:41], v[206:209], v[198:201], v[38:41]
	v_mfma_f32_16x16x32_bf16 v[34:37], v[214:217], v[198:201], v[34:37]
	v_mfma_f32_16x16x32_bf16 v[70:73], v[210:213], v[164:167], v[70:73]
	v_mfma_f32_16x16x32_bf16 v[66:69], v[218:221], v[164:167], v[66:69]
	v_mfma_f32_16x16x32_bf16 v[54:57], v[210:213], v[172:175], v[54:57]
	v_mfma_f32_16x16x32_bf16 v[50:53], v[218:221], v[172:175], v[50:53]
	v_mfma_f32_16x16x32_bf16 v[46:49], v[210:213], v[194:197], v[46:49]
	v_mfma_f32_16x16x32_bf16 v[42:45], v[218:221], v[194:197], v[42:45]
	v_mfma_f32_16x16x32_bf16 v[38:41], v[210:213], v[202:205], v[38:41]
	v_mfma_f32_16x16x32_bf16 v[34:37], v[218:221], v[202:205], v[34:37]
	s_mov_b32 m0, s34
	v_lshl_add_u64 v[176:177], v[222:223], 0, s[86:87]
	s_barrier
	ds_read_b128 v[160:163], v143 offset:49152
	ds_read_b128 v[164:167], v143 offset:50176
	ds_read_b128 v[168:171], v143 offset:51200
	ds_read_b128 v[172:175], v143 offset:52224
	ds_read_b128 v[190:193], v143 offset:53248
	ds_read_b128 v[194:197], v143 offset:54272
	ds_read_b128 v[198:201], v143 offset:55296
	ds_read_b128 v[202:205], v143 offset:56320
	global_load_lds_dwordx4 v[176:177], off
	s_mov_b32 m0, s35
	v_lshl_add_u64 v[176:177], v[224:225], 0, s[86:87]
	global_load_lds_dwordx4 v[176:177], off
	s_barrier
	s_waitcnt lgkmcnt(0)
	v_mfma_f32_16x16x32_bf16 v[94:97], v[144:147], v[160:163], v[94:97]
	v_mfma_f32_16x16x32_bf16 v[90:93], v[152:155], v[160:163], v[90:93]
	v_mfma_f32_16x16x32_bf16 v[86:89], v[144:147], v[168:171], v[86:89]
	v_mfma_f32_16x16x32_bf16 v[82:85], v[152:155], v[168:171], v[82:85]
	v_mfma_f32_16x16x32_bf16 v[78:81], v[144:147], v[190:193], v[78:81]
	v_mfma_f32_16x16x32_bf16 v[74:77], v[152:155], v[190:193], v[74:77]
	v_mfma_f32_16x16x32_bf16 v[62:65], v[144:147], v[198:201], v[62:65]
	v_mfma_f32_16x16x32_bf16 v[58:61], v[152:155], v[198:201], v[58:61]
	v_mfma_f32_16x16x32_bf16 v[94:97], v[148:151], v[164:167], v[94:97]
	v_mfma_f32_16x16x32_bf16 v[90:93], v[156:159], v[164:167], v[90:93]
	v_mfma_f32_16x16x32_bf16 v[86:89], v[148:151], v[172:175], v[86:89]
	v_mfma_f32_16x16x32_bf16 v[82:85], v[156:159], v[172:175], v[82:85]
	v_mfma_f32_16x16x32_bf16 v[78:81], v[148:151], v[194:197], v[78:81]
	v_mfma_f32_16x16x32_bf16 v[74:77], v[156:159], v[194:197], v[74:77]
	v_mfma_f32_16x16x32_bf16 v[62:65], v[148:151], v[202:205], v[62:65]
	v_mfma_f32_16x16x32_bf16 v[58:61], v[156:159], v[202:205], v[58:61]
	s_barrier
	s_add_u32 s0, s18, 0x20080
	s_addc_u32 s1, s19, 0
	s_add_i32 s18, s20, s27
	s_mov_b32 m0, s18
	v_lshl_add_u64 v[144:145], s[0:1], 0, v[4:5]
	global_load_lds_dwordx4 v[144:145], off
	s_add_i32 m0, s18, 0x2000
	v_lshl_add_u64 v[144:145], s[0:1], 0, v[130:131]
	global_load_lds_dwordx4 v[144:145], off
	s_waitcnt vmcnt(6)
	s_barrier
	v_mfma_f32_16x16x32_bf16 v[30:33], v[206:209], v[160:163], v[30:33]
	v_mfma_f32_16x16x32_bf16 v[26:29], v[214:217], v[160:163], v[26:29]
	v_mfma_f32_16x16x32_bf16 v[22:25], v[206:209], v[168:171], v[22:25]
	v_mfma_f32_16x16x32_bf16 v[18:21], v[214:217], v[168:171], v[18:21]
	v_mfma_f32_16x16x32_bf16 v[14:17], v[206:209], v[190:193], v[14:17]
	v_mfma_f32_16x16x32_bf16 v[10:13], v[214:217], v[190:193], v[10:13]
	v_mfma_f32_16x16x32_bf16 v[6:9], v[206:209], v[198:201], v[6:9]
	v_mfma_f32_16x16x32_bf16 v[0:3], v[214:217], v[198:201], v[0:3]
	v_mfma_f32_16x16x32_bf16 v[30:33], v[210:213], v[164:167], v[30:33]
	v_mfma_f32_16x16x32_bf16 v[26:29], v[218:221], v[164:167], v[26:29]
	v_mfma_f32_16x16x32_bf16 v[22:25], v[210:213], v[172:175], v[22:25]
	v_mfma_f32_16x16x32_bf16 v[18:21], v[218:221], v[172:175], v[18:21]
	v_mfma_f32_16x16x32_bf16 v[14:17], v[210:213], v[194:197], v[14:17]
	v_mfma_f32_16x16x32_bf16 v[10:13], v[218:221], v[194:197], v[10:13]
	v_mfma_f32_16x16x32_bf16 v[6:9], v[210:213], v[202:205], v[6:9]
	v_mfma_f32_16x16x32_bf16 v[0:3], v[218:221], v[202:205], v[0:3]
	s_add_i32 s43, s43, 2
	s_add_u32 s16, s16, 0x100
	s_addc_u32 s17, s17, 0
	s_add_u32 s41, s41, 0x100
	s_addc_u32 s42, s42, 0
	s_cmp_gt_u32 s43, 5
	s_barrier
	s_cbranch_scc1 .Lpeel_exit_3

; __device__ __forceinline__ unsigned cvt_pk_bf16(float lo, float hi) { unsigned r; asm volatile("s_nop 0\n\tv_cvt_pk_bf16_f32 %0, %1, %2" : "=v"(r) : "v"(lo), "v"(hi)); return r; }
;     __device__ __forceinline__ void operator()(const f32x4 (&acc)[2][2][4][2], const Unit& u, int wr, int wc, int fr, int fq) const {
;         const int row0 = u.pm * 256 + wr * 64 + fr, col0 = u.pn * 256 + wc * 32 + 8 * fq;
;         f32x4 ra = (f32x4){1.f, 1.f, 1.f, 1.f}, rb = ra;
;         f32x4 swv[4] = {(f32x4){0.f, 0.f, 0.f, 0.f}, (f32x4){0.f, 0.f, 0.f, 0.f}, (f32x4){0.f, 0.f, 0.f, 0.f}, (f32x4){0.f, 0.f, 0.f, 0.f}};
;         if (ss) { load_rstd(ss, row0, ra, rb); const float* swp = sw + (size_t)(u.pm >> 3) * ldc + col0;
;             swv[0] = *(const f32x4*)(swp); swv[1] = *(const f32x4*)(swp + 4); swv[2] = *(const f32x4*)(swp + 128); swv[3] = *(const f32x4*)(swp + 132); }
; #pragma unroll
;         for (int bj = 0; bj < 2; ++bj) {
;             const f32x4 s0 = swv[2 * bj], s1 = swv[2 * bj + 1];
; #pragma unroll
;             for (int ai = 0; ai < 2; ++ai)
; #pragma unroll
;                 for (int m = 0; m < 4; ++m) { const int r = row0 + ai * 128 + m * 16;
;                     const float rstd = ai ? rb[m] : ra[m];
;                     const f32x4 v0 = acc[ai][bj][m][0] * rstd + s0, v1 = acc[ai][bj][m][1] * rstd + s1;
;                     uint4 st; st.x = cvt_pk_bf16(v0[0], v0[1]); st.y = cvt_pk_bf16(v0[2], v0[3]); st.z = cvt_pk_bf16(v1[0], v1[1]); st.w = cvt_pk_bf16(v1[2], v1[3]);
;                     *(uint4*)(O + (size_t)r * ldc + col0 + bj * 128) = st; }
.Lpeel_exit_3:
	s_setprio 0
	v_lshl_add_u32 v144, s38, 8, v140
	v_lshl_or_b32 v146, s37, 8, v142
	v_ashrrev_i32_e32 v145, 31, v144
	v_pk_add_f32 v[126:127], v[126:127], 0 op_sel_hi:[1,0]
	v_ashrrev_i32_e32 v147, 31, v146
	v_pk_add_f32 v[128:129], v[128:129], 0 op_sel_hi:[1,0]
	v_pk_add_f32 v[148:149], v[124:125], 0 op_sel_hi:[1,0]
	v_pk_add_f32 v[124:125], v[122:123], 0 op_sel_hi:[1,0]
	s_nop 0
	v_cvt_pk_bf16_f32 v122, v126, v127
	v_lshlrev_b64 v[126:127], 11, v[144:145]
	s_nop 0
	v_cvt_pk_bf16_f32 v123, v128, v129
	v_lshl_add_u64 v[126:127], s[6:7], 0, v[126:127]
	v_lshlrev_b64 v[128:129], 1, v[146:147]
	v_lshl_add_u64 v[126:127], v[126:127], 0, v[128:129]
	s_nop 0
	v_cvt_pk_bf16_f32 v124, v124, v125
	s_nop 0
	v_cvt_pk_bf16_f32 v125, v148, v149
	global_store_dwordx4 v[126:127], v[122:125], off
	v_pk_add_f32 v[118:119], v[118:119], 0 op_sel_hi:[1,0]
	v_pk_add_f32 v[120:121], v[120:121], 0 op_sel_hi:[1,0]
	v_or_b32_e32 v122, 16, v144
	v_ashrrev_i32_e32 v123, 31, v122
	v_pk_add_f32 v[124:125], v[116:117], 0 op_sel_hi:[1,0]
	v_pk_add_f32 v[116:117], v[114:115], 0 op_sel_hi:[1,0]
	s_nop 0
	v_cvt_pk_bf16_f32 v114, v118, v119
	v_lshlrev_b64 v[118:119], 11, v[122:123]
	v_lshl_add_u64 v[118:119], s[6:7], 0, v[118:119]
	v_lshl_add_u64 v[118:119], v[118:119], 0, v[128:129]
	s_nop 0
	v_cvt_pk_bf16_f32 v115, v120, v121
	s_nop 0
	v_cvt_pk_bf16_f32 v116, v116, v117
	s_nop 0
	v_cvt_pk_bf16_f32 v117, v124, v125
	global_store_dwordx4 v[118:119], v[114:117], off
	v_pk_add_f32 v[110:111], v[110:111], 0 op_sel_hi:[1,0]
	v_pk_add_f32 v[112:113], v[112:113], 0 op_sel_hi:[1,0]
	v_or_b32_e32 v114, 32, v144
	v_ashrrev_i32_e32 v115, 31, v114
	v_pk_add_f32 v[116:117], v[108:109], 0 op_sel_hi:[1,0]
	v_pk_add_f32 v[108:109], v[106:107], 0 op_sel_hi:[1,0]
	s_nop 0
	v_cvt_pk_bf16_f32 v106, v110, v111
	v_lshlrev_b64 v[110:111], 11, v[114:115]
	v_lshl_add_u64 v[110:111], s[6:7], 0, v[110:111]
	v_lshl_add_u64 v[110:111], v[110:111], 0, v[128:129]
	s_nop 0
	v_cvt_pk_bf16_f32 v107, v112, v113
	s_nop 0
	v_cvt_pk_bf16_f32 v108, v108, v109
	s_nop 0
	v_cvt_pk_bf16_f32 v109, v116, v117
	global_store_dwordx4 v[110:111], v[106:109], off
	v_pk_add_f32 v[102:103], v[102:103], 0 op_sel_hi:[1,0]
	v_pk_add_f32 v[104:105], v[104:105], 0 op_sel_hi:[1,0]
	v_or_b32_e32 v106, 48, v144
	v_ashrrev_i32_e32 v107, 31, v106
	v_pk_add_f32 v[108:109], v[100:101], 0 op_sel_hi:[1,0]
	v_pk_add_f32 v[100:101], v[98:99], 0 op_sel_hi:[1,0]
	s_nop 0
	v_cvt_pk_bf16_f32 v98, v102, v103
	v_lshlrev_b64 v[102:103], 11, v[106:107]
	v_lshl_add_u64 v[102:103], s[6:7], 0, v[102:103]
	s_nop 0
	v_cvt_pk_bf16_f32 v99, v104, v105
	v_lshl_add_u64 v[102:103], v[102:103], 0, v[128:129]
	v_pk_add_f32 v[96:97], v[96:97], 0 op_sel_hi:[1,0]
	s_nop 0
	v_cvt_pk_bf16_f32 v100, v100, v101
	s_nop 0
	v_cvt_pk_bf16_f32 v101, v108, v109
	global_store_dwordx4 v[102:103], v[98:101], off
	v_pk_add_f32 v[94:95], v[94:95], 0 op_sel_hi:[1,0]
	s_mov_b64 s[0:1], 0x40000
	v_pk_add_f32 v[98:99], v[92:93], 0 op_sel_hi:[1,0]
	v_pk_add_f32 v[92:93], v[90:91], 0 op_sel_hi:[1,0]
	s_nop 0
	v_cvt_pk_bf16_f32 v90, v94, v95
	s_nop 0
	v_cvt_pk_bf16_f32 v91, v96, v97
	v_add_co_u32_e32 v96, vcc, s85, v126
	v_lshl_add_u64 v[94:95], v[126:127], 0, s[0:1]
	s_nop 0
	v_addc_co_u32_e32 v97, vcc, 0, v127, vcc
	v_pk_add_f32 v[86:87], v[86:87], 0 op_sel_hi:[1,0]
	s_mov_b64 s[0:1], 0x48000
	s_nop 0
	v_cvt_pk_bf16_f32 v92, v92, v93
	s_nop 0
	v_cvt_pk_bf16_f32 v93, v98, v99
	global_store_dwordx4 v[96:97], v[90:93], off
	v_pk_add_f32 v[88:89], v[88:89], 0 op_sel_hi:[1,0]
	v_pk_add_f32 v[78:79], v[78:79], 0 op_sel_hi:[1,0]
	v_pk_add_f32 v[90:91], v[84:85], 0 op_sel_hi:[1,0]
	v_pk_add_f32 v[84:85], v[82:83], 0 op_sel_hi:[1,0]
	s_nop 0
	v_cvt_pk_bf16_f32 v82, v86, v87
	v_lshl_add_u64 v[86:87], v[126:127], 0, s[0:1]
	s_mov_b32 s0, 0x48000
	s_nop 0
	v_cvt_pk_bf16_f32 v83, v88, v89
	v_add_co_u32_e32 v88, vcc, s0, v126
	s_mov_b64 s[0:1], 0x50000
	s_nop 0
	v_addc_co_u32_e32 v89, vcc, 0, v127, vcc
	s_nop 0
	v_cvt_pk_bf16_f32 v84, v84, v85
	s_nop 0
	v_cvt_pk_bf16_f32 v85, v90, v91
	global_store_dwordx4 v[88:89], v[82:85], off
	v_pk_add_f32 v[80:81], v[80:81], 0 op_sel_hi:[1,0]
	v_pk_add_f32 v[62:63], v[62:63], 0 op_sel_hi:[1,0]
	v_pk_add_f32 v[82:83], v[76:77], 0 op_sel_hi:[1,0]
	v_pk_add_f32 v[76:77], v[74:75], 0 op_sel_hi:[1,0]
	s_nop 0
	v_cvt_pk_bf16_f32 v74, v78, v79
	v_lshl_add_u64 v[78:79], v[126:127], 0, s[0:1]
	s_mov_b32 s0, 0x50000
	s_nop 0
	v_cvt_pk_bf16_f32 v75, v80, v81
	v_add_co_u32_e32 v80, vcc, s0, v126
; __device__ __forceinline__ unsigned cvt_pk_bf16(float lo, float hi) { unsigned r; asm volatile("s_nop 0\n\tv_cvt_pk_bf16_f32 %0, %1, %2" : "=v"(r) : "v"(lo), "v"(hi)); return r; }
; #define PG8_WAIT_V(n) asm volatile("s_waitcnt vmcnt(" #n ")" ::: "memory")
; #define PG8_BAR __builtin_amdgcn_s_barrier()
; template <class Epi>
; __device__ __forceinline__ void gemm_phase(LAS unsigned char* lds, const Gemm g, const StaticOrder& S, const Epi& E) {
;     ...
;     PG8_WAIT_V(0);
;     if (wr == 0) PG8_BAR;
;     PG8_BAR;
;     __device__ __forceinline__ void operator()(const f32x4 (&acc)[2][2][4][2], const Unit& u, int wr, int wc, int fr, int fq) const {
;     ...
;                 for (int m = 0; m < 4; ++m) { const int r = row0 + ai * 128 + m * 16;
;                     const float rstd = ai ? rb[m] : ra[m];
;                     const f32x4 v0 = acc[ai][bj][m][0] * rstd + s0, v1 = acc[ai][bj][m][1] * rstd + s1;
;                     uint4 st; st.x = cvt_pk_bf16(v0[0], v0[1]); st.y = cvt_pk_bf16(v0[2], v0[3]); st.z = cvt_pk_bf16(v1[0], v1[1]); st.w = cvt_pk_bf16(v1[2], v1[3]);
;                     *(uint4*)(O + (size_t)r * ldc + col0 + bj * 128) = st; }
	s_mov_b64 s[0:1], 0x58000
	s_nop 0
	v_addc_co_u32_e32 v81, vcc, 0, v127, vcc
	s_nop 0
	v_cvt_pk_bf16_f32 v76, v76, v77
	s_nop 0
	v_cvt_pk_bf16_f32 v77, v82, v83
	global_store_dwordx4 v[80:81], v[74:77], off
	v_pk_add_f32 v[64:65], v[64:65], 0 op_sel_hi:[1,0]
	v_pk_add_f32 v[66:67], v[66:67], 0 op_sel_hi:[1,0]
	v_pk_add_f32 v[74:75], v[60:61], 0 op_sel_hi:[1,0]
	v_pk_add_f32 v[60:61], v[58:59], 0 op_sel_hi:[1,0]
	s_nop 0
	v_cvt_pk_bf16_f32 v58, v62, v63
	v_lshl_add_u64 v[62:63], v[126:127], 0, s[0:1]
	s_mov_b32 s0, 0x58000
	s_nop 0
	v_cvt_pk_bf16_f32 v59, v64, v65
	v_add_co_u32_e32 v64, vcc, s0, v126
	s_nop 0
	v_cvt_pk_bf16_f32 v60, v60, v61
	s_nop 0
	v_cvt_pk_bf16_f32 v61, v74, v75
	v_pk_add_f32 v[56:57], v[56:57], 0 op_sel_hi:[1,0]
	s_nop 0
	v_addc_co_u32_e32 v65, vcc, 0, v127, vcc
	global_store_dwordx4 v[64:65], v[58:61], off
	v_pk_add_f32 v[64:65], v[68:69], 0 op_sel_hi:[1,0]
	v_pk_add_f32 v[54:55], v[54:55], 0 op_sel_hi:[1,0]
	v_pk_add_f32 v[58:59], v[70:71], 0 op_sel_hi:[1,0]
	v_pk_add_f32 v[60:61], v[72:73], 0 op_sel_hi:[1,0]
	s_nop 0
	v_cvt_pk_bf16_f32 v58, v58, v59
	v_pk_add_f32 v[48:49], v[48:49], 0 op_sel_hi:[1,0]
	s_nop 0
	v_cvt_pk_bf16_f32 v59, v60, v61
	s_nop 0
	v_cvt_pk_bf16_f32 v60, v66, v67
	s_nop 0
	v_cvt_pk_bf16_f32 v61, v64, v65
	global_store_dwordx4 v[126:127], v[58:61], off offset:256
	v_pk_add_f32 v[46:47], v[46:47], 0 op_sel_hi:[1,0]
	v_pk_add_f32 v[40:41], v[40:41], 0 op_sel_hi:[1,0]
	v_pk_add_f32 v[58:59], v[52:53], 0 op_sel_hi:[1,0]
	v_pk_add_f32 v[52:53], v[50:51], 0 op_sel_hi:[1,0]
	s_nop 0
	v_cvt_pk_bf16_f32 v50, v54, v55
	s_nop 0
	v_cvt_pk_bf16_f32 v51, v56, v57
	v_pk_add_f32 v[38:39], v[38:39], 0 op_sel_hi:[1,0]
	s_nop 0
	v_cvt_pk_bf16_f32 v52, v52, v53
	s_nop 0
	v_cvt_pk_bf16_f32 v53, v58, v59
	global_store_dwordx4 v[118:119], v[50:53], off offset:256
	v_pk_add_f32 v[32:33], v[32:33], 0 op_sel_hi:[1,0]
	v_pk_add_f32 v[30:31], v[30:31], 0 op_sel_hi:[1,0]
	v_pk_add_f32 v[50:51], v[44:45], 0 op_sel_hi:[1,0]
	v_pk_add_f32 v[44:45], v[42:43], 0 op_sel_hi:[1,0]
	s_nop 0
	v_cvt_pk_bf16_f32 v42, v46, v47
	s_nop 0
	v_cvt_pk_bf16_f32 v43, v48, v49
	v_pk_add_f32 v[24:25], v[24:25], 0 op_sel_hi:[1,0]
	s_nop 0
	v_cvt_pk_bf16_f32 v44, v44, v45
	s_nop 0
	v_cvt_pk_bf16_f32 v45, v50, v51
	global_store_dwordx4 v[110:111], v[42:45], off offset:256
	v_pk_add_f32 v[22:23], v[22:23], 0 op_sel_hi:[1,0]
	v_pk_add_f32 v[16:17], v[16:17], 0 op_sel_hi:[1,0]
	v_pk_add_f32 v[42:43], v[36:37], 0 op_sel_hi:[1,0]
	v_pk_add_f32 v[36:37], v[34:35], 0 op_sel_hi:[1,0]
	s_nop 0
	v_cvt_pk_bf16_f32 v34, v38, v39
	s_nop 0
	v_cvt_pk_bf16_f32 v35, v40, v41
	v_pk_add_f32 v[14:15], v[14:15], 0 op_sel_hi:[1,0]
	s_nop 0
	v_cvt_pk_bf16_f32 v36, v36, v37
	s_nop 0
	v_cvt_pk_bf16_f32 v37, v42, v43
	global_store_dwordx4 v[102:103], v[34:37], off offset:256
	s_and_b64 vcc, exec, s[4:5]
	s_mov_b32 s37, s8
	v_pk_add_f32 v[34:35], v[28:29], 0 op_sel_hi:[1,0]
	v_pk_add_f32 v[28:29], v[26:27], 0 op_sel_hi:[1,0]
	s_nop 0
	v_cvt_pk_bf16_f32 v26, v30, v31
	s_nop 0
	v_cvt_pk_bf16_f32 v27, v32, v33
	s_mov_b32 s38, s10
	s_nop 0
	v_cvt_pk_bf16_f32 v28, v28, v29
	s_nop 0
	v_cvt_pk_bf16_f32 v29, v34, v35
	global_store_dwordx4 v[94:95], v[26:29], off offset:256
	s_mov_b64 s[18:19], s[14:15]
	s_mov_b64 s[16:17], s[12:13]
	v_pk_add_f32 v[26:27], v[20:21], 0 op_sel_hi:[1,0]
	v_pk_add_f32 v[20:21], v[18:19], 0 op_sel_hi:[1,0]
	s_nop 0
	v_cvt_pk_bf16_f32 v18, v22, v23
	s_nop 0
	v_cvt_pk_bf16_f32 v19, v24, v25
	v_pk_add_f32 v[8:9], v[8:9], 0 op_sel_hi:[1,0]
	s_nop 0
	v_cvt_pk_bf16_f32 v20, v20, v21
	s_nop 0
	v_cvt_pk_bf16_f32 v21, v26, v27
	global_store_dwordx4 v[86:87], v[18:21], off offset:256
	v_pk_add_f32 v[6:7], v[6:7], 0 op_sel_hi:[1,0]
	s_nop 0
	v_pk_add_f32 v[18:19], v[12:13], 0 op_sel_hi:[1,0]
	v_pk_add_f32 v[12:13], v[10:11], 0 op_sel_hi:[1,0]
	s_nop 0
	v_cvt_pk_bf16_f32 v10, v14, v15
	s_nop 0
	v_cvt_pk_bf16_f32 v11, v16, v17
	s_nop 0
	s_nop 0
	v_cvt_pk_bf16_f32 v12, v12, v13
	s_nop 0
	v_cvt_pk_bf16_f32 v13, v18, v19
	global_store_dwordx4 v[78:79], v[10:13], off offset:256
	s_nop 1
	v_pk_add_f32 v[10:11], v[2:3], 0 op_sel_hi:[1,0]
	v_pk_add_f32 v[2:3], v[0:1], 0 op_sel_hi:[1,0]
	s_nop 0
	v_cvt_pk_bf16_f32 v0, v6, v7
	s_nop 0
	v_cvt_pk_bf16_f32 v1, v8, v9
	s_nop 0
	s_nop 0
	v_cvt_pk_bf16_f32 v2, v2, v3
	s_nop 0
	v_cvt_pk_bf16_f32 v3, v10, v11
	global_store_dwordx4 v[62:63], v[0:3], off offset:256
	s_cbranch_vccz .LBB0_2725
	s_waitcnt vmcnt(0)
	s_cmpk_gt_u32 s22, 0xff
	s_cbranch_scc1 .LBB0_2736
	s_barrier

; #define PG8_STAGE(bufoff, gbase, voff) do { _Pragma("unroll") for (int _i = 0; _i < 2; ++_i) \
;         __builtin_amdgcn_global_load_lds((const unsigned*)((const char*)(gbase) + (voff)[_i]), (LAS unsigned*)(lds + (bufoff) + ldsw + _i * 8192), 16, 0, 0); } while (0)
; #define PG8_LDA(dst, b, h) do { _Pragma("unroll") for (int m = 0; m < 4; ++m) _Pragma("unroll") for (int k = 0; k < 2; ++k) dst[m][k] = *(const LAS bf16x8*)(lds + PG8_SA(b, h) + aoff + m * 2048 + k * 1024); } while (0)
; #define PG8_LDB(dst, b, h) do { _Pragma("unroll") for (int n = 0; n < 2; ++n) _Pragma("unroll") for (int k = 0; k < 2; ++k) dst[n][k] = *(const LAS bf16x8*)(lds + PG8_SB(b, h) + boff + n * 2048 + k * 1024); } while (0)
; #define PG8_MMA(ai, bj, At, Bt) do { __builtin_amdgcn_s_setprio(1); _Pragma("unroll") for (int m = 0; m < 4; ++m) _Pragma("unroll") for (int n = 0; n < 2; ++n) _Pragma("unroll") for (int k = 0; k < 2; ++k) \
;         acc[ai][bj][m][n] = __builtin_amdgcn_mfma_f32_16x16x32_bf16(Bt[n][k], At[m][k], acc[ai][bj][m][n], 0, 0, 0); __builtin_amdgcn_s_setprio(0); } while (0)
; #define PG8_WAIT_L(n) asm volatile("s_waitcnt lgkmcnt(" #n ")" ::: "memory")
; #define PG8_BAR __builtin_amdgcn_s_barrier()
; #define PG8_SCHED __builtin_amdgcn_sched_barrier(0)
; template <class Epi>
; __device__ __forceinline__ void gemm_phase(LAS unsigned char* lds, const Gemm g, const StaticOrder& S, const Epi& E) {
;     ...
;         for (int t = 0; t < nt; t += 2) {
;             const bool last = (t == nt - 2);
;             const char* a1 = cA + (size_t)(t + 1) * kstep;
;             const char* a2 = last ? nA : cA + (size_t)(t + 2) * kstep; const char* b2 = last ? nB : cB + (size_t)(t + 2) * kstep;
;             const char* a3 = a2 + kstep; const char* b3 = b2 + kstep;
;             PG8_LDB(B0, 0, 0); PG8_SCHED; PG8_LDA(At, 0, 0); PG8_STAGE(PG8_SA(1, 1), a1 + hstep, voffA);
;             PG8_WAIT_L(8); PG8_BAR; PG8_WAIT_L(0); PG8_MMA(0, 0, At, B0); PG8_BAR; PG8_SCHED;
;             PG8_LDB(B1, 0, 1); PG8_STAGE(PG8_SB(0, 0), b2, voffB);
;             PG8_BAR; PG8_WAIT_L(0); PG8_MMA(0, 1, At, B1); PG8_BAR;
;             PG8_LDA(At, 0, 1); PG8_STAGE(PG8_SA(0, 0), a2, voffA);
;             PG8_BAR; PG8_WAIT_L(0); PG8_MMA(1, 0, At, B0); PG8_BAR; PG8_SCHED;
.LBB0_2800:
	s_ashr_i32 s17, s16, 31
	s_lshl_b64 s[0:1], s[16:17], 19
	v_cmp_lt_i64_e32 vcc, s[18:19], v[184:185]
	s_add_u32 s18, s27, s0
	s_addc_u32 s19, s28, s1
	s_and_b64 s[0:1], vcc, exec
	s_cselect_b32 s17, s19, s7
	s_cselect_b32 s49, s18, s6
	s_ashr_i32 s15, s14, 31
	s_lshl_b64 s[0:1], s[14:15], 19
	s_add_u32 s20, s29, s0
	s_addc_u32 s21, s30, s1
	s_and_b64 s[0:1], vcc, exec
	s_cselect_b32 s15, s21, s23
	s_cselect_b32 s50, s20, s22
	s_add_u32 s6, s6, 0x40080
	s_addc_u32 s7, s7, 0
	s_add_u32 s51, s22, 0x100
	s_addc_u32 s52, s23, 0
	s_mov_b32 s54, -2
	v_cmp_lt_u32_e32 vcc, 0xff, v228
	s_cbranch_vccnz .Lsp_skip_2
	s_setprio 1
.Lsp_skip_2:
	s_add_u32 s0, s6, 0xfffc0080
	s_addc_u32 s1, s7, -1
	s_add_i32 s55, 0, 0x10000
	v_add_u32_e32 v130, s55, v243
	ds_read_b128 v[34:37], v130
	ds_read_b128 v[38:41], v130 offset:1024
	ds_read_b128 v[122:125], v130 offset:2048
	ds_read_b128 v[130:133], v130 offset:3072
	s_cmp_eq_u32 s54, 12
	s_cselect_b32 s25, s17, s1
	s_cselect_b32 s24, s49, s0
	s_cselect_b32 s23, s15, s52
	s_cselect_b32 s22, s50, s51
	v_lshl_add_u64 v[186:187], s[6:7], 0, v[196:197]
	s_add_i32 m0, s34, 0xc000
	ds_read_b128 v[146:149], v245
	ds_read_b128 v[150:153], v245 offset:1024
	ds_read_b128 v[154:157], v245 offset:2048
	ds_read_b128 v[158:161], v245 offset:3072
	ds_read_b128 v[162:165], v245 offset:4096
	ds_read_b128 v[166:169], v245 offset:5120
	ds_read_b128 v[170:173], v245 offset:6144
	ds_read_b128 v[174:177], v245 offset:7168
	global_load_lds_dwordx4 v[186:187], off
	s_add_i32 m0, s34, 0xe000
	v_lshl_add_u64 v[186:187], s[6:7], 0, v[198:199]
	global_load_lds_dwordx4 v[186:187], off
	s_waitcnt lgkmcnt(8)
	s_barrier
	s_waitcnt lgkmcnt(0)
	v_mfma_f32_16x16x32_bf16 v[142:145], v[34:37], v[146:149], 0
	v_mfma_f32_16x16x32_bf16 v[138:141], v[122:125], v[146:149], 0
	v_mfma_f32_16x16x32_bf16 v[134:137], v[34:37], v[154:157], 0
	v_mfma_f32_16x16x32_bf16 v[126:129], v[122:125], v[154:157], 0
	v_mfma_f32_16x16x32_bf16 v[118:121], v[34:37], v[162:165], 0
	v_mfma_f32_16x16x32_bf16 v[114:117], v[122:125], v[162:165], 0
	v_mfma_f32_16x16x32_bf16 v[110:113], v[34:37], v[170:173], 0
	v_mfma_f32_16x16x32_bf16 v[106:109], v[122:125], v[170:173], 0
	v_mfma_f32_16x16x32_bf16 v[142:145], v[38:41], v[150:153], v[142:145]
	v_mfma_f32_16x16x32_bf16 v[138:141], v[130:133], v[150:153], v[138:141]
	v_mfma_f32_16x16x32_bf16 v[134:137], v[38:41], v[158:161], v[134:137]
	v_mfma_f32_16x16x32_bf16 v[126:129], v[130:133], v[158:161], v[126:129]
	v_mfma_f32_16x16x32_bf16 v[118:121], v[38:41], v[166:169], v[118:121]
	v_mfma_f32_16x16x32_bf16 v[114:117], v[130:133], v[166:169], v[114:117]
	v_mfma_f32_16x16x32_bf16 v[110:113], v[38:41], v[174:177], v[110:113]
	v_mfma_f32_16x16x32_bf16 v[106:109], v[130:133], v[174:177], v[106:109]
	s_barrier
	s_add_i32 s56, 0, 0x14000
	v_add_u32_e32 v186, s56, v243
	s_add_i32 s0, s55, s31
	ds_read_b128 v[200:203], v186
	ds_read_b128 v[204:207], v186 offset:1024
	ds_read_b128 v[208:211], v186 offset:2048
	ds_read_b128 v[212:215], v186 offset:3072
	v_lshl_add_u64 v[186:187], s[22:23], 0, v[4:5]
	s_mov_b32 m0, s0
	v_lshl_add_u64 v[216:217], s[22:23], 0, v[190:191]
	global_load_lds_dwordx4 v[186:187], off
	s_add_i32 m0, s0, 0x2000
	s_nop 0
	global_load_lds_dwordx4 v[216:217], off
	s_barrier
	s_waitcnt lgkmcnt(0)
	v_mfma_f32_16x16x32_bf16 v[70:73], v[200:203], v[146:149], 0
	v_mfma_f32_16x16x32_bf16 v[66:69], v[208:211], v[146:149], 0
	v_mfma_f32_16x16x32_bf16 v[62:65], v[200:203], v[154:157], 0
	v_mfma_f32_16x16x32_bf16 v[58:61], v[208:211], v[154:157], 0
	v_mfma_f32_16x16x32_bf16 v[54:57], v[200:203], v[162:165], 0
	v_mfma_f32_16x16x32_bf16 v[50:53], v[208:211], v[162:165], 0
	v_mfma_f32_16x16x32_bf16 v[46:49], v[200:203], v[170:173], 0
	v_mfma_f32_16x16x32_bf16 v[42:45], v[208:211], v[170:173], 0
	v_mfma_f32_16x16x32_bf16 v[70:73], v[204:207], v[150:153], v[70:73]
	v_mfma_f32_16x16x32_bf16 v[66:69], v[212:215], v[150:153], v[66:69]
	v_mfma_f32_16x16x32_bf16 v[62:65], v[204:207], v[158:161], v[62:65]
	v_mfma_f32_16x16x32_bf16 v[58:61], v[212:215], v[158:161], v[58:61]
	v_mfma_f32_16x16x32_bf16 v[54:57], v[204:207], v[166:169], v[54:57]
	v_mfma_f32_16x16x32_bf16 v[50:53], v[212:215], v[166:169], v[50:53]
	v_mfma_f32_16x16x32_bf16 v[46:49], v[204:207], v[174:177], v[46:49]
	v_mfma_f32_16x16x32_bf16 v[42:45], v[212:215], v[174:177], v[42:45]
	s_mov_b32 m0, s34
	v_lshl_add_u64 v[218:219], s[24:25], 0, v[194:195]
	s_barrier
	ds_read_b128 v[146:149], v245 offset:16384
	ds_read_b128 v[150:153], v245 offset:17408
	ds_read_b128 v[154:157], v245 offset:18432
	ds_read_b128 v[158:161], v245 offset:19456
	ds_read_b128 v[162:165], v245 offset:20480
	ds_read_b128 v[166:169], v245 offset:21504
	ds_read_b128 v[170:173], v245 offset:22528
	ds_read_b128 v[174:177], v245 offset:23552
	global_load_lds_dwordx4 v[218:219], off
	s_mov_b32 m0, s35
	v_lshl_add_u64 v[220:221], s[24:25], 0, v[192:193]
	global_load_lds_dwordx4 v[220:221], off
	s_barrier
	s_waitcnt lgkmcnt(0)
	v_mfma_f32_16x16x32_bf16 v[102:105], v[34:37], v[146:149], 0
	v_mfma_f32_16x16x32_bf16 v[98:101], v[122:125], v[146:149], 0
	v_mfma_f32_16x16x32_bf16 v[94:97], v[34:37], v[154:157], 0
	v_mfma_f32_16x16x32_bf16 v[90:93], v[122:125], v[154:157], 0
	v_mfma_f32_16x16x32_bf16 v[86:89], v[34:37], v[162:165], 0
	v_mfma_f32_16x16x32_bf16 v[82:85], v[122:125], v[162:165], 0
	v_mfma_f32_16x16x32_bf16 v[34:37], v[34:37], v[170:173], 0
	v_mfma_f32_16x16x32_bf16 v[102:105], v[38:41], v[150:153], v[102:105]
	v_mfma_f32_16x16x32_bf16 v[98:101], v[130:133], v[150:153], v[98:101]
	v_mfma_f32_16x16x32_bf16 v[94:97], v[38:41], v[158:161], v[94:97]
	v_mfma_f32_16x16x32_bf16 v[90:93], v[130:133], v[158:161], v[90:93]
	v_mfma_f32_16x16x32_bf16 v[86:89], v[38:41], v[166:169], v[86:89]
	v_mfma_f32_16x16x32_bf16 v[82:85], v[130:133], v[166:169], v[82:85]
	v_mfma_f32_16x16x32_bf16 v[34:37], v[38:41], v[174:177], v[34:37]
	v_mfma_f32_16x16x32_bf16 v[38:41], v[122:125], v[170:173], 0
	v_mfma_f32_16x16x32_bf16 v[38:41], v[130:133], v[174:177], v[38:41]
	s_barrier
; #define PG8_STAGE(bufoff, gbase, voff) do { _Pragma("unroll") for (int _i = 0; _i < 2; ++_i) \
;         __builtin_amdgcn_global_load_lds((const unsigned*)((const char*)(gbase) + (voff)[_i]), (LAS unsigned*)(lds + (bufoff) + ldsw + _i * 8192), 16, 0, 0); } while (0)
; #define PG8_LDA(dst, b, h) do { _Pragma("unroll") for (int m = 0; m < 4; ++m) _Pragma("unroll") for (int k = 0; k < 2; ++k) dst[m][k] = *(const LAS bf16x8*)(lds + PG8_SA(b, h) + aoff + m * 2048 + k * 1024); } while (0)
; #define PG8_LDB(dst, b, h) do { _Pragma("unroll") for (int n = 0; n < 2; ++n) _Pragma("unroll") for (int k = 0; k < 2; ++k) dst[n][k] = *(const LAS bf16x8*)(lds + PG8_SB(b, h) + boff + n * 2048 + k * 1024); } while (0)
; #define PG8_MMA(ai, bj, At, Bt) do { __builtin_amdgcn_s_setprio(1); _Pragma("unroll") for (int m = 0; m < 4; ++m) _Pragma("unroll") for (int n = 0; n < 2; ++n) _Pragma("unroll") for (int k = 0; k < 2; ++k) \
;         acc[ai][bj][m][n] = __builtin_amdgcn_mfma_f32_16x16x32_bf16(Bt[n][k], At[m][k], acc[ai][bj][m][n], 0, 0, 0); __builtin_amdgcn_s_setprio(0); } while (0)
; #define PG8_WAIT_V(n) asm volatile("s_waitcnt vmcnt(" #n ")" ::: "memory")
; #define PG8_WAIT_L(n) asm volatile("s_waitcnt lgkmcnt(" #n ")" ::: "memory")
; #define PG8_BAR __builtin_amdgcn_s_barrier()
; #define PG8_SCHED __builtin_amdgcn_sched_barrier(0)
; template <class Epi>
; __device__ __forceinline__ void gemm_phase(LAS unsigned char* lds, const Gemm g, const StaticOrder& S, const Epi& E) {
;     ...
;             PG8_STAGE(PG8_SB(0, 1), b2 + hstep, voffB);
;             PG8_WAIT_V(6); PG8_BAR; PG8_MMA(1, 1, At, B1); PG8_BAR;
;             PG8_LDB(B0, 1, 0); PG8_SCHED; PG8_LDA(At, 1, 0); PG8_STAGE(PG8_SA(0, 1), a2 + hstep, voffA);
;             PG8_WAIT_L(8); PG8_BAR; PG8_WAIT_L(0); PG8_MMA(0, 0, At, B0); PG8_BAR; PG8_SCHED;
;             PG8_LDB(B1, 1, 1); PG8_STAGE(PG8_SB(1, 0), b3, voffB);
;             PG8_BAR; PG8_WAIT_L(0); PG8_MMA(0, 1, At, B1); PG8_BAR;
	s_add_u32 s0, s22, 0x40000
	s_addc_u32 s1, s23, 0
	s_add_i32 s55, s56, s31
	s_mov_b32 m0, s55
	v_lshl_add_u64 v[74:75], s[0:1], 0, v[4:5]
	global_load_lds_dwordx4 v[74:75], off
	s_add_i32 m0, s55, 0x2000
	v_lshl_add_u64 v[74:75], s[0:1], 0, v[190:191]
	global_load_lds_dwordx4 v[74:75], off
	s_waitcnt vmcnt(6)
	s_barrier
	v_mfma_f32_16x16x32_bf16 v[30:33], v[200:203], v[146:149], 0
	v_mfma_f32_16x16x32_bf16 v[26:29], v[208:211], v[146:149], 0
	v_mfma_f32_16x16x32_bf16 v[22:25], v[200:203], v[154:157], 0
	v_mfma_f32_16x16x32_bf16 v[18:21], v[208:211], v[154:157], 0
	v_mfma_f32_16x16x32_bf16 v[14:17], v[200:203], v[162:165], 0
	v_mfma_f32_16x16x32_bf16 v[10:13], v[208:211], v[162:165], 0
	v_mfma_f32_16x16x32_bf16 v[6:9], v[200:203], v[170:173], 0
	v_mfma_f32_16x16x32_bf16 v[0:3], v[208:211], v[170:173], 0
	v_mfma_f32_16x16x32_bf16 v[30:33], v[204:207], v[150:153], v[30:33]
	v_mfma_f32_16x16x32_bf16 v[26:29], v[212:215], v[150:153], v[26:29]
	v_mfma_f32_16x16x32_bf16 v[22:25], v[204:207], v[158:161], v[22:25]
	v_mfma_f32_16x16x32_bf16 v[18:21], v[212:215], v[158:161], v[18:21]
	v_mfma_f32_16x16x32_bf16 v[14:17], v[204:207], v[166:169], v[14:17]
	v_mfma_f32_16x16x32_bf16 v[10:13], v[212:215], v[166:169], v[10:13]
	v_mfma_f32_16x16x32_bf16 v[6:9], v[204:207], v[174:177], v[6:9]
	v_mfma_f32_16x16x32_bf16 v[0:3], v[212:215], v[174:177], v[0:3]
	s_add_i32 s55, 0, 0x18000
	v_add_u32_e32 v130, s55, v243
	s_barrier
	ds_read_b128 v[74:77], v130
	ds_read_b128 v[78:81], v130 offset:1024
	ds_read_b128 v[122:125], v130 offset:2048
	ds_read_b128 v[130:133], v130 offset:3072
	s_add_u32 s0, s24, 0x40000
	s_addc_u32 s1, s25, 0
	s_mov_b32 m0, s36
	v_lshl_add_u64 v[200:201], s[0:1], 0, v[194:195]
	ds_read_b128 v[146:149], v245 offset:32768
	ds_read_b128 v[150:153], v245 offset:33792
	ds_read_b128 v[154:157], v245 offset:34816
	ds_read_b128 v[158:161], v245 offset:35840
	ds_read_b128 v[162:165], v245 offset:36864
	ds_read_b128 v[166:169], v245 offset:37888
	ds_read_b128 v[170:173], v245 offset:38912
	ds_read_b128 v[174:177], v245 offset:39936
	global_load_lds_dwordx4 v[200:201], off
	s_mov_b32 m0, s37
	v_lshl_add_u64 v[200:201], s[0:1], 0, v[192:193]
	global_load_lds_dwordx4 v[200:201], off
	s_waitcnt lgkmcnt(8)
	s_barrier
	s_waitcnt lgkmcnt(0)
	v_mfma_f32_16x16x32_bf16 v[142:145], v[74:77], v[146:149], v[142:145]
	v_mfma_f32_16x16x32_bf16 v[138:141], v[122:125], v[146:149], v[138:141]
	v_mfma_f32_16x16x32_bf16 v[134:137], v[74:77], v[154:157], v[134:137]
	v_mfma_f32_16x16x32_bf16 v[126:129], v[122:125], v[154:157], v[126:129]
	v_mfma_f32_16x16x32_bf16 v[118:121], v[74:77], v[162:165], v[118:121]
	v_mfma_f32_16x16x32_bf16 v[114:117], v[122:125], v[162:165], v[114:117]
	v_mfma_f32_16x16x32_bf16 v[110:113], v[74:77], v[170:173], v[110:113]
	v_mfma_f32_16x16x32_bf16 v[106:109], v[122:125], v[170:173], v[106:109]
	v_mfma_f32_16x16x32_bf16 v[142:145], v[78:81], v[150:153], v[142:145]
	v_mfma_f32_16x16x32_bf16 v[138:141], v[130:133], v[150:153], v[138:141]
	v_mfma_f32_16x16x32_bf16 v[134:137], v[78:81], v[158:161], v[134:137]
	v_mfma_f32_16x16x32_bf16 v[126:129], v[130:133], v[158:161], v[126:129]
	v_mfma_f32_16x16x32_bf16 v[118:121], v[78:81], v[166:169], v[118:121]
	v_mfma_f32_16x16x32_bf16 v[114:117], v[130:133], v[166:169], v[114:117]
	v_mfma_f32_16x16x32_bf16 v[110:113], v[78:81], v[174:177], v[110:113]
	v_mfma_f32_16x16x32_bf16 v[106:109], v[130:133], v[174:177], v[106:109]
	s_barrier
	s_add_i32 s24, 0, 0x1c000
	s_add_i32 s0, s55, s31
	v_add_u32_e32 v212, s24, v243
	v_lshl_add_u64 v[186:187], v[186:187], 0, s[86:87]
	s_mov_b32 m0, s0
	ds_read_b128 v[200:203], v212
	ds_read_b128 v[204:207], v212 offset:1024
	ds_read_b128 v[208:211], v212 offset:2048
	ds_read_b128 v[212:215], v212 offset:3072
	global_load_lds_dwordx4 v[186:187], off
	s_add_i32 m0, s0, 0x2000
	v_lshl_add_u64 v[186:187], v[216:217], 0, s[86:87]
	global_load_lds_dwordx4 v[186:187], off
	s_barrier
; #define PG8_STAGE(bufoff, gbase, voff) do { _Pragma("unroll") for (int _i = 0; _i < 2; ++_i) \
;         __builtin_amdgcn_global_load_lds((const unsigned*)((const char*)(gbase) + (voff)[_i]), (LAS unsigned*)(lds + (bufoff) + ldsw + _i * 8192), 16, 0, 0); } while (0)
; #define PG8_LDA(dst, b, h) do { _Pragma("unroll") for (int m = 0; m < 4; ++m) _Pragma("unroll") for (int k = 0; k < 2; ++k) dst[m][k] = *(const LAS bf16x8*)(lds + PG8_SA(b, h) + aoff + m * 2048 + k * 1024); } while (0)
; #define PG8_LDB(dst, b, h) do { _Pragma("unroll") for (int n = 0; n < 2; ++n) _Pragma("unroll") for (int k = 0; k < 2; ++k) dst[n][k] = *(const LAS bf16x8*)(lds + PG8_SB(b, h) + boff + n * 2048 + k * 1024); } while (0)
; #define PG8_MMA(ai, bj, At, Bt) do { __builtin_amdgcn_s_setprio(1); _Pragma("unroll") for (int m = 0; m < 4; ++m) _Pragma("unroll") for (int n = 0; n < 2; ++n) _Pragma("unroll") for (int k = 0; k < 2; ++k) \
;         acc[ai][bj][m][n] = __builtin_amdgcn_mfma_f32_16x16x32_bf16(Bt[n][k], At[m][k], acc[ai][bj][m][n], 0, 0, 0); __builtin_amdgcn_s_setprio(0); } while (0)
; #define PG8_WAIT_V(n) asm volatile("s_waitcnt vmcnt(" #n ")" ::: "memory")
; #define PG8_WAIT_L(n) asm volatile("s_waitcnt lgkmcnt(" #n ")" ::: "memory")
; #define PG8_BAR __builtin_amdgcn_s_barrier()
; #define PG8_SCHED __builtin_amdgcn_sched_barrier(0)
; template <class Epi>
; __device__ __forceinline__ void gemm_phase(LAS unsigned char* lds, const Gemm g, const StaticOrder& S, const Epi& E) {
;     ...
;             PG8_LDB(B1, 1, 1); PG8_STAGE(PG8_SB(1, 0), b3, voffB);
;             PG8_BAR; PG8_WAIT_L(0); PG8_MMA(0, 1, At, B1); PG8_BAR;
;             PG8_LDA(At, 1, 1); PG8_STAGE(PG8_SA(1, 0), a3, voffA);
;             PG8_BAR; PG8_WAIT_L(0); PG8_MMA(1, 0, At, B0); PG8_BAR; PG8_SCHED;
;             PG8_STAGE(PG8_SB(1, 1), b3 + hstep, voffB);
;             PG8_WAIT_V(6); PG8_BAR; PG8_MMA(1, 1, At, B1); PG8_BAR;
	s_waitcnt lgkmcnt(0)
	v_mfma_f32_16x16x32_bf16 v[70:73], v[200:203], v[146:149], v[70:73]
	v_mfma_f32_16x16x32_bf16 v[66:69], v[208:211], v[146:149], v[66:69]
	v_mfma_f32_16x16x32_bf16 v[62:65], v[200:203], v[154:157], v[62:65]
	v_mfma_f32_16x16x32_bf16 v[58:61], v[208:211], v[154:157], v[58:61]
	v_mfma_f32_16x16x32_bf16 v[54:57], v[200:203], v[162:165], v[54:57]
	v_mfma_f32_16x16x32_bf16 v[50:53], v[208:211], v[162:165], v[50:53]
	v_mfma_f32_16x16x32_bf16 v[46:49], v[200:203], v[170:173], v[46:49]
	v_mfma_f32_16x16x32_bf16 v[42:45], v[208:211], v[170:173], v[42:45]
	v_mfma_f32_16x16x32_bf16 v[70:73], v[204:207], v[150:153], v[70:73]
	v_mfma_f32_16x16x32_bf16 v[66:69], v[212:215], v[150:153], v[66:69]
	v_mfma_f32_16x16x32_bf16 v[62:65], v[204:207], v[158:161], v[62:65]
	v_mfma_f32_16x16x32_bf16 v[58:61], v[212:215], v[158:161], v[58:61]
	v_mfma_f32_16x16x32_bf16 v[54:57], v[204:207], v[166:169], v[54:57]
	v_mfma_f32_16x16x32_bf16 v[50:53], v[212:215], v[166:169], v[50:53]
	v_mfma_f32_16x16x32_bf16 v[46:49], v[204:207], v[174:177], v[46:49]
	v_mfma_f32_16x16x32_bf16 v[42:45], v[212:215], v[174:177], v[42:45]
	s_mov_b32 m0, s40
	v_lshl_add_u64 v[186:187], v[218:219], 0, s[86:87]
	s_barrier
	ds_read_b128 v[146:149], v245 offset:49152
	ds_read_b128 v[150:153], v245 offset:50176
	ds_read_b128 v[154:157], v245 offset:51200
	ds_read_b128 v[158:161], v245 offset:52224
	ds_read_b128 v[162:165], v245 offset:53248
	ds_read_b128 v[166:169], v245 offset:54272
	ds_read_b128 v[170:173], v245 offset:55296
	ds_read_b128 v[174:177], v245 offset:56320
	global_load_lds_dwordx4 v[186:187], off
	s_mov_b32 m0, s41
	v_lshl_add_u64 v[186:187], v[220:221], 0, s[86:87]
	global_load_lds_dwordx4 v[186:187], off
	s_barrier
	s_waitcnt lgkmcnt(0)
	v_mfma_f32_16x16x32_bf16 v[102:105], v[74:77], v[146:149], v[102:105]
	v_mfma_f32_16x16x32_bf16 v[94:97], v[74:77], v[154:157], v[94:97]
	v_mfma_f32_16x16x32_bf16 v[86:89], v[74:77], v[162:165], v[86:89]
	v_mfma_f32_16x16x32_bf16 v[34:37], v[74:77], v[170:173], v[34:37]
	v_mfma_f32_16x16x32_bf16 v[102:105], v[78:81], v[150:153], v[102:105]
	v_mfma_f32_16x16x32_bf16 v[98:101], v[122:125], v[146:149], v[98:101]
	v_mfma_f32_16x16x32_bf16 v[94:97], v[78:81], v[158:161], v[94:97]
	v_mfma_f32_16x16x32_bf16 v[90:93], v[122:125], v[154:157], v[90:93]
	v_mfma_f32_16x16x32_bf16 v[86:89], v[78:81], v[166:169], v[86:89]
	v_mfma_f32_16x16x32_bf16 v[82:85], v[122:125], v[162:165], v[82:85]
	v_mfma_f32_16x16x32_bf16 v[78:81], v[78:81], v[174:177], v[34:37]
	v_mfma_f32_16x16x32_bf16 v[34:37], v[122:125], v[170:173], v[38:41]
	v_mfma_f32_16x16x32_bf16 v[98:101], v[130:133], v[150:153], v[98:101]
	v_mfma_f32_16x16x32_bf16 v[90:93], v[130:133], v[158:161], v[90:93]
	v_mfma_f32_16x16x32_bf16 v[82:85], v[130:133], v[166:169], v[82:85]
	v_mfma_f32_16x16x32_bf16 v[74:77], v[130:133], v[174:177], v[34:37]
	s_barrier
	s_add_u32 s0, s22, 0x40080
	s_addc_u32 s1, s23, 0
	s_add_i32 s22, s24, s31
	s_mov_b32 m0, s22
	v_lshl_add_u64 v[34:35], s[0:1], 0, v[4:5]
	global_load_lds_dwordx4 v[34:35], off
	s_add_i32 m0, s22, 0x2000
	v_lshl_add_u64 v[34:35], s[0:1], 0, v[190:191]
	global_load_lds_dwordx4 v[34:35], off
	s_waitcnt vmcnt(6)
	s_barrier
	v_mfma_f32_16x16x32_bf16 v[30:33], v[200:203], v[146:149], v[30:33]
	v_mfma_f32_16x16x32_bf16 v[26:29], v[208:211], v[146:149], v[26:29]
	v_mfma_f32_16x16x32_bf16 v[22:25], v[200:203], v[154:157], v[22:25]
	v_mfma_f32_16x16x32_bf16 v[18:21], v[208:211], v[154:157], v[18:21]
	v_mfma_f32_16x16x32_bf16 v[14:17], v[200:203], v[162:165], v[14:17]
	v_mfma_f32_16x16x32_bf16 v[10:13], v[208:211], v[162:165], v[10:13]
	v_mfma_f32_16x16x32_bf16 v[6:9], v[200:203], v[170:173], v[6:9]
	v_mfma_f32_16x16x32_bf16 v[0:3], v[208:211], v[170:173], v[0:3]
	v_mfma_f32_16x16x32_bf16 v[30:33], v[204:207], v[150:153], v[30:33]
	v_mfma_f32_16x16x32_bf16 v[26:29], v[212:215], v[150:153], v[26:29]
	v_mfma_f32_16x16x32_bf16 v[22:25], v[204:207], v[158:161], v[22:25]
	v_mfma_f32_16x16x32_bf16 v[18:21], v[212:215], v[158:161], v[18:21]
	v_mfma_f32_16x16x32_bf16 v[14:17], v[204:207], v[166:169], v[14:17]
	v_mfma_f32_16x16x32_bf16 v[10:13], v[212:215], v[166:169], v[10:13]
	v_mfma_f32_16x16x32_bf16 v[6:9], v[204:207], v[174:177], v[6:9]
	v_mfma_f32_16x16x32_bf16 v[0:3], v[212:215], v[174:177], v[0:3]
	s_add_i32 s54, s54, 2
	s_add_u32 s6, s6, 0x100
	s_addc_u32 s7, s7, 0
	s_add_u32 s51, s51, 0x100
	s_addc_u32 s52, s52, 0
	s_cmp_gt_u32 s54, 13
	s_barrier
	s_cbranch_scc1 .Lpeel_exit_2

;     __device__ __forceinline__ void operator()(const f32x4 (&acc)[2][2][4][2], const Unit& u, int wr, int wc, int fr, int fq) const {
;         const int row0 = u.pm * 256 + wr * 64 + fr, col0 = u.pn * 256 + wc * 32 + 8 * fq;
;         f32x4 ra, rb; load_rstd(ss, row0, ra, rb);
;         const float* swp = sw + (size_t)(u.pm >> 3) * 3072 + col0;
;         const f32x4 swv[4] = {*(const f32x4*)(swp), *(const f32x4*)(swp + 4), *(const f32x4*)(swp + 128), *(const f32x4*)(swp + 132)};
; #pragma unroll
;         for (int bj = 0; bj < 2; ++bj) {
;             const f32x4 s0 = swv[2 * bj], s1 = swv[2 * bj + 1];
; #pragma unroll
;             for (int ai = 0; ai < 2; ++ai) {
;                 uint4 yld[4], zld[4];
; #pragma unroll
;                 for (int i = 0; i < 4; ++i) { const size_t off = (size_t)(row0 + ai * 128 + i * 16) * DM + col0 + bj * 128;
;                     yld[i] = *(const uint4*)(Y + off); zld[i] = first ? make_uint4(0u, 0u, 0u, 0u) : *(const uint4*)(Z + off); }
.Lpeel_exit_2:
	s_setprio 0
	v_lshl_add_u32 v218, s43, 8, v242
	v_ashrrev_i32_e32 v219, 31, v218
	v_lshl_add_u64 v[34:35], v[218:219], 2, s[12:13]
	s_ashr_i32 s0, s43, 3
	global_load_dword v206, v[34:35], off
	global_load_dword v204, v[34:35], off offset:64
	global_load_dword v187, v[34:35], off offset:128
	global_load_dword v186, v[34:35], off offset:192
	global_load_dword v246, v[34:35], off offset:512
	global_load_dword v209, v[34:35], off offset:576
	global_load_dword v207, v[34:35], off offset:640
	global_load_dword v205, v[34:35], off offset:704
	s_mul_hi_i32 s1, s0, 0x3000
	s_mulk_i32 s0, 0x3000
	v_lshl_or_b32 v200, s48, 8, v244
	s_add_u32 s0, s38, s0
	s_addc_u32 s1, s39, s1
	v_ashrrev_i32_e32 v201, 31, v200
	v_lshl_add_u64 v[38:39], v[200:201], 2, s[0:1]
	v_lshlrev_b64 v[210:211], 10, v[218:219]
	global_load_dwordx4 v[122:125], v[38:39], off offset:16
	global_load_dwordx4 v[130:133], v[38:39], off
	global_load_dwordx4 v[34:37], v[38:39], off offset:528
	s_nop 0
	global_load_dwordx4 v[38:41], v[38:39], off offset:512
	v_lshl_add_u64 v[146:147], v[210:211], 0, v[200:201]
	v_lshl_add_u64 v[148:149], v[146:147], 1, s[10:11]
	global_load_dwordx4 v[174:177], v[148:149], off
	v_cndmask_b32_e64 v148, 0, 1, s[88:89]
	v_mov_b32_e32 v162, 0
	v_cmp_ne_u32_e64 s[6:7], 1, v148
	s_andn2_b64 vcc, exec, s[88:89]
	v_mov_b32_e32 v170, 0
	v_mov_b32_e32 v171, 0
	v_mov_b32_e32 v172, 0
	v_mov_b32_e32 v173, 0
	s_cbranch_vccnz .LBB0_2804
	v_lshl_add_u64 v[146:147], v[146:147], 1, s[8:9]
	global_load_dwordx4 v[170:173], v[146:147], off

; #define PG8_STAGE(bufoff, gbase, voff) do { _Pragma("unroll") for (int _i = 0; _i < 2; ++_i) \
;         __builtin_amdgcn_global_load_lds((const unsigned*)((const char*)(gbase) + (voff)[_i]), (LAS unsigned*)(lds + (bufoff) + ldsw + _i * 8192), 16, 0, 0); } while (0)
; #define PG8_LDA(dst, b, h) do { _Pragma("unroll") for (int m = 0; m < 4; ++m) _Pragma("unroll") for (int k = 0; k < 2; ++k) dst[m][k] = *(const LAS bf16x8*)(lds + PG8_SA(b, h) + aoff + m * 2048 + k * 1024); } while (0)
; #define PG8_LDB(dst, b, h) do { _Pragma("unroll") for (int n = 0; n < 2; ++n) _Pragma("unroll") for (int k = 0; k < 2; ++k) dst[n][k] = *(const LAS bf16x8*)(lds + PG8_SB(b, h) + boff + n * 2048 + k * 1024); } while (0)
; #define PG8_WAIT_V(n) asm volatile("s_waitcnt vmcnt(" #n ")" ::: "memory")
; #define PG8_WAIT_L(n) asm volatile("s_waitcnt lgkmcnt(" #n ")" ::: "memory")
; #define PG8_BAR __builtin_amdgcn_s_barrier()
; #define PG8_SCHED __builtin_amdgcn_sched_barrier(0)
; template <class Epi>
; __device__ __forceinline__ void gemm_phase(LAS unsigned char* lds, const Gemm g, const StaticOrder& S, const Epi& E) {
;     ...
;         const bool has_next = S.next(ui + 1, nxt);
;         const char* nA = has_next ? (const char*)g.A + (size_t)nxt.pm * tstep : cA; const char* nB = has_next ? (const char*)g.Bt + (size_t)nxt.pn * tstep : cB;
;         for (int t = 0; t < nt; t += 2) {
;             const bool last = (t == nt - 2);
;             const char* a1 = cA + (size_t)(t + 1) * kstep;
;             const char* a2 = last ? nA : cA + (size_t)(t + 2) * kstep; const char* b2 = last ? nB : cB + (size_t)(t + 2) * kstep;
;             const char* a3 = a2 + kstep; const char* b3 = b2 + kstep;
;             PG8_LDB(B0, 0, 0); PG8_SCHED; PG8_LDA(At, 0, 0); PG8_STAGE(PG8_SA(1, 1), a1 + hstep, voffA);
;             PG8_WAIT_L(8); PG8_BAR; PG8_WAIT_L(0); PG8_MMA(0, 0, At, B0); PG8_BAR; PG8_SCHED;
;             PG8_LDB(B1, 0, 1); PG8_STAGE(PG8_SB(0, 0), b2, voffB);
;             PG8_BAR; PG8_WAIT_L(0); PG8_MMA(0, 1, At, B1); PG8_BAR;
;             PG8_LDA(At, 0, 1); PG8_STAGE(PG8_SA(0, 0), a2, voffA);
;             PG8_BAR; PG8_WAIT_L(0); PG8_MMA(1, 0, At, B0); PG8_BAR; PG8_SCHED;
;             PG8_STAGE(PG8_SB(0, 1), b2 + hstep, voffB);
;             PG8_WAIT_V(6); PG8_BAR; PG8_MMA(1, 1, At, B1); PG8_BAR;
.LBB0_2896:
	v_mov_b64_e32 v[0:1], 0x1600
	s_ashr_i32 s13, s12, 31
	v_cmp_lt_i64_e32 vcc, s[14:15], v[0:1]
	s_lshl_b64 s[14:15], s[12:13], 19
	s_add_u32 s14, s25, s14
	s_addc_u32 s15, s26, s15
	s_and_b64 s[16:17], vcc, exec
	s_cselect_b32 s13, s15, s19
	s_cselect_b32 s48, s14, s18
	s_ashr_i32 s11, s10, 31
	s_lshl_b64 s[16:17], s[10:11], 19
	s_add_u32 s16, s27, s16
	s_addc_u32 s17, s28, s17
	s_and_b64 s[22:23], vcc, exec
	s_cselect_b32 s11, s17, s21
	s_cselect_b32 s49, s16, s20
	s_add_u32 s18, s18, 0x40080
	s_addc_u32 s19, s19, 0
	s_add_u32 s50, s20, 0x100
	s_addc_u32 s51, s21, 0
	s_mov_b32 s52, -2
	v_cmp_lt_u32_e32 vcc, 0xff, v228
	s_cbranch_vccnz .Lsp_skip_1
	s_setprio 1
.Lsp_skip_1:
	s_add_u32 s0, s18, 0xfffc0080
	s_addc_u32 s1, s19, -1
	s_add_i32 s54, 0, 0x10000
	v_add_u32_e32 v78, s54, v161
	ds_read_b128 v[66:69], v78
	ds_read_b128 v[70:73], v78 offset:1024
	ds_read_b128 v[74:77], v78 offset:2048
	ds_read_b128 v[78:81], v78 offset:3072
	s_cmp_eq_u32 s52, 12
	s_cselect_b32 s23, s13, s1
	s_cselect_b32 s22, s48, s0
	s_cselect_b32 s21, s11, s51
	s_cselect_b32 s20, s49, s50
	v_lshl_add_u64 v[156:157], s[18:19], 0, v[152:153]
	s_add_i32 m0, s30, 0xc000
	ds_read_b128 v[168:171], v165
	ds_read_b128 v[172:175], v165 offset:1024
	ds_read_b128 v[190:193], v165 offset:2048
	ds_read_b128 v[194:197], v165 offset:3072
	ds_read_b128 v[198:201], v165 offset:4096
	ds_read_b128 v[202:205], v165 offset:5120
	ds_read_b128 v[206:209], v165 offset:6144
	ds_read_b128 v[210:213], v165 offset:7168
	global_load_lds_dwordx4 v[156:157], off
	s_add_i32 m0, s30, 0xe000
	v_lshl_add_u64 v[156:157], s[18:19], 0, v[154:155]
	global_load_lds_dwordx4 v[156:157], off
	s_waitcnt lgkmcnt(8)
	s_barrier
	s_waitcnt lgkmcnt(0)
	v_mfma_f32_16x16x32_bf16 v[142:145], v[66:69], v[168:171], 0
	v_mfma_f32_16x16x32_bf16 v[138:141], v[74:77], v[168:171], 0
	v_mfma_f32_16x16x32_bf16 v[126:129], v[66:69], v[190:193], 0
	v_mfma_f32_16x16x32_bf16 v[122:125], v[74:77], v[190:193], 0
	v_mfma_f32_16x16x32_bf16 v[110:113], v[66:69], v[198:201], 0
	v_mfma_f32_16x16x32_bf16 v[106:109], v[74:77], v[198:201], 0
	v_mfma_f32_16x16x32_bf16 v[94:97], v[66:69], v[206:209], 0
	v_mfma_f32_16x16x32_bf16 v[90:93], v[74:77], v[206:209], 0
	v_mfma_f32_16x16x32_bf16 v[142:145], v[70:73], v[172:175], v[142:145]
	v_mfma_f32_16x16x32_bf16 v[138:141], v[78:81], v[172:175], v[138:141]
	v_mfma_f32_16x16x32_bf16 v[126:129], v[70:73], v[194:197], v[126:129]
	v_mfma_f32_16x16x32_bf16 v[122:125], v[78:81], v[194:197], v[122:125]
	v_mfma_f32_16x16x32_bf16 v[110:113], v[70:73], v[202:205], v[110:113]
	v_mfma_f32_16x16x32_bf16 v[106:109], v[78:81], v[202:205], v[106:109]
	v_mfma_f32_16x16x32_bf16 v[94:97], v[70:73], v[210:213], v[94:97]
	v_mfma_f32_16x16x32_bf16 v[90:93], v[78:81], v[210:213], v[90:93]
	s_barrier
	s_add_i32 s0, 0, 0x14000
	v_add_u32_e32 v156, s0, v161
	s_add_i32 s1, s54, s29
	ds_read_b128 v[214:217], v156
	ds_read_b128 v[218:221], v156 offset:1024
	ds_read_b128 v[222:225], v156 offset:2048
	ds_read_b128 v[242:245], v156 offset:3072
	v_lshl_add_u64 v[156:157], s[20:21], 0, v[4:5]
	s_mov_b32 m0, s1
	v_lshl_add_u64 v[176:177], s[20:21], 0, v[146:147]
	global_load_lds_dwordx4 v[156:157], off
	s_add_i32 m0, s1, 0x2000
	s_nop 0
	global_load_lds_dwordx4 v[176:177], off
	s_barrier
	s_waitcnt lgkmcnt(0)
	v_mfma_f32_16x16x32_bf16 v[134:137], v[214:217], v[168:171], 0
	v_mfma_f32_16x16x32_bf16 v[130:133], v[222:225], v[168:171], 0
	v_mfma_f32_16x16x32_bf16 v[118:121], v[214:217], v[190:193], 0
	v_mfma_f32_16x16x32_bf16 v[114:117], v[222:225], v[190:193], 0
	v_mfma_f32_16x16x32_bf16 v[102:105], v[214:217], v[198:201], 0
	v_mfma_f32_16x16x32_bf16 v[98:101], v[222:225], v[198:201], 0
	v_mfma_f32_16x16x32_bf16 v[86:89], v[214:217], v[206:209], 0
	v_mfma_f32_16x16x32_bf16 v[82:85], v[222:225], v[206:209], 0
	v_mfma_f32_16x16x32_bf16 v[134:137], v[218:221], v[172:175], v[134:137]
	v_mfma_f32_16x16x32_bf16 v[130:133], v[242:245], v[172:175], v[130:133]
	v_mfma_f32_16x16x32_bf16 v[118:121], v[218:221], v[194:197], v[118:121]
	v_mfma_f32_16x16x32_bf16 v[114:117], v[242:245], v[194:197], v[114:117]
	v_mfma_f32_16x16x32_bf16 v[102:105], v[218:221], v[202:205], v[102:105]
	v_mfma_f32_16x16x32_bf16 v[98:101], v[242:245], v[202:205], v[98:101]
	v_mfma_f32_16x16x32_bf16 v[86:89], v[218:221], v[210:213], v[86:89]
	v_mfma_f32_16x16x32_bf16 v[82:85], v[242:245], v[210:213], v[82:85]
	s_mov_b32 m0, s30
	v_lshl_add_u64 v[186:187], s[22:23], 0, v[150:151]
	s_barrier
	ds_read_b128 v[168:171], v165 offset:16384
	ds_read_b128 v[172:175], v165 offset:17408
	ds_read_b128 v[190:193], v165 offset:18432
	ds_read_b128 v[194:197], v165 offset:19456
	ds_read_b128 v[198:201], v165 offset:20480
	ds_read_b128 v[202:205], v165 offset:21504
	ds_read_b128 v[206:209], v165 offset:22528
	ds_read_b128 v[210:213], v165 offset:23552
	global_load_lds_dwordx4 v[186:187], off
	s_mov_b32 m0, s31
	v_lshl_add_u64 v[226:227], s[22:23], 0, v[148:149]
	global_load_lds_dwordx4 v[226:227], off
	s_barrier
	s_waitcnt lgkmcnt(0)
	v_mfma_f32_16x16x32_bf16 v[62:65], v[66:69], v[168:171], 0
	v_mfma_f32_16x16x32_bf16 v[58:61], v[74:77], v[168:171], 0
	v_mfma_f32_16x16x32_bf16 v[46:49], v[66:69], v[190:193], 0
	v_mfma_f32_16x16x32_bf16 v[42:45], v[74:77], v[190:193], 0
	v_mfma_f32_16x16x32_bf16 v[30:33], v[66:69], v[198:201], 0
	v_mfma_f32_16x16x32_bf16 v[26:29], v[74:77], v[198:201], 0
	v_mfma_f32_16x16x32_bf16 v[14:17], v[66:69], v[206:209], 0
	v_mfma_f32_16x16x32_bf16 v[10:13], v[74:77], v[206:209], 0
	v_mfma_f32_16x16x32_bf16 v[62:65], v[70:73], v[172:175], v[62:65]
	v_mfma_f32_16x16x32_bf16 v[58:61], v[78:81], v[172:175], v[58:61]
	v_mfma_f32_16x16x32_bf16 v[46:49], v[70:73], v[194:197], v[46:49]
	v_mfma_f32_16x16x32_bf16 v[42:45], v[78:81], v[194:197], v[42:45]
	v_mfma_f32_16x16x32_bf16 v[30:33], v[70:73], v[202:205], v[30:33]
	v_mfma_f32_16x16x32_bf16 v[26:29], v[78:81], v[202:205], v[26:29]
	v_mfma_f32_16x16x32_bf16 v[14:17], v[70:73], v[210:213], v[14:17]
	v_mfma_f32_16x16x32_bf16 v[10:13], v[78:81], v[210:213], v[10:13]
	s_barrier
; #define PG8_STAGE(bufoff, gbase, voff) do { _Pragma("unroll") for (int _i = 0; _i < 2; ++_i) \
;         __builtin_amdgcn_global_load_lds((const unsigned*)((const char*)(gbase) + (voff)[_i]), (LAS unsigned*)(lds + (bufoff) + ldsw + _i * 8192), 16, 0, 0); } while (0)
; #define PG8_LDA(dst, b, h) do { _Pragma("unroll") for (int m = 0; m < 4; ++m) _Pragma("unroll") for (int k = 0; k < 2; ++k) dst[m][k] = *(const LAS bf16x8*)(lds + PG8_SA(b, h) + aoff + m * 2048 + k * 1024); } while (0)
; #define PG8_LDB(dst, b, h) do { _Pragma("unroll") for (int n = 0; n < 2; ++n) _Pragma("unroll") for (int k = 0; k < 2; ++k) dst[n][k] = *(const LAS bf16x8*)(lds + PG8_SB(b, h) + boff + n * 2048 + k * 1024); } while (0)
; #define PG8_MMA(ai, bj, At, Bt) do { __builtin_amdgcn_s_setprio(1); _Pragma("unroll") for (int m = 0; m < 4; ++m) _Pragma("unroll") for (int n = 0; n < 2; ++n) _Pragma("unroll") for (int k = 0; k < 2; ++k) \
;         acc[ai][bj][m][n] = __builtin_amdgcn_mfma_f32_16x16x32_bf16(Bt[n][k], At[m][k], acc[ai][bj][m][n], 0, 0, 0); __builtin_amdgcn_s_setprio(0); } while (0)
; #define PG8_WAIT_V(n) asm volatile("s_waitcnt vmcnt(" #n ")" ::: "memory")
; #define PG8_WAIT_L(n) asm volatile("s_waitcnt lgkmcnt(" #n ")" ::: "memory")
; #define PG8_BAR __builtin_amdgcn_s_barrier()
; #define PG8_SCHED __builtin_amdgcn_sched_barrier(0)
; template <class Epi>
; __device__ __forceinline__ void gemm_phase(LAS unsigned char* lds, const Gemm g, const StaticOrder& S, const Epi& E) {
;     ...
;             PG8_STAGE(PG8_SB(0, 1), b2 + hstep, voffB);
;             PG8_WAIT_V(6); PG8_BAR; PG8_MMA(1, 1, At, B1); PG8_BAR;
;             PG8_LDB(B0, 1, 0); PG8_SCHED; PG8_LDA(At, 1, 0); PG8_STAGE(PG8_SA(0, 1), a2 + hstep, voffA);
;             PG8_WAIT_L(8); PG8_BAR; PG8_WAIT_L(0); PG8_MMA(0, 0, At, B0); PG8_BAR; PG8_SCHED;
;             PG8_LDB(B1, 1, 1); PG8_STAGE(PG8_SB(1, 0), b3, voffB);
	s_add_u32 s54, s20, 0x40000
	s_addc_u32 s55, s21, 0
	s_add_i32 s0, s0, s29
	s_mov_b32 m0, s0
	v_lshl_add_u64 v[66:67], s[54:55], 0, v[4:5]
	global_load_lds_dwordx4 v[66:67], off
	s_add_i32 m0, s0, 0x2000
	v_lshl_add_u64 v[66:67], s[54:55], 0, v[146:147]
	global_load_lds_dwordx4 v[66:67], off
	s_waitcnt vmcnt(6)
	s_barrier
	v_mfma_f32_16x16x32_bf16 v[54:57], v[214:217], v[168:171], 0
	v_mfma_f32_16x16x32_bf16 v[50:53], v[222:225], v[168:171], 0
	v_mfma_f32_16x16x32_bf16 v[38:41], v[214:217], v[190:193], 0
	v_mfma_f32_16x16x32_bf16 v[34:37], v[222:225], v[190:193], 0
	v_mfma_f32_16x16x32_bf16 v[22:25], v[214:217], v[198:201], 0
	v_mfma_f32_16x16x32_bf16 v[18:21], v[222:225], v[198:201], 0
	v_mfma_f32_16x16x32_bf16 v[6:9], v[214:217], v[206:209], 0
	v_mfma_f32_16x16x32_bf16 v[0:3], v[222:225], v[206:209], 0
	v_mfma_f32_16x16x32_bf16 v[54:57], v[218:221], v[172:175], v[54:57]
	v_mfma_f32_16x16x32_bf16 v[50:53], v[242:245], v[172:175], v[50:53]
	v_mfma_f32_16x16x32_bf16 v[38:41], v[218:221], v[194:197], v[38:41]
	v_mfma_f32_16x16x32_bf16 v[34:37], v[242:245], v[194:197], v[34:37]
	v_mfma_f32_16x16x32_bf16 v[22:25], v[218:221], v[202:205], v[22:25]
	v_mfma_f32_16x16x32_bf16 v[18:21], v[242:245], v[202:205], v[18:21]
	v_mfma_f32_16x16x32_bf16 v[6:9], v[218:221], v[210:213], v[6:9]
	v_mfma_f32_16x16x32_bf16 v[0:3], v[242:245], v[210:213], v[0:3]
	s_add_i32 s0, 0, 0x18000
	v_add_u32_e32 v78, s0, v161
	s_barrier
	ds_read_b128 v[66:69], v78
	ds_read_b128 v[70:73], v78 offset:1024
	ds_read_b128 v[74:77], v78 offset:2048
	ds_read_b128 v[78:81], v78 offset:3072
	s_add_u32 s22, s22, 0x40000
	s_addc_u32 s23, s23, 0
	s_mov_b32 m0, s34
	v_lshl_add_u64 v[214:215], s[22:23], 0, v[150:151]
	ds_read_b128 v[168:171], v165 offset:32768
	ds_read_b128 v[172:175], v165 offset:33792
	ds_read_b128 v[190:193], v165 offset:34816
	ds_read_b128 v[194:197], v165 offset:35840
	ds_read_b128 v[198:201], v165 offset:36864
	ds_read_b128 v[202:205], v165 offset:37888
	ds_read_b128 v[206:209], v165 offset:38912
	ds_read_b128 v[210:213], v165 offset:39936
	global_load_lds_dwordx4 v[214:215], off
	s_mov_b32 m0, s35
	v_lshl_add_u64 v[214:215], s[22:23], 0, v[148:149]
	global_load_lds_dwordx4 v[214:215], off
	s_waitcnt lgkmcnt(8)
	s_barrier
	s_waitcnt lgkmcnt(0)
	v_mfma_f32_16x16x32_bf16 v[142:145], v[66:69], v[168:171], v[142:145]
	v_mfma_f32_16x16x32_bf16 v[138:141], v[74:77], v[168:171], v[138:141]
	v_mfma_f32_16x16x32_bf16 v[126:129], v[66:69], v[190:193], v[126:129]
	v_mfma_f32_16x16x32_bf16 v[122:125], v[74:77], v[190:193], v[122:125]
	v_mfma_f32_16x16x32_bf16 v[110:113], v[66:69], v[198:201], v[110:113]
	v_mfma_f32_16x16x32_bf16 v[106:109], v[74:77], v[198:201], v[106:109]
	v_mfma_f32_16x16x32_bf16 v[94:97], v[66:69], v[206:209], v[94:97]
	v_mfma_f32_16x16x32_bf16 v[90:93], v[74:77], v[206:209], v[90:93]
	v_mfma_f32_16x16x32_bf16 v[142:145], v[70:73], v[172:175], v[142:145]
	v_mfma_f32_16x16x32_bf16 v[138:141], v[78:81], v[172:175], v[138:141]
	v_mfma_f32_16x16x32_bf16 v[126:129], v[70:73], v[194:197], v[126:129]
	v_mfma_f32_16x16x32_bf16 v[122:125], v[78:81], v[194:197], v[122:125]
	v_mfma_f32_16x16x32_bf16 v[110:113], v[70:73], v[202:205], v[110:113]
	v_mfma_f32_16x16x32_bf16 v[106:109], v[78:81], v[202:205], v[106:109]
	v_mfma_f32_16x16x32_bf16 v[94:97], v[70:73], v[210:213], v[94:97]
	v_mfma_f32_16x16x32_bf16 v[90:93], v[78:81], v[210:213], v[90:93]
	s_barrier
	s_add_i32 s1, 0, 0x1c000
	s_add_i32 s0, s0, s29
	v_add_u32_e32 v158, s1, v161
	v_lshl_add_u64 v[156:157], v[156:157], 0, s[86:87]
	s_mov_b32 m0, s0
	ds_read_b128 v[214:217], v158
	ds_read_b128 v[218:221], v158 offset:1024
	ds_read_b128 v[222:225], v158 offset:2048
	ds_read_b128 v[242:245], v158 offset:3072
	global_load_lds_dwordx4 v[156:157], off
	s_add_i32 m0, s0, 0x2000
	v_lshl_add_u64 v[156:157], v[176:177], 0, s[86:87]
	global_load_lds_dwordx4 v[156:157], off
	s_barrier
; #define PG8_STAGE(bufoff, gbase, voff) do { _Pragma("unroll") for (int _i = 0; _i < 2; ++_i) \
;         __builtin_amdgcn_global_load_lds((const unsigned*)((const char*)(gbase) + (voff)[_i]), (LAS unsigned*)(lds + (bufoff) + ldsw + _i * 8192), 16, 0, 0); } while (0)
; #define PG8_LDA(dst, b, h) do { _Pragma("unroll") for (int m = 0; m < 4; ++m) _Pragma("unroll") for (int k = 0; k < 2; ++k) dst[m][k] = *(const LAS bf16x8*)(lds + PG8_SA(b, h) + aoff + m * 2048 + k * 1024); } while (0)
; #define PG8_LDB(dst, b, h) do { _Pragma("unroll") for (int n = 0; n < 2; ++n) _Pragma("unroll") for (int k = 0; k < 2; ++k) dst[n][k] = *(const LAS bf16x8*)(lds + PG8_SB(b, h) + boff + n * 2048 + k * 1024); } while (0)
; #define PG8_MMA(ai, bj, At, Bt) do { __builtin_amdgcn_s_setprio(1); _Pragma("unroll") for (int m = 0; m < 4; ++m) _Pragma("unroll") for (int n = 0; n < 2; ++n) _Pragma("unroll") for (int k = 0; k < 2; ++k) \
;         acc[ai][bj][m][n] = __builtin_amdgcn_mfma_f32_16x16x32_bf16(Bt[n][k], At[m][k], acc[ai][bj][m][n], 0, 0, 0); __builtin_amdgcn_s_setprio(0); } while (0)
; #define PG8_WAIT_V(n) asm volatile("s_waitcnt vmcnt(" #n ")" ::: "memory")
; #define PG8_WAIT_L(n) asm volatile("s_waitcnt lgkmcnt(" #n ")" ::: "memory")
; #define PG8_BAR __builtin_amdgcn_s_barrier()
; #define PG8_SCHED __builtin_amdgcn_sched_barrier(0)
; template <class Epi>
; __device__ __forceinline__ void gemm_phase(LAS unsigned char* lds, const Gemm g, const StaticOrder& S, const Epi& E) {
;     ...
;             PG8_LDB(B1, 1, 1); PG8_STAGE(PG8_SB(1, 0), b3, voffB);
;             PG8_BAR; PG8_WAIT_L(0); PG8_MMA(0, 1, At, B1); PG8_BAR;
;             PG8_LDA(At, 1, 1); PG8_STAGE(PG8_SA(1, 0), a3, voffA);
;             PG8_BAR; PG8_WAIT_L(0); PG8_MMA(1, 0, At, B0); PG8_BAR; PG8_SCHED;
;             PG8_STAGE(PG8_SB(1, 1), b3 + hstep, voffB);
;             PG8_WAIT_V(6); PG8_BAR; PG8_MMA(1, 1, At, B1); PG8_BAR;
	s_waitcnt lgkmcnt(0)
	v_mfma_f32_16x16x32_bf16 v[134:137], v[214:217], v[168:171], v[134:137]
	v_mfma_f32_16x16x32_bf16 v[130:133], v[222:225], v[168:171], v[130:133]
	v_mfma_f32_16x16x32_bf16 v[118:121], v[214:217], v[190:193], v[118:121]
	v_mfma_f32_16x16x32_bf16 v[114:117], v[222:225], v[190:193], v[114:117]
	v_mfma_f32_16x16x32_bf16 v[102:105], v[214:217], v[198:201], v[102:105]
	v_mfma_f32_16x16x32_bf16 v[98:101], v[222:225], v[198:201], v[98:101]
	v_mfma_f32_16x16x32_bf16 v[86:89], v[214:217], v[206:209], v[86:89]
	v_mfma_f32_16x16x32_bf16 v[82:85], v[222:225], v[206:209], v[82:85]
	v_mfma_f32_16x16x32_bf16 v[134:137], v[218:221], v[172:175], v[134:137]
	v_mfma_f32_16x16x32_bf16 v[130:133], v[242:245], v[172:175], v[130:133]
	v_mfma_f32_16x16x32_bf16 v[118:121], v[218:221], v[194:197], v[118:121]
	v_mfma_f32_16x16x32_bf16 v[114:117], v[242:245], v[194:197], v[114:117]
	v_mfma_f32_16x16x32_bf16 v[102:105], v[218:221], v[202:205], v[102:105]
	v_mfma_f32_16x16x32_bf16 v[98:101], v[242:245], v[202:205], v[98:101]
	v_mfma_f32_16x16x32_bf16 v[86:89], v[218:221], v[210:213], v[86:89]
	v_mfma_f32_16x16x32_bf16 v[82:85], v[242:245], v[210:213], v[82:85]
	s_mov_b32 m0, s38
	v_lshl_add_u64 v[156:157], v[186:187], 0, s[86:87]
	s_barrier
	ds_read_b128 v[168:171], v165 offset:49152
	ds_read_b128 v[172:175], v165 offset:50176
	ds_read_b128 v[190:193], v165 offset:51200
	ds_read_b128 v[194:197], v165 offset:52224
	ds_read_b128 v[198:201], v165 offset:53248
	ds_read_b128 v[202:205], v165 offset:54272
	ds_read_b128 v[206:209], v165 offset:55296
	ds_read_b128 v[210:213], v165 offset:56320
	global_load_lds_dwordx4 v[156:157], off
	s_mov_b32 m0, s39
	v_lshl_add_u64 v[156:157], v[226:227], 0, s[86:87]
	global_load_lds_dwordx4 v[156:157], off
	s_barrier
	s_waitcnt lgkmcnt(0)
	v_mfma_f32_16x16x32_bf16 v[62:65], v[66:69], v[168:171], v[62:65]
	v_mfma_f32_16x16x32_bf16 v[58:61], v[74:77], v[168:171], v[58:61]
	v_mfma_f32_16x16x32_bf16 v[46:49], v[66:69], v[190:193], v[46:49]
	v_mfma_f32_16x16x32_bf16 v[42:45], v[74:77], v[190:193], v[42:45]
	v_mfma_f32_16x16x32_bf16 v[30:33], v[66:69], v[198:201], v[30:33]
	v_mfma_f32_16x16x32_bf16 v[26:29], v[74:77], v[198:201], v[26:29]
	v_mfma_f32_16x16x32_bf16 v[14:17], v[66:69], v[206:209], v[14:17]
	v_mfma_f32_16x16x32_bf16 v[10:13], v[74:77], v[206:209], v[10:13]
	v_mfma_f32_16x16x32_bf16 v[62:65], v[70:73], v[172:175], v[62:65]
	v_mfma_f32_16x16x32_bf16 v[58:61], v[78:81], v[172:175], v[58:61]
	v_mfma_f32_16x16x32_bf16 v[46:49], v[70:73], v[194:197], v[46:49]
	v_mfma_f32_16x16x32_bf16 v[42:45], v[78:81], v[194:197], v[42:45]
	v_mfma_f32_16x16x32_bf16 v[30:33], v[70:73], v[202:205], v[30:33]
	v_mfma_f32_16x16x32_bf16 v[26:29], v[78:81], v[202:205], v[26:29]
	v_mfma_f32_16x16x32_bf16 v[14:17], v[70:73], v[210:213], v[14:17]
	v_mfma_f32_16x16x32_bf16 v[10:13], v[78:81], v[210:213], v[10:13]
	s_barrier
	s_add_u32 s20, s20, 0x40080
	s_addc_u32 s21, s21, 0
	s_add_i32 s0, s1, s29
	s_mov_b32 m0, s0
	v_lshl_add_u64 v[66:67], s[20:21], 0, v[4:5]
	global_load_lds_dwordx4 v[66:67], off
	s_add_i32 m0, s0, 0x2000
	v_lshl_add_u64 v[66:67], s[20:21], 0, v[146:147]
	global_load_lds_dwordx4 v[66:67], off
	s_waitcnt vmcnt(6)
	s_barrier
	v_mfma_f32_16x16x32_bf16 v[54:57], v[214:217], v[168:171], v[54:57]
	v_mfma_f32_16x16x32_bf16 v[50:53], v[222:225], v[168:171], v[50:53]
	v_mfma_f32_16x16x32_bf16 v[38:41], v[214:217], v[190:193], v[38:41]
	v_mfma_f32_16x16x32_bf16 v[34:37], v[222:225], v[190:193], v[34:37]
	v_mfma_f32_16x16x32_bf16 v[22:25], v[214:217], v[198:201], v[22:25]
	v_mfma_f32_16x16x32_bf16 v[18:21], v[222:225], v[198:201], v[18:21]
	v_mfma_f32_16x16x32_bf16 v[6:9], v[214:217], v[206:209], v[6:9]
	v_mfma_f32_16x16x32_bf16 v[0:3], v[222:225], v[206:209], v[0:3]
	v_mfma_f32_16x16x32_bf16 v[54:57], v[218:221], v[172:175], v[54:57]
	v_mfma_f32_16x16x32_bf16 v[50:53], v[242:245], v[172:175], v[50:53]
	v_mfma_f32_16x16x32_bf16 v[38:41], v[218:221], v[194:197], v[38:41]
	v_mfma_f32_16x16x32_bf16 v[34:37], v[242:245], v[194:197], v[34:37]
	v_mfma_f32_16x16x32_bf16 v[22:25], v[218:221], v[202:205], v[22:25]
	v_mfma_f32_16x16x32_bf16 v[18:21], v[242:245], v[202:205], v[18:21]
	v_mfma_f32_16x16x32_bf16 v[6:9], v[218:221], v[210:213], v[6:9]
	v_mfma_f32_16x16x32_bf16 v[0:3], v[242:245], v[210:213], v[0:3]
	s_add_i32 s52, s52, 2
	s_add_u32 s18, s18, 0x100
	s_addc_u32 s19, s19, 0
	s_add_u32 s50, s50, 0x100
	s_addc_u32 s51, s51, 0
	s_cmp_gt_u32 s52, 13
	s_barrier
	s_cbranch_scc1 .Lpeel_exit_1

; __device__ __forceinline__ unsigned cvt_pk_bf16(float lo, float hi) { unsigned r; asm volatile("s_nop 0\n\tv_cvt_pk_bf16_f32 %0, %1, %2" : "=v"(r) : "v"(lo), "v"(hi)); return r; }
; __device__ __forceinline__ float siluf_(float x) { return x * __builtin_amdgcn_rcpf(1.f + __expf(-x)); }
;     __device__ __forceinline__ void operator()(const f32x4 (&acc)[2][2][4][2], const Unit& u, int wr, int wc, int fr, int fq) const {
;         const int row0 = u.pm * 256 + wr * 64 + fr, hc0 = u.pn * 128 + wc * 32 + fq * 8;
;         const float* swp = sw + (size_t)(u.pm >> 3) * 5632 + u.pn * 256 + wc * 32 + 8 * fq;
;         f32x4 ra, rb; load_rstd(ss, row0, ra, rb);
;         const f32x4 sg0 = *(const f32x4*)(swp), sg1 = *(const f32x4*)(swp + 4), su0 = *(const f32x4*)(swp + 128), su1 = *(const f32x4*)(swp + 132);
; #pragma unroll
;         for (int ai = 0; ai < 2; ++ai)
; #pragma unroll
;             for (int m = 0; m < 4; ++m) { const int r = row0 + ai * 128 + m * 16;
;                 const float rstd = ai ? rb[m] : ra[m];
;                 const f32x4 g0 = acc[ai][0][m][0] * rstd + sg0, g1 = acc[ai][0][m][1] * rstd + sg1, u0 = acc[ai][1][m][0] * rstd + su0, u1 = acc[ai][1][m][1] * rstd + su1;
;                 uint4 st; st.x = cvt_pk_bf16(siluf_(g0[0]) * u0[0], siluf_(g0[1]) * u0[1]); st.y = cvt_pk_bf16(siluf_(g0[2]) * u0[2], siluf_(g0[3]) * u0[3]);
;                 st.z = cvt_pk_bf16(siluf_(g1[0]) * u1[0], siluf_(g1[1]) * u1[1]); st.w = cvt_pk_bf16(siluf_(g1[2]) * u1[2], siluf_(g1[3]) * u1[3]);
;                 *(uint4*)(hid + (size_t)r * DFF + hc0) = st; }
.Lpeel_exit_1:
	s_setprio 0
	v_lshl_add_u32 v156, s43, 8, v159
	v_ashrrev_i32_e32 v157, 31, v156
	v_lshl_add_u64 v[66:67], v[156:157], 2, s[8:9]
	global_load_dword v190, v[66:67], off
	global_load_dword v191, v[66:67], off offset:64
	global_load_dword v192, v[66:67], off offset:128
	global_load_dword v193, v[66:67], off offset:192
	global_load_dword v194, v[66:67], off offset:512
	global_load_dword v195, v[66:67], off offset:576
	global_load_dword v196, v[66:67], off offset:640
	global_load_dword v197, v[66:67], off offset:704
	s_ashr_i32 s0, s43, 3
	s_mul_hi_i32 s1, s0, 0x5800
	s_mulk_i32 s0, 0x5800
	s_add_u32 s0, s36, s0
	s_addc_u32 s1, s37, s1
	s_lshl_b32 s18, s42, 8
	s_ashr_i32 s19, s18, 31
	s_lshl_b64 s[18:19], s[18:19], 2
	s_add_u32 s0, s0, s18
	s_addc_u32 s1, s1, s19
	s_add_u32 s18, s0, s41
	s_addc_u32 s19, s1, 0
	v_lshl_or_b32 v170, s42, 7, v163
	v_ashrrev_i32_e32 v171, 31, v170
	global_load_dwordx4 v[66:69], v167, s[18:19] offset:16
	global_load_dwordx4 v[74:77], v167, s[18:19]
	global_load_dwordx4 v[70:73], v167, s[18:19] offset:528
	global_load_dwordx4 v[78:81], v167, s[18:19] offset:512
	s_and_b64 vcc, exec, s[4:5]
	s_mov_b32 s42, s10
	s_mov_b32 s43, s12
	s_mov_b64 s[20:21], s[16:17]
	s_waitcnt vmcnt(4)
	v_fmamk_f32 v198, v190, 0x3a800000, v229
	v_rsq_f32_e32 v174, v198
	v_fmamk_f32 v198, v194, 0x3a800000, v229
	v_rsq_f32_e32 v164, v198
	v_fmamk_f32 v198, v191, 0x3a800000, v229
	v_rsq_f32_e32 v172, v198
	v_fmamk_f32 v198, v195, 0x3a800000, v229
	v_rsq_f32_e32 v162, v198
	v_fmamk_f32 v198, v192, 0x3a800000, v229
	v_rsq_f32_e32 v168, v198
	v_fmamk_f32 v198, v196, 0x3a800000, v229
	v_rsq_f32_e32 v160, v198
	v_fmamk_f32 v198, v193, 0x3a800000, v229
	v_fmamk_f32 v199, v197, 0x3a800000, v229
	v_rsq_f32_e32 v166, v198
	v_rsq_f32_e32 v158, v199
	s_waitcnt vmcnt(0)
	v_pk_fma_f32 v[138:139], v[138:139], v[174:175], v[66:67] op_sel_hi:[1,0,1]
	v_pk_fma_f32 v[142:143], v[142:143], v[174:175], v[74:75] op_sel_hi:[1,0,1]
	v_pk_fma_f32 v[144:145], v[144:145], v[174:175], v[76:77] op_sel_hi:[1,0,1]
	v_pk_fma_f32 v[176:177], v[134:135], v[174:175], v[78:79] op_sel_hi:[1,0,1]
	v_pk_fma_f32 v[134:135], v[132:133], v[174:175], v[72:73] op_sel_hi:[1,0,1]
	v_pk_fma_f32 v[132:133], v[130:131], v[174:175], v[70:71] op_sel_hi:[1,0,1]
	v_mul_f32_e32 v130, 0xbfb8aa3b, v142
	v_mul_f32_e32 v131, 0xbfb8aa3b, v143
	v_exp_f32_e32 v130, v130
	v_exp_f32_e32 v131, v131
	v_pk_fma_f32 v[136:137], v[136:137], v[174:175], v[80:81] op_sel_hi:[1,0,1]
	v_pk_fma_f32 v[140:141], v[140:141], v[174:175], v[68:69] op_sel_hi:[1,0,1]
	v_add_f32_e32 v130, 1.0, v130
	v_add_f32_e32 v131, 1.0, v131
	v_rcp_f32_e32 v130, v130
	v_rcp_f32_e32 v131, v131
	v_pk_fma_f32 v[126:127], v[126:127], v[172:173], v[74:75] op_sel_hi:[1,0,1]
	v_pk_fma_f32 v[118:119], v[118:119], v[172:173], v[78:79] op_sel_hi:[1,0,1]
	v_mul_f32_e32 v130, v142, v130
	v_mul_f32_e32 v131, v143, v131
	v_mul_f32_e32 v130, v176, v130
	v_mul_f32_e32 v131, v177, v131
	s_nop 0
	v_cvt_pk_bf16_f32 v130, v130, v131
	v_mul_f32_e32 v131, 0xbfb8aa3b, v144
	v_exp_f32_e32 v131, v131
	v_pk_fma_f32 v[128:129], v[128:129], v[172:173], v[76:77] op_sel_hi:[1,0,1]
	v_pk_fma_f32 v[120:121], v[120:121], v[172:173], v[80:81] op_sel_hi:[1,0,1]
	v_pk_fma_f32 v[122:123], v[122:123], v[172:173], v[66:67] op_sel_hi:[1,0,1]
	v_add_f32_e32 v131, 1.0, v131
	v_rcp_f32_e32 v131, v131
	v_pk_fma_f32 v[124:125], v[124:125], v[172:173], v[68:69] op_sel_hi:[1,0,1]
	v_pk_fma_f32 v[110:111], v[110:111], v[168:169], v[74:75] op_sel_hi:[1,0,1]
	v_pk_fma_f32 v[102:103], v[102:103], v[168:169], v[78:79] op_sel_hi:[1,0,1]
	v_mul_f32_e32 v131, v144, v131
	v_mul_f32_e32 v131, v136, v131
	v_mul_f32_e32 v136, 0xbfb8aa3b, v145
	v_exp_f32_e32 v136, v136
	v_pk_fma_f32 v[112:113], v[112:113], v[168:169], v[76:77] op_sel_hi:[1,0,1]
	v_pk_fma_f32 v[104:105], v[104:105], v[168:169], v[80:81] op_sel_hi:[1,0,1]
	v_pk_fma_f32 v[106:107], v[106:107], v[168:169], v[66:67] op_sel_hi:[1,0,1]
	v_add_f32_e32 v136, 1.0, v136
	v_rcp_f32_e32 v136, v136
	v_pk_fma_f32 v[108:109], v[108:109], v[168:169], v[68:69] op_sel_hi:[1,0,1]
	v_pk_fma_f32 v[94:95], v[94:95], v[166:167], v[74:75] op_sel_hi:[1,0,1]
	v_pk_fma_f32 v[86:87], v[86:87], v[166:167], v[78:79] op_sel_hi:[1,0,1]
	v_mul_f32_e32 v136, v145, v136
	v_mul_f32_e32 v136, v137, v136
	s_nop 0
	v_cvt_pk_bf16_f32 v131, v131, v136
	v_mul_f32_e32 v136, 0xbfb8aa3b, v138
	v_exp_f32_e32 v136, v136
	v_pk_fma_f32 v[96:97], v[96:97], v[166:167], v[76:77] op_sel_hi:[1,0,1]
	v_pk_fma_f32 v[88:89], v[88:89], v[166:167], v[80:81] op_sel_hi:[1,0,1]
	v_pk_fma_f32 v[90:91], v[90:91], v[166:167], v[66:67] op_sel_hi:[1,0,1]
	v_add_f32_e32 v136, 1.0, v136
	v_rcp_f32_e32 v136, v136
	v_pk_fma_f32 v[92:93], v[92:93], v[166:167], v[68:69] op_sel_hi:[1,0,1]
	v_pk_fma_f32 v[62:63], v[62:63], v[164:165], v[74:75] op_sel_hi:[1,0,1]
	v_pk_fma_f32 v[54:55], v[54:55], v[164:165], v[78:79] op_sel_hi:[1,0,1]
	v_mul_f32_e32 v136, v138, v136
	v_mul_f32_e32 v132, v132, v136
	v_mul_f32_e32 v136, 0xbfb8aa3b, v139
	v_exp_f32_e32 v136, v136
	v_pk_fma_f32 v[64:65], v[64:65], v[164:165], v[76:77] op_sel_hi:[1,0,1]
	v_pk_fma_f32 v[56:57], v[56:57], v[164:165], v[80:81] op_sel_hi:[1,0,1]
	v_pk_fma_f32 v[58:59], v[58:59], v[164:165], v[66:67] op_sel_hi:[1,0,1]
	v_add_f32_e32 v136, 1.0, v136
	v_rcp_f32_e32 v136, v136
	v_pk_fma_f32 v[60:61], v[60:61], v[164:165], v[68:69] op_sel_hi:[1,0,1]
	v_pk_fma_f32 v[46:47], v[46:47], v[162:163], v[74:75] op_sel_hi:[1,0,1]
	v_pk_fma_f32 v[38:39], v[38:39], v[162:163], v[78:79] op_sel_hi:[1,0,1]
	v_mul_f32_e32 v136, v139, v136
	v_mul_f32_e32 v133, v133, v136
	s_nop 0
	v_cvt_pk_bf16_f32 v132, v132, v133
	v_mul_f32_e32 v133, 0xbfb8aa3b, v140
; __device__ __forceinline__ unsigned cvt_pk_bf16(float lo, float hi) { unsigned r; asm volatile("s_nop 0\n\tv_cvt_pk_bf16_f32 %0, %1, %2" : "=v"(r) : "v"(lo), "v"(hi)); return r; }
; __device__ __forceinline__ float siluf_(float x) { return x * __builtin_amdgcn_rcpf(1.f + __expf(-x)); }
;     __device__ __forceinline__ void operator()(const f32x4 (&acc)[2][2][4][2], const Unit& u, int wr, int wc, int fr, int fq) const {
;     ...
;             for (int m = 0; m < 4; ++m) { const int r = row0 + ai * 128 + m * 16;
;                 const float rstd = ai ? rb[m] : ra[m];
;                 const f32x4 g0 = acc[ai][0][m][0] * rstd + sg0, g1 = acc[ai][0][m][1] * rstd + sg1, u0 = acc[ai][1][m][0] * rstd + su0, u1 = acc[ai][1][m][1] * rstd + su1;
;                 uint4 st; st.x = cvt_pk_bf16(siluf_(g0[0]) * u0[0], siluf_(g0[1]) * u0[1]); st.y = cvt_pk_bf16(siluf_(g0[2]) * u0[2], siluf_(g0[3]) * u0[3]);
;                 st.z = cvt_pk_bf16(siluf_(g1[0]) * u1[0], siluf_(g1[1]) * u1[1]); st.w = cvt_pk_bf16(siluf_(g1[2]) * u1[2], siluf_(g1[3]) * u1[3]);
;                 *(uint4*)(hid + (size_t)r * DFF + hc0) = st; }
	v_exp_f32_e32 v133, v133
	v_lshlrev_b64 v[136:137], 1, v[170:171]
	v_pk_fma_f32 v[48:49], v[48:49], v[162:163], v[76:77] op_sel_hi:[1,0,1]
	v_pk_fma_f32 v[40:41], v[40:41], v[162:163], v[80:81] op_sel_hi:[1,0,1]
	v_add_f32_e32 v133, 1.0, v133
	v_rcp_f32_e32 v133, v133
	v_pk_fma_f32 v[42:43], v[42:43], v[162:163], v[66:67] op_sel_hi:[1,0,1]
	v_pk_fma_f32 v[44:45], v[44:45], v[162:163], v[68:69] op_sel_hi:[1,0,1]
	v_pk_fma_f32 v[30:31], v[30:31], v[160:161], v[74:75] op_sel_hi:[1,0,1]
	v_mul_f32_e32 v133, v140, v133
	v_mul_f32_e32 v133, v134, v133
	v_mul_f32_e32 v134, 0xbfb8aa3b, v141
	v_exp_f32_e32 v134, v134
	v_pk_fma_f32 v[22:23], v[22:23], v[160:161], v[78:79] op_sel_hi:[1,0,1]
	v_pk_fma_f32 v[32:33], v[32:33], v[160:161], v[76:77] op_sel_hi:[1,0,1]
	v_pk_fma_f32 v[24:25], v[24:25], v[160:161], v[80:81] op_sel_hi:[1,0,1]
	v_add_f32_e32 v134, 1.0, v134
	v_rcp_f32_e32 v134, v134
	v_pk_fma_f32 v[26:27], v[26:27], v[160:161], v[66:67] op_sel_hi:[1,0,1]
	v_pk_fma_f32 v[28:29], v[28:29], v[160:161], v[68:69] op_sel_hi:[1,0,1]
	v_pk_fma_f32 v[14:15], v[14:15], v[158:159], v[74:75] op_sel_hi:[1,0,1]
	v_mul_f32_e32 v134, v141, v134
	v_mul_f32_e32 v134, v135, v134
	s_nop 0
	v_cvt_pk_bf16_f32 v133, v133, v134
	v_mov_b64_e32 v[134:135], s[6:7]
	v_mad_i64_i32 v[138:139], s[18:19], v156, s74, v[134:135]
	v_lshl_add_u64 v[138:139], v[138:139], 0, v[136:137]
	global_store_dwordx4 v[138:139], v[130:133], off
	v_pk_fma_f32 v[6:7], v[6:7], v[158:159], v[78:79] op_sel_hi:[1,0,1]
	v_pk_fma_f32 v[16:17], v[16:17], v[158:159], v[76:77] op_sel_hi:[1,0,1]
	v_pk_fma_f32 v[130:131], v[116:117], v[172:173], v[72:73] op_sel_hi:[1,0,1]
	v_pk_fma_f32 v[116:117], v[114:115], v[172:173], v[70:71] op_sel_hi:[1,0,1]
	v_mul_f32_e32 v114, 0xbfb8aa3b, v126
	v_mul_f32_e32 v115, 0xbfb8aa3b, v127
	v_exp_f32_e32 v114, v114
	v_exp_f32_e32 v115, v115
	v_or_b32_e32 v132, 16, v156
	v_pk_fma_f32 v[8:9], v[8:9], v[158:159], v[80:81] op_sel_hi:[1,0,1]
	v_add_f32_e32 v114, 1.0, v114
	v_add_f32_e32 v115, 1.0, v115
	v_rcp_f32_e32 v114, v114
	v_rcp_f32_e32 v115, v115
	v_pk_fma_f32 v[10:11], v[10:11], v[158:159], v[66:67] op_sel_hi:[1,0,1]
	v_pk_fma_f32 v[12:13], v[12:13], v[158:159], v[68:69] op_sel_hi:[1,0,1]
	v_mul_f32_e32 v114, v126, v114
	v_mul_f32_e32 v115, v127, v115
	v_mul_f32_e32 v114, v118, v114
	v_mul_f32_e32 v115, v119, v115
	s_nop 0
	v_cvt_pk_bf16_f32 v114, v114, v115
	v_mul_f32_e32 v115, 0xbfb8aa3b, v128
	v_mul_f32_e32 v118, 0xbfb8aa3b, v129
	v_exp_f32_e32 v115, v115
	v_exp_f32_e32 v118, v118
	v_add_f32_e32 v115, 1.0, v115
	v_add_f32_e32 v118, 1.0, v118
	v_rcp_f32_e32 v115, v115
	v_rcp_f32_e32 v118, v118
	v_mul_f32_e32 v115, v128, v115
	v_mul_f32_e32 v118, v129, v118
	v_mul_f32_e32 v115, v120, v115
	v_mul_f32_e32 v118, v121, v118
	s_nop 0
	v_cvt_pk_bf16_f32 v115, v115, v118
	v_mul_f32_e32 v118, 0xbfb8aa3b, v122
	v_exp_f32_e32 v118, v118
	s_nop 0
	v_add_f32_e32 v118, 1.0, v118
	v_rcp_f32_e32 v118, v118
	s_nop 0
	v_mul_f32_e32 v118, v122, v118
	v_mul_f32_e32 v116, v116, v118
	v_mul_f32_e32 v118, 0xbfb8aa3b, v123
	v_exp_f32_e32 v118, v118
	s_nop 0
	v_add_f32_e32 v118, 1.0, v118
	v_rcp_f32_e32 v118, v118
	s_nop 0
	v_mul_f32_e32 v118, v123, v118
	v_mul_f32_e32 v117, v117, v118
	s_nop 0
	v_cvt_pk_bf16_f32 v116, v116, v117
	v_mul_f32_e32 v117, 0xbfb8aa3b, v124
	v_mul_f32_e32 v118, 0xbfb8aa3b, v125
	v_exp_f32_e32 v117, v117
	v_exp_f32_e32 v118, v118
	v_add_f32_e32 v117, 1.0, v117
	v_add_f32_e32 v118, 1.0, v118
	v_rcp_f32_e32 v117, v117
	v_rcp_f32_e32 v118, v118
	v_mul_f32_e32 v117, v124, v117
	v_mul_f32_e32 v118, v125, v118
	v_mul_f32_e32 v117, v130, v117
	v_mul_f32_e32 v118, v131, v118
	s_nop 0
	v_cvt_pk_bf16_f32 v117, v117, v118
	v_mad_i64_i32 v[118:119], s[18:19], v132, s74, v[134:135]
	v_lshl_add_u64 v[118:119], v[118:119], 0, v[136:137]
	global_store_dwordx4 v[118:119], v[114:117], off
	s_nop 1
	v_pk_fma_f32 v[114:115], v[100:101], v[168:169], v[72:73] op_sel_hi:[1,0,1]
	v_pk_fma_f32 v[100:101], v[98:99], v[168:169], v[70:71] op_sel_hi:[1,0,1]
	v_mul_f32_e32 v98, 0xbfb8aa3b, v110
	v_mul_f32_e32 v99, 0xbfb8aa3b, v111
	v_exp_f32_e32 v98, v98
	v_exp_f32_e32 v99, v99
	v_or_b32_e32 v116, 32, v156
	v_add_f32_e32 v98, 1.0, v98
	v_add_f32_e32 v99, 1.0, v99
	v_rcp_f32_e32 v98, v98
	v_rcp_f32_e32 v99, v99
	v_mul_f32_e32 v98, v110, v98
	v_mul_f32_e32 v99, v111, v99
	v_mul_f32_e32 v98, v102, v98
	v_mul_f32_e32 v99, v103, v99
	s_nop 0
	v_cvt_pk_bf16_f32 v98, v98, v99
	v_mul_f32_e32 v99, 0xbfb8aa3b, v112
	v_mul_f32_e32 v102, 0xbfb8aa3b, v113
	v_exp_f32_e32 v99, v99
	v_exp_f32_e32 v102, v102
	v_add_f32_e32 v99, 1.0, v99
	v_add_f32_e32 v102, 1.0, v102
	v_rcp_f32_e32 v99, v99
	v_rcp_f32_e32 v102, v102
	v_mul_f32_e32 v99, v112, v99
	v_mul_f32_e32 v102, v113, v102
	v_mul_f32_e32 v99, v104, v99
	v_mul_f32_e32 v102, v105, v102
	s_nop 0
	v_cvt_pk_bf16_f32 v99, v99, v102
	v_mul_f32_e32 v102, 0xbfb8aa3b, v106
	v_exp_f32_e32 v102, v102
	s_nop 0
	v_add_f32_e32 v102, 1.0, v102
	v_rcp_f32_e32 v102, v102
	s_nop 0
	v_mul_f32_e32 v102, v106, v102
	v_mul_f32_e32 v100, v100, v102
	v_mul_f32_e32 v102, 0xbfb8aa3b, v107
	v_exp_f32_e32 v102, v102
	s_nop 0
	v_add_f32_e32 v102, 1.0, v102
	v_rcp_f32_e32 v102, v102
	s_nop 0
	v_mul_f32_e32 v102, v107, v102
	v_mul_f32_e32 v101, v101, v102
	s_nop 0
	v_cvt_pk_bf16_f32 v100, v100, v101
	v_mul_f32_e32 v101, 0xbfb8aa3b, v108
	v_mul_f32_e32 v102, 0xbfb8aa3b, v109
	v_exp_f32_e32 v101, v101
	v_exp_f32_e32 v102, v102
	v_add_f32_e32 v101, 1.0, v101
	v_add_f32_e32 v102, 1.0, v102
	v_rcp_f32_e32 v101, v101
	v_rcp_f32_e32 v102, v102
	v_mul_f32_e32 v101, v108, v101
	v_mul_f32_e32 v102, v109, v102
	v_mul_f32_e32 v101, v114, v101
	v_mul_f32_e32 v102, v115, v102
	s_nop 0
; __device__ __forceinline__ unsigned cvt_pk_bf16(float lo, float hi) { unsigned r; asm volatile("s_nop 0\n\tv_cvt_pk_bf16_f32 %0, %1, %2" : "=v"(r) : "v"(lo), "v"(hi)); return r; }
; __device__ __forceinline__ float siluf_(float x) { return x * __builtin_amdgcn_rcpf(1.f + __expf(-x)); }
;     __device__ __forceinline__ void operator()(const f32x4 (&acc)[2][2][4][2], const Unit& u, int wr, int wc, int fr, int fq) const {
;     ...
;             for (int m = 0; m < 4; ++m) { const int r = row0 + ai * 128 + m * 16;
;                 const float rstd = ai ? rb[m] : ra[m];
;                 const f32x4 g0 = acc[ai][0][m][0] * rstd + sg0, g1 = acc[ai][0][m][1] * rstd + sg1, u0 = acc[ai][1][m][0] * rstd + su0, u1 = acc[ai][1][m][1] * rstd + su1;
;                 uint4 st; st.x = cvt_pk_bf16(siluf_(g0[0]) * u0[0], siluf_(g0[1]) * u0[1]); st.y = cvt_pk_bf16(siluf_(g0[2]) * u0[2], siluf_(g0[3]) * u0[3]);
;                 st.z = cvt_pk_bf16(siluf_(g1[0]) * u1[0], siluf_(g1[1]) * u1[1]); st.w = cvt_pk_bf16(siluf_(g1[2]) * u1[2], siluf_(g1[3]) * u1[3]);
;                 *(uint4*)(hid + (size_t)r * DFF + hc0) = st; }
	v_cvt_pk_bf16_f32 v101, v101, v102
	v_mad_i64_i32 v[102:103], s[18:19], v116, s74, v[134:135]
	v_lshl_add_u64 v[102:103], v[102:103], 0, v[136:137]
	global_store_dwordx4 v[102:103], v[98:101], off
	s_nop 1
	v_pk_fma_f32 v[98:99], v[84:85], v[166:167], v[72:73] op_sel_hi:[1,0,1]
	v_pk_fma_f32 v[84:85], v[82:83], v[166:167], v[70:71] op_sel_hi:[1,0,1]
	v_mul_f32_e32 v82, 0xbfb8aa3b, v94
	v_mul_f32_e32 v83, 0xbfb8aa3b, v95
	v_exp_f32_e32 v82, v82
	v_exp_f32_e32 v83, v83
	v_or_b32_e32 v100, 48, v156
	v_add_f32_e32 v82, 1.0, v82
	v_add_f32_e32 v83, 1.0, v83
	v_rcp_f32_e32 v82, v82
	v_rcp_f32_e32 v83, v83
	v_mul_f32_e32 v82, v94, v82
	v_mul_f32_e32 v83, v95, v83
	v_mul_f32_e32 v82, v86, v82
	v_mul_f32_e32 v83, v87, v83
	s_nop 0
	v_cvt_pk_bf16_f32 v82, v82, v83
	v_mul_f32_e32 v83, 0xbfb8aa3b, v96
	v_mul_f32_e32 v86, 0xbfb8aa3b, v97
	v_exp_f32_e32 v83, v83
	v_exp_f32_e32 v86, v86
	v_add_f32_e32 v83, 1.0, v83
	v_add_f32_e32 v86, 1.0, v86
	v_rcp_f32_e32 v83, v83
	v_rcp_f32_e32 v86, v86
	v_mul_f32_e32 v83, v96, v83
	v_mul_f32_e32 v86, v97, v86
	v_mul_f32_e32 v83, v88, v83
	v_mul_f32_e32 v86, v89, v86
	s_nop 0
	v_cvt_pk_bf16_f32 v83, v83, v86
	v_mul_f32_e32 v86, 0xbfb8aa3b, v90
	v_exp_f32_e32 v86, v86
	s_nop 0
	v_add_f32_e32 v86, 1.0, v86
	v_rcp_f32_e32 v86, v86
	s_nop 0
	v_mul_f32_e32 v86, v90, v86
	v_mul_f32_e32 v84, v84, v86
	v_mul_f32_e32 v86, 0xbfb8aa3b, v91
	v_exp_f32_e32 v86, v86
	s_nop 0
	v_add_f32_e32 v86, 1.0, v86
	v_rcp_f32_e32 v86, v86
	s_nop 0
	v_mul_f32_e32 v86, v91, v86
	v_mul_f32_e32 v85, v85, v86
	s_nop 0
	v_cvt_pk_bf16_f32 v84, v84, v85
	v_mul_f32_e32 v85, 0xbfb8aa3b, v92
	v_mul_f32_e32 v86, 0xbfb8aa3b, v93
	v_exp_f32_e32 v85, v85
	v_exp_f32_e32 v86, v86
	v_add_f32_e32 v85, 1.0, v85
	v_add_f32_e32 v86, 1.0, v86
	v_rcp_f32_e32 v85, v85
	v_rcp_f32_e32 v86, v86
	v_mul_f32_e32 v85, v92, v85
	v_mul_f32_e32 v86, v93, v86
	v_mul_f32_e32 v85, v98, v85
	v_mul_f32_e32 v86, v99, v86
	s_nop 0
	v_cvt_pk_bf16_f32 v85, v85, v86
	v_mad_i64_i32 v[86:87], s[18:19], v100, s74, v[134:135]
	v_lshl_add_u64 v[86:87], v[86:87], 0, v[136:137]
	global_store_dwordx4 v[86:87], v[82:85], off
	s_nop 1
	v_pk_fma_f32 v[82:83], v[52:53], v[164:165], v[72:73] op_sel_hi:[1,0,1]
	v_pk_fma_f32 v[52:53], v[50:51], v[164:165], v[70:71] op_sel_hi:[1,0,1]
	v_mul_f32_e32 v50, 0xbfb8aa3b, v62
	v_mul_f32_e32 v51, 0xbfb8aa3b, v63
	v_exp_f32_e32 v50, v50
	v_exp_f32_e32 v51, v51
	v_add_u32_e32 v84, 0x80, v156
	v_add_f32_e32 v50, 1.0, v50
	v_add_f32_e32 v51, 1.0, v51
	v_rcp_f32_e32 v50, v50
	v_rcp_f32_e32 v51, v51
	v_mul_f32_e32 v50, v62, v50
	v_mul_f32_e32 v51, v63, v51
	v_mul_f32_e32 v50, v54, v50
	v_mul_f32_e32 v51, v55, v51
	s_nop 0
	v_cvt_pk_bf16_f32 v50, v50, v51
	v_mul_f32_e32 v51, 0xbfb8aa3b, v64
	v_mul_f32_e32 v54, 0xbfb8aa3b, v65
	v_exp_f32_e32 v51, v51
	v_exp_f32_e32 v54, v54
	v_add_f32_e32 v51, 1.0, v51
	v_add_f32_e32 v54, 1.0, v54
	v_rcp_f32_e32 v51, v51
	v_rcp_f32_e32 v54, v54
	v_mul_f32_e32 v51, v64, v51
	v_mul_f32_e32 v54, v65, v54
	v_mul_f32_e32 v51, v56, v51
	v_mul_f32_e32 v54, v57, v54
	s_nop 0
	v_cvt_pk_bf16_f32 v51, v51, v54
	v_mul_f32_e32 v54, 0xbfb8aa3b, v58
	v_exp_f32_e32 v54, v54
	s_nop 0
	v_add_f32_e32 v54, 1.0, v54
	v_rcp_f32_e32 v54, v54
	s_nop 0
	v_mul_f32_e32 v54, v58, v54
	v_mul_f32_e32 v52, v52, v54
	v_mul_f32_e32 v54, 0xbfb8aa3b, v59
	v_exp_f32_e32 v54, v54
	s_nop 0
	v_add_f32_e32 v54, 1.0, v54
	v_rcp_f32_e32 v54, v54
	s_nop 0
	v_mul_f32_e32 v54, v59, v54
	v_mul_f32_e32 v53, v53, v54
	s_nop 0
	v_cvt_pk_bf16_f32 v52, v52, v53
	v_mul_f32_e32 v53, 0xbfb8aa3b, v60
	v_mul_f32_e32 v54, 0xbfb8aa3b, v61
	v_exp_f32_e32 v53, v53
	v_exp_f32_e32 v54, v54
	v_add_f32_e32 v53, 1.0, v53
	v_add_f32_e32 v54, 1.0, v54
	v_rcp_f32_e32 v53, v53
	v_rcp_f32_e32 v54, v54
	v_mul_f32_e32 v53, v60, v53
	v_mul_f32_e32 v54, v61, v54
	v_mul_f32_e32 v53, v82, v53
	v_mul_f32_e32 v54, v83, v54
	s_nop 0
	v_cvt_pk_bf16_f32 v53, v53, v54
	v_mad_i64_i32 v[54:55], s[18:19], v84, s74, v[134:135]
	v_lshl_add_u64 v[54:55], v[54:55], 0, v[136:137]
	global_store_dwordx4 v[54:55], v[50:53], off
	s_nop 1
	v_pk_fma_f32 v[50:51], v[36:37], v[162:163], v[72:73] op_sel_hi:[1,0,1]
	v_pk_fma_f32 v[36:37], v[34:35], v[162:163], v[70:71] op_sel_hi:[1,0,1]
	v_mul_f32_e32 v34, 0xbfb8aa3b, v46
	v_mul_f32_e32 v35, 0xbfb8aa3b, v47
	v_exp_f32_e32 v34, v34
	v_exp_f32_e32 v35, v35
	v_add_u32_e32 v52, 0x90, v156
	v_add_f32_e32 v34, 1.0, v34
	v_add_f32_e32 v35, 1.0, v35
	v_rcp_f32_e32 v34, v34
	v_rcp_f32_e32 v35, v35
	v_mul_f32_e32 v34, v46, v34
	v_mul_f32_e32 v35, v47, v35
	v_mul_f32_e32 v34, v38, v34
	v_mul_f32_e32 v35, v39, v35
	s_nop 0
	v_cvt_pk_bf16_f32 v34, v34, v35
	v_mul_f32_e32 v35, 0xbfb8aa3b, v48
	v_mul_f32_e32 v38, 0xbfb8aa3b, v49
	v_exp_f32_e32 v35, v35
	v_exp_f32_e32 v38, v38
	v_add_f32_e32 v35, 1.0, v35
	v_add_f32_e32 v38, 1.0, v38
	v_rcp_f32_e32 v35, v35
	v_rcp_f32_e32 v38, v38
	v_mul_f32_e32 v35, v48, v35
	v_mul_f32_e32 v38, v49, v38
; __device__ __forceinline__ unsigned cvt_pk_bf16(float lo, float hi) { unsigned r; asm volatile("s_nop 0\n\tv_cvt_pk_bf16_f32 %0, %1, %2" : "=v"(r) : "v"(lo), "v"(hi)); return r; }
; __device__ __forceinline__ float siluf_(float x) { return x * __builtin_amdgcn_rcpf(1.f + __expf(-x)); }
; #define PG8_WAIT_V(n) asm volatile("s_waitcnt vmcnt(" #n ")" ::: "memory")
; #define PG8_BAR __builtin_amdgcn_s_barrier()
; template <class Epi>
; __device__ __forceinline__ void gemm_phase(LAS unsigned char* lds, const Gemm g, const StaticOrder& S, const Epi& E) {
;     ...
;     PG8_WAIT_V(0);
;     if (wr == 0) PG8_BAR;
;     PG8_BAR;
;     __device__ __forceinline__ void operator()(const f32x4 (&acc)[2][2][4][2], const Unit& u, int wr, int wc, int fr, int fq) const {
;     ...
;             for (int m = 0; m < 4; ++m) { const int r = row0 + ai * 128 + m * 16;
;                 const float rstd = ai ? rb[m] : ra[m];
;                 const f32x4 g0 = acc[ai][0][m][0] * rstd + sg0, g1 = acc[ai][0][m][1] * rstd + sg1, u0 = acc[ai][1][m][0] * rstd + su0, u1 = acc[ai][1][m][1] * rstd + su1;
;                 uint4 st; st.x = cvt_pk_bf16(siluf_(g0[0]) * u0[0], siluf_(g0[1]) * u0[1]); st.y = cvt_pk_bf16(siluf_(g0[2]) * u0[2], siluf_(g0[3]) * u0[3]);
;                 st.z = cvt_pk_bf16(siluf_(g1[0]) * u1[0], siluf_(g1[1]) * u1[1]); st.w = cvt_pk_bf16(siluf_(g1[2]) * u1[2], siluf_(g1[3]) * u1[3]);
;                 *(uint4*)(hid + (size_t)r * DFF + hc0) = st; }
	v_mul_f32_e32 v35, v40, v35
	v_mul_f32_e32 v38, v41, v38
	s_nop 0
	v_cvt_pk_bf16_f32 v35, v35, v38
	v_mul_f32_e32 v38, 0xbfb8aa3b, v42
	v_exp_f32_e32 v38, v38
	s_nop 0
	v_add_f32_e32 v38, 1.0, v38
	v_rcp_f32_e32 v38, v38
	s_nop 0
	v_mul_f32_e32 v38, v42, v38
	v_mul_f32_e32 v36, v36, v38
	v_mul_f32_e32 v38, 0xbfb8aa3b, v43
	v_exp_f32_e32 v38, v38
	s_nop 0
	v_add_f32_e32 v38, 1.0, v38
	v_rcp_f32_e32 v38, v38
	s_nop 0
	v_mul_f32_e32 v38, v43, v38
	v_mul_f32_e32 v37, v37, v38
	s_nop 0
	v_cvt_pk_bf16_f32 v36, v36, v37
	v_mul_f32_e32 v37, 0xbfb8aa3b, v44
	v_mul_f32_e32 v38, 0xbfb8aa3b, v45
	v_exp_f32_e32 v37, v37
	v_exp_f32_e32 v38, v38
	v_add_f32_e32 v37, 1.0, v37
	v_add_f32_e32 v38, 1.0, v38
	v_rcp_f32_e32 v37, v37
	v_rcp_f32_e32 v38, v38
	v_mul_f32_e32 v37, v44, v37
	v_mul_f32_e32 v38, v45, v38
	v_mul_f32_e32 v37, v50, v37
	v_mul_f32_e32 v38, v51, v38
	s_nop 0
	v_cvt_pk_bf16_f32 v37, v37, v38
	v_mad_i64_i32 v[38:39], s[18:19], v52, s74, v[134:135]
	v_lshl_add_u64 v[38:39], v[38:39], 0, v[136:137]
	global_store_dwordx4 v[38:39], v[34:37], off
	s_nop 1
	v_pk_fma_f32 v[34:35], v[20:21], v[160:161], v[72:73] op_sel_hi:[1,0,1]
	v_pk_fma_f32 v[20:21], v[18:19], v[160:161], v[70:71] op_sel_hi:[1,0,1]
	v_mul_f32_e32 v18, 0xbfb8aa3b, v30
	v_mul_f32_e32 v19, 0xbfb8aa3b, v31
	v_exp_f32_e32 v18, v18
	v_exp_f32_e32 v19, v19
	v_add_u32_e32 v36, 0xa0, v156
	v_add_f32_e32 v18, 1.0, v18
	v_add_f32_e32 v19, 1.0, v19
	v_rcp_f32_e32 v18, v18
	v_rcp_f32_e32 v19, v19
	v_mul_f32_e32 v18, v30, v18
	v_mul_f32_e32 v19, v31, v19
	v_mul_f32_e32 v18, v22, v18
	v_mul_f32_e32 v19, v23, v19
	s_nop 0
	v_cvt_pk_bf16_f32 v18, v18, v19
	v_mul_f32_e32 v19, 0xbfb8aa3b, v32
	v_mul_f32_e32 v22, 0xbfb8aa3b, v33
	v_exp_f32_e32 v19, v19
	v_exp_f32_e32 v22, v22
	v_add_f32_e32 v19, 1.0, v19
	v_add_f32_e32 v22, 1.0, v22
	v_rcp_f32_e32 v19, v19
	v_rcp_f32_e32 v22, v22
	v_mul_f32_e32 v19, v32, v19
	v_mul_f32_e32 v22, v33, v22
	v_mul_f32_e32 v19, v24, v19
	v_mul_f32_e32 v22, v25, v22
	s_nop 0
	v_cvt_pk_bf16_f32 v19, v19, v22
	v_mul_f32_e32 v22, 0xbfb8aa3b, v26
	v_exp_f32_e32 v22, v22
	s_nop 0
	v_add_f32_e32 v22, 1.0, v22
	v_rcp_f32_e32 v22, v22
	s_nop 0
	v_mul_f32_e32 v22, v26, v22
	v_mul_f32_e32 v20, v20, v22
	v_mul_f32_e32 v22, 0xbfb8aa3b, v27
	v_exp_f32_e32 v22, v22
	s_nop 0
	v_add_f32_e32 v22, 1.0, v22
	v_rcp_f32_e32 v22, v22
	s_nop 0
	v_mul_f32_e32 v22, v27, v22
	v_mul_f32_e32 v21, v21, v22
	s_nop 0
	v_cvt_pk_bf16_f32 v20, v20, v21
	v_mul_f32_e32 v21, 0xbfb8aa3b, v28
	v_mul_f32_e32 v22, 0xbfb8aa3b, v29
	v_exp_f32_e32 v21, v21
	v_exp_f32_e32 v22, v22
	v_add_f32_e32 v21, 1.0, v21
	v_add_f32_e32 v22, 1.0, v22
	v_rcp_f32_e32 v21, v21
	v_rcp_f32_e32 v22, v22
	v_mul_f32_e32 v21, v28, v21
	v_mul_f32_e32 v22, v29, v22
	v_mul_f32_e32 v21, v34, v21
	v_mul_f32_e32 v22, v35, v22
	s_nop 0
	v_cvt_pk_bf16_f32 v21, v21, v22
	v_mad_i64_i32 v[22:23], s[18:19], v36, s74, v[134:135]
	v_lshl_add_u64 v[22:23], v[22:23], 0, v[136:137]
	global_store_dwordx4 v[22:23], v[18:21], off
	s_nop 1
	v_pk_fma_f32 v[18:19], v[2:3], v[158:159], v[72:73] op_sel_hi:[1,0,1]
	v_pk_fma_f32 v[2:3], v[0:1], v[158:159], v[70:71] op_sel_hi:[1,0,1]
	v_mul_f32_e32 v0, 0xbfb8aa3b, v14
	v_mul_f32_e32 v1, 0xbfb8aa3b, v15
	v_exp_f32_e32 v0, v0
	v_exp_f32_e32 v1, v1
	v_add_u32_e32 v20, 0xb0, v156
	v_add_f32_e32 v0, 1.0, v0
	v_add_f32_e32 v1, 1.0, v1
	v_rcp_f32_e32 v0, v0
	v_rcp_f32_e32 v1, v1
	v_mul_f32_e32 v0, v14, v0
	v_mul_f32_e32 v1, v15, v1
	v_mul_f32_e32 v0, v6, v0
	v_mul_f32_e32 v1, v7, v1
	s_nop 0
	v_cvt_pk_bf16_f32 v0, v0, v1
	v_mul_f32_e32 v1, 0xbfb8aa3b, v16
	v_mul_f32_e32 v6, 0xbfb8aa3b, v17
	v_exp_f32_e32 v1, v1
	v_exp_f32_e32 v6, v6
	v_add_f32_e32 v1, 1.0, v1
	v_add_f32_e32 v6, 1.0, v6
	v_rcp_f32_e32 v1, v1
	v_rcp_f32_e32 v6, v6
	v_mul_f32_e32 v1, v16, v1
	v_mul_f32_e32 v6, v17, v6
	v_mul_f32_e32 v1, v8, v1
	v_mul_f32_e32 v6, v9, v6
	s_nop 0
	v_cvt_pk_bf16_f32 v1, v1, v6
	v_mul_f32_e32 v6, 0xbfb8aa3b, v10
	v_exp_f32_e32 v6, v6
	s_nop 0
	v_add_f32_e32 v6, 1.0, v6
	v_rcp_f32_e32 v6, v6
	s_nop 0
	v_mul_f32_e32 v6, v10, v6
	v_mul_f32_e32 v2, v2, v6
	v_mul_f32_e32 v6, 0xbfb8aa3b, v11
	v_exp_f32_e32 v6, v6
	s_nop 0
	v_add_f32_e32 v6, 1.0, v6
	v_rcp_f32_e32 v6, v6
	s_nop 0
	v_mul_f32_e32 v6, v11, v6
	v_mul_f32_e32 v3, v3, v6
	s_nop 0
	v_cvt_pk_bf16_f32 v2, v2, v3
	v_mul_f32_e32 v3, 0xbfb8aa3b, v12
	v_mul_f32_e32 v6, 0xbfb8aa3b, v13
	v_exp_f32_e32 v3, v3
	v_exp_f32_e32 v6, v6
	v_add_f32_e32 v3, 1.0, v3
	v_add_f32_e32 v6, 1.0, v6
	v_rcp_f32_e32 v3, v3
	v_rcp_f32_e32 v6, v6
	v_mul_f32_e32 v3, v12, v3
	v_mul_f32_e32 v6, v13, v6
	v_mul_f32_e32 v3, v18, v3
	v_mul_f32_e32 v6, v19, v6
	s_nop 0
	v_cvt_pk_bf16_f32 v3, v3, v6
	v_mad_i64_i32 v[6:7], s[18:19], v20, s74, v[134:135]
	v_lshl_add_u64 v[6:7], v[6:7], 0, v[136:137]
	s_mov_b64 s[18:19], s[14:15]
	global_store_dwordx4 v[6:7], v[0:3], off
	s_cbranch_vccz .LBB0_2894
	s_waitcnt vmcnt(0)
	s_cmpk_gt_u32 s24, 0xff
	s_cbranch_scc1 .LBB0_2901
	s_barrier

; #define PG8_STAGE(bufoff, gbase, voff) do { _Pragma("unroll") for (int _i = 0; _i < 2; ++_i) \
;         __builtin_amdgcn_global_load_lds((const unsigned*)((const char*)(gbase) + (voff)[_i]), (LAS unsigned*)(lds + (bufoff) + ldsw + _i * 8192), 16, 0, 0); } while (0)
; #define PG8_LDA(dst, b, h) do { _Pragma("unroll") for (int m = 0; m < 4; ++m) _Pragma("unroll") for (int k = 0; k < 2; ++k) dst[m][k] = *(const LAS bf16x8*)(lds + PG8_SA(b, h) + aoff + m * 2048 + k * 1024); } while (0)
; #define PG8_LDB(dst, b, h) do { _Pragma("unroll") for (int n = 0; n < 2; ++n) _Pragma("unroll") for (int k = 0; k < 2; ++k) dst[n][k] = *(const LAS bf16x8*)(lds + PG8_SB(b, h) + boff + n * 2048 + k * 1024); } while (0)
; #define PG8_WAIT_V(n) asm volatile("s_waitcnt vmcnt(" #n ")" ::: "memory")
; #define PG8_WAIT_L(n) asm volatile("s_waitcnt lgkmcnt(" #n ")" ::: "memory")
; #define PG8_BAR __builtin_amdgcn_s_barrier()
; #define PG8_SCHED __builtin_amdgcn_sched_barrier(0)
; template <class Epi>
; __device__ __forceinline__ void gemm_phase(LAS unsigned char* lds, const Gemm g, const StaticOrder& S, const Epi& E) {
;     ...
;         for (int t = 0; t < nt; t += 2) {
;             const bool last = (t == nt - 2);
;             const char* a1 = cA + (size_t)(t + 1) * kstep;
;             const char* a2 = last ? nA : cA + (size_t)(t + 2) * kstep; const char* b2 = last ? nB : cB + (size_t)(t + 2) * kstep;
;             const char* a3 = a2 + kstep; const char* b3 = b2 + kstep;
;             PG8_LDB(B0, 0, 0); PG8_SCHED; PG8_LDA(At, 0, 0); PG8_STAGE(PG8_SA(1, 1), a1 + hstep, voffA);
;             PG8_WAIT_L(8); PG8_BAR; PG8_WAIT_L(0); PG8_MMA(0, 0, At, B0); PG8_BAR; PG8_SCHED;
;             PG8_LDB(B1, 0, 1); PG8_STAGE(PG8_SB(0, 0), b2, voffB);
;             PG8_BAR; PG8_WAIT_L(0); PG8_MMA(0, 1, At, B1); PG8_BAR;
;             PG8_LDA(At, 0, 1); PG8_STAGE(PG8_SA(0, 0), a2, voffA);
;             PG8_BAR; PG8_WAIT_L(0); PG8_MMA(1, 0, At, B0); PG8_BAR; PG8_SCHED;
;             PG8_STAGE(PG8_SB(0, 1), b2 + hstep, voffB);
;             PG8_WAIT_V(6); PG8_BAR; PG8_MMA(1, 1, At, B1); PG8_BAR;
;             PG8_LDB(B0, 1, 0); PG8_SCHED; PG8_LDA(At, 1, 0); PG8_STAGE(PG8_SA(0, 1), a2 + hstep, voffA);
;             PG8_WAIT_L(8); PG8_BAR; PG8_WAIT_L(0); PG8_MMA(0, 0, At, B0); PG8_BAR; PG8_SCHED;
.LBB0_2973:
	s_add_u32 s8, s28, 0x80
	s_addc_u32 s9, s29, 0
	s_add_u32 s62, s26, 0x100
	s_addc_u32 s63, s27, 0
	s_mov_b32 s26, 0
	s_waitcnt lgkmcnt(0)
	v_cmp_lt_u32_e32 vcc, 0xff, v228
	s_cbranch_vccnz .Lsp_skip_0
	s_setprio 1
.Lsp_skip_0:
	s_add_i32 s64, s26, 2
	s_add_u32 s0, s8, 0x80
	s_addc_u32 s1, s9, 0
	s_add_i32 s65, 0, 0x10000
	v_add_u32_e32 v4, s65, v245
	ds_read_b128 v[132:135], v4
	ds_read_b128 v[136:139], v4 offset:1024
	ds_read_b128 v[140:143], v4 offset:2048
	ds_read_b128 v[144:147], v4 offset:3072
	s_cmp_eq_u32 s57, s26
	s_cselect_b32 s26, s24, s0
	s_cselect_b32 s27, s25, s1
	s_cselect_b32 s29, s11, s63
	s_cselect_b32 s28, s10, s62
	v_lshl_add_u64 v[6:7], s[8:9], 0, v[164:165]
	s_add_i32 m0, s39, 0xc000
	ds_read_b128 v[148:151], v249
	ds_read_b128 v[152:155], v249 offset:1024
	ds_read_b128 v[156:159], v249 offset:2048
	ds_read_b128 v[168:171], v249 offset:3072
	ds_read_b128 v[172:175], v249 offset:4096
	ds_read_b128 v[190:193], v249 offset:5120
	ds_read_b128 v[194:197], v249 offset:6144
	ds_read_b128 v[198:201], v249 offset:7168
	global_load_lds_dwordx4 v[6:7], off
	s_add_i32 m0, s39, 0xe000
	v_lshl_add_u64 v[6:7], s[8:9], 0, v[166:167]
	global_load_lds_dwordx4 v[6:7], off
	s_waitcnt lgkmcnt(8)
	s_barrier
	s_waitcnt lgkmcnt(0)
	v_mfma_f32_16x16x32_bf16 v[80:83], v[132:135], v[148:151], 0
	v_mfma_f32_16x16x32_bf16 v[104:107], v[140:143], v[148:151], 0
	v_mfma_f32_16x16x32_bf16 v[128:131], v[132:135], v[156:159], 0
	v_mfma_f32_16x16x32_bf16 v[100:103], v[140:143], v[156:159], 0
	v_mfma_f32_16x16x32_bf16 v[124:127], v[132:135], v[172:175], 0
	v_mfma_f32_16x16x32_bf16 v[96:99], v[140:143], v[172:175], 0
	v_mfma_f32_16x16x32_bf16 v[120:123], v[132:135], v[194:197], 0
	v_mfma_f32_16x16x32_bf16 v[88:91], v[140:143], v[194:197], 0
	v_mfma_f32_16x16x32_bf16 v[80:83], v[136:139], v[152:155], v[80:83]
	v_mfma_f32_16x16x32_bf16 v[104:107], v[144:147], v[152:155], v[104:107]
	v_mfma_f32_16x16x32_bf16 v[128:131], v[136:139], v[168:171], v[128:131]
	v_mfma_f32_16x16x32_bf16 v[100:103], v[144:147], v[168:171], v[100:103]
	v_mfma_f32_16x16x32_bf16 v[124:127], v[136:139], v[190:193], v[124:127]
	v_mfma_f32_16x16x32_bf16 v[96:99], v[144:147], v[190:193], v[96:99]
	v_mfma_f32_16x16x32_bf16 v[120:123], v[136:139], v[198:201], v[120:123]
	v_mfma_f32_16x16x32_bf16 v[88:91], v[144:147], v[198:201], v[88:91]
	s_barrier
	s_add_i32 s70, 0, 0x14000
	s_add_i32 s0, s65, s34
	v_add_u32_e32 v4, s70, v245
	v_lshl_add_u64 v[176:177], s[28:29], 0, v[162:163]
	s_mov_b32 m0, s0
	ds_read_b128 v[202:205], v4
	ds_read_b128 v[206:209], v4 offset:1024
	ds_read_b128 v[210:213], v4 offset:2048
	ds_read_b128 v[214:217], v4 offset:3072
	global_load_lds_dwordx4 v[176:177], off
	s_add_i32 m0, s0, 0x2000
	v_lshl_add_u64 v[186:187], s[28:29], 0, v[160:161]
	global_load_lds_dwordx4 v[186:187], off
	s_barrier
	s_waitcnt lgkmcnt(0)
	v_mfma_f32_16x16x32_bf16 v[64:67], v[202:205], v[148:151], 0
	v_mfma_f32_16x16x32_bf16 v[32:35], v[210:213], v[148:151], 0
	v_mfma_f32_16x16x32_bf16 v[60:63], v[202:205], v[156:159], 0
	v_mfma_f32_16x16x32_bf16 v[28:31], v[210:213], v[156:159], 0
	v_mfma_f32_16x16x32_bf16 v[56:59], v[202:205], v[172:175], 0
	v_mfma_f32_16x16x32_bf16 v[24:27], v[210:213], v[172:175], 0
	v_mfma_f32_16x16x32_bf16 v[52:55], v[202:205], v[194:197], 0
	v_mfma_f32_16x16x32_bf16 v[20:23], v[210:213], v[194:197], 0
	v_mfma_f32_16x16x32_bf16 v[64:67], v[206:209], v[152:155], v[64:67]
	v_mfma_f32_16x16x32_bf16 v[32:35], v[214:217], v[152:155], v[32:35]
	v_mfma_f32_16x16x32_bf16 v[60:63], v[206:209], v[168:171], v[60:63]
	v_mfma_f32_16x16x32_bf16 v[28:31], v[214:217], v[168:171], v[28:31]
	v_mfma_f32_16x16x32_bf16 v[56:59], v[206:209], v[190:193], v[56:59]
	v_mfma_f32_16x16x32_bf16 v[24:27], v[214:217], v[190:193], v[24:27]
	v_mfma_f32_16x16x32_bf16 v[52:55], v[206:209], v[198:201], v[52:55]
	v_mfma_f32_16x16x32_bf16 v[20:23], v[214:217], v[198:201], v[20:23]
	s_mov_b32 m0, s39
	v_lshl_add_u64 v[218:219], s[26:27], 0, v[162:163]
	s_barrier
	ds_read_b128 v[148:151], v249 offset:16384
	ds_read_b128 v[152:155], v249 offset:17408
	ds_read_b128 v[156:159], v249 offset:18432
	ds_read_b128 v[168:171], v249 offset:19456
	ds_read_b128 v[172:175], v249 offset:20480
	ds_read_b128 v[190:193], v249 offset:21504
	ds_read_b128 v[194:197], v249 offset:22528
	ds_read_b128 v[198:201], v249 offset:23552
	global_load_lds_dwordx4 v[218:219], off
	s_mov_b32 m0, s40
	v_lshl_add_u64 v[220:221], s[26:27], 0, v[160:161]
	global_load_lds_dwordx4 v[220:221], off
	s_barrier
	s_waitcnt lgkmcnt(0)
	v_mfma_f32_16x16x32_bf16 v[92:95], v[132:135], v[148:151], 0
	v_mfma_f32_16x16x32_bf16 v[84:87], v[140:143], v[148:151], 0
	v_mfma_f32_16x16x32_bf16 v[116:119], v[132:135], v[156:159], 0
	v_mfma_f32_16x16x32_bf16 v[76:79], v[140:143], v[156:159], 0
	v_mfma_f32_16x16x32_bf16 v[112:115], v[132:135], v[172:175], 0
	v_mfma_f32_16x16x32_bf16 v[72:75], v[140:143], v[172:175], 0
	v_mfma_f32_16x16x32_bf16 v[108:111], v[132:135], v[194:197], 0
	v_mfma_f32_16x16x32_bf16 v[68:71], v[140:143], v[194:197], 0
	v_mfma_f32_16x16x32_bf16 v[92:95], v[136:139], v[152:155], v[92:95]
	v_mfma_f32_16x16x32_bf16 v[84:87], v[144:147], v[152:155], v[84:87]
	v_mfma_f32_16x16x32_bf16 v[116:119], v[136:139], v[168:171], v[116:119]
	v_mfma_f32_16x16x32_bf16 v[76:79], v[144:147], v[168:171], v[76:79]
	v_mfma_f32_16x16x32_bf16 v[112:115], v[136:139], v[190:193], v[112:115]
	v_mfma_f32_16x16x32_bf16 v[72:75], v[144:147], v[190:193], v[72:75]
	v_mfma_f32_16x16x32_bf16 v[108:111], v[136:139], v[198:201], v[108:111]
	v_mfma_f32_16x16x32_bf16 v[68:71], v[144:147], v[198:201], v[68:71]
	s_barrier
; #define PG8_STAGE(bufoff, gbase, voff) do { _Pragma("unroll") for (int _i = 0; _i < 2; ++_i) \
;         __builtin_amdgcn_global_load_lds((const unsigned*)((const char*)(gbase) + (voff)[_i]), (LAS unsigned*)(lds + (bufoff) + ldsw + _i * 8192), 16, 0, 0); } while (0)
; #define PG8_LDA(dst, b, h) do { _Pragma("unroll") for (int m = 0; m < 4; ++m) _Pragma("unroll") for (int k = 0; k < 2; ++k) dst[m][k] = *(const LAS bf16x8*)(lds + PG8_SA(b, h) + aoff + m * 2048 + k * 1024); } while (0)
; #define PG8_LDB(dst, b, h) do { _Pragma("unroll") for (int n = 0; n < 2; ++n) _Pragma("unroll") for (int k = 0; k < 2; ++k) dst[n][k] = *(const LAS bf16x8*)(lds + PG8_SB(b, h) + boff + n * 2048 + k * 1024); } while (0)
; #define PG8_MMA(ai, bj, At, Bt) do { __builtin_amdgcn_s_setprio(1); _Pragma("unroll") for (int m = 0; m < 4; ++m) _Pragma("unroll") for (int n = 0; n < 2; ++n) _Pragma("unroll") for (int k = 0; k < 2; ++k) \
;         acc[ai][bj][m][n] = __builtin_amdgcn_mfma_f32_16x16x32_bf16(Bt[n][k], At[m][k], acc[ai][bj][m][n], 0, 0, 0); __builtin_amdgcn_s_setprio(0); } while (0)
; #define PG8_WAIT_V(n) asm volatile("s_waitcnt vmcnt(" #n ")" ::: "memory")
; #define PG8_WAIT_L(n) asm volatile("s_waitcnt lgkmcnt(" #n ")" ::: "memory")
; #define PG8_BAR __builtin_amdgcn_s_barrier()
; #define PG8_SCHED __builtin_amdgcn_sched_barrier(0)
; template <class Epi>
; __device__ __forceinline__ void gemm_phase(LAS unsigned char* lds, const Gemm g, const StaticOrder& S, const Epi& E) {
;     ...
;             PG8_BAR; PG8_WAIT_L(0); PG8_MMA(1, 0, At, B0); PG8_BAR; PG8_SCHED;
;             PG8_STAGE(PG8_SB(0, 1), b2 + hstep, voffB);
;             PG8_WAIT_V(6); PG8_BAR; PG8_MMA(1, 1, At, B1); PG8_BAR;
;             PG8_LDB(B0, 1, 0); PG8_SCHED; PG8_LDA(At, 1, 0); PG8_STAGE(PG8_SA(0, 1), a2 + hstep, voffA);
;             PG8_WAIT_L(8); PG8_BAR; PG8_WAIT_L(0); PG8_MMA(0, 0, At, B0); PG8_BAR; PG8_SCHED;
;             PG8_LDB(B1, 1, 1); PG8_STAGE(PG8_SB(1, 0), b3, voffB);
;             PG8_BAR; PG8_WAIT_L(0); PG8_MMA(0, 1, At, B1); PG8_BAR;
	s_add_u32 s0, s28, s52
	s_addc_u32 s1, s29, 0
	s_add_i32 s28, s70, s34
	v_lshl_add_u64 v[222:223], s[0:1], 0, v[162:163]
	s_mov_b32 m0, s28
	v_lshl_add_u64 v[224:225], s[0:1], 0, v[160:161]
	global_load_lds_dwordx4 v[222:223], off
	s_add_i32 m0, s28, 0x2000
	s_nop 0
	global_load_lds_dwordx4 v[224:225], off
	s_waitcnt vmcnt(6)
	s_barrier
	v_mfma_f32_16x16x32_bf16 v[48:51], v[202:205], v[148:151], 0
	v_mfma_f32_16x16x32_bf16 v[16:19], v[210:213], v[148:151], 0
	v_mfma_f32_16x16x32_bf16 v[44:47], v[202:205], v[156:159], 0
	v_mfma_f32_16x16x32_bf16 v[12:15], v[210:213], v[156:159], 0
	v_mfma_f32_16x16x32_bf16 v[40:43], v[202:205], v[172:175], 0
	v_mfma_f32_16x16x32_bf16 v[6:9], v[210:213], v[172:175], 0
	v_mfma_f32_16x16x32_bf16 v[36:39], v[202:205], v[194:197], 0
	v_mfma_f32_16x16x32_bf16 v[0:3], v[210:213], v[194:197], 0
	v_mfma_f32_16x16x32_bf16 v[48:51], v[206:209], v[152:155], v[48:51]
	v_mfma_f32_16x16x32_bf16 v[16:19], v[214:217], v[152:155], v[16:19]
	v_mfma_f32_16x16x32_bf16 v[44:47], v[206:209], v[168:171], v[44:47]
	v_mfma_f32_16x16x32_bf16 v[12:15], v[214:217], v[168:171], v[12:15]
	v_mfma_f32_16x16x32_bf16 v[40:43], v[206:209], v[190:193], v[40:43]
	v_mfma_f32_16x16x32_bf16 v[6:9], v[214:217], v[190:193], v[6:9]
	v_mfma_f32_16x16x32_bf16 v[36:39], v[206:209], v[198:201], v[36:39]
	v_mfma_f32_16x16x32_bf16 v[0:3], v[214:217], v[198:201], v[0:3]
	s_add_i32 s28, 0, 0x18000
	v_add_u32_e32 v4, s28, v245
	s_barrier
	ds_read_b128 v[132:135], v4
	ds_read_b128 v[136:139], v4 offset:1024
	ds_read_b128 v[140:143], v4 offset:2048
	ds_read_b128 v[144:147], v4 offset:3072
	s_add_u32 s0, s26, s52
	s_addc_u32 s1, s27, 0
	s_mov_b32 m0, s41
	v_lshl_add_u64 v[10:11], s[0:1], 0, v[162:163]
	ds_read_b128 v[148:151], v249 offset:32768
	ds_read_b128 v[152:155], v249 offset:33792
	ds_read_b128 v[156:159], v249 offset:34816
	ds_read_b128 v[168:171], v249 offset:35840
	ds_read_b128 v[172:175], v249 offset:36864
	ds_read_b128 v[190:193], v249 offset:37888
	ds_read_b128 v[194:197], v249 offset:38912
	ds_read_b128 v[198:201], v249 offset:39936
	global_load_lds_dwordx4 v[10:11], off
	s_mov_b32 m0, s42
	v_lshl_add_u64 v[10:11], s[0:1], 0, v[160:161]
	global_load_lds_dwordx4 v[10:11], off
	s_waitcnt lgkmcnt(8)
	s_barrier
	s_waitcnt lgkmcnt(0)
	v_mfma_f32_16x16x32_bf16 v[80:83], v[132:135], v[148:151], v[80:83]
	v_mfma_f32_16x16x32_bf16 v[104:107], v[140:143], v[148:151], v[104:107]
	v_mfma_f32_16x16x32_bf16 v[128:131], v[132:135], v[156:159], v[128:131]
	v_mfma_f32_16x16x32_bf16 v[100:103], v[140:143], v[156:159], v[100:103]
	v_mfma_f32_16x16x32_bf16 v[124:127], v[132:135], v[172:175], v[124:127]
	v_mfma_f32_16x16x32_bf16 v[96:99], v[140:143], v[172:175], v[96:99]
	v_mfma_f32_16x16x32_bf16 v[120:123], v[132:135], v[194:197], v[120:123]
	v_mfma_f32_16x16x32_bf16 v[88:91], v[140:143], v[194:197], v[88:91]
	v_mfma_f32_16x16x32_bf16 v[80:83], v[136:139], v[152:155], v[80:83]
	v_mfma_f32_16x16x32_bf16 v[104:107], v[144:147], v[152:155], v[104:107]
	v_mfma_f32_16x16x32_bf16 v[128:131], v[136:139], v[168:171], v[128:131]
	v_mfma_f32_16x16x32_bf16 v[100:103], v[144:147], v[168:171], v[100:103]
	v_mfma_f32_16x16x32_bf16 v[124:127], v[136:139], v[190:193], v[124:127]
	v_mfma_f32_16x16x32_bf16 v[96:99], v[144:147], v[190:193], v[96:99]
	v_mfma_f32_16x16x32_bf16 v[120:123], v[136:139], v[198:201], v[120:123]
	v_mfma_f32_16x16x32_bf16 v[88:91], v[144:147], v[198:201], v[88:91]
	s_barrier
	s_add_i32 s0, 0, 0x1c000
	s_add_i32 s1, s28, s34
	v_add_u32_e32 v4, s0, v245
	v_lshl_add_u64 v[10:11], v[176:177], 0, s[86:87]
	s_mov_b32 m0, s1
	ds_read_b128 v[202:205], v4
	ds_read_b128 v[206:209], v4 offset:1024
	ds_read_b128 v[210:213], v4 offset:2048
	ds_read_b128 v[214:217], v4 offset:3072
	global_load_lds_dwordx4 v[10:11], off
	s_add_i32 m0, s1, 0x2000
	v_lshl_add_u64 v[10:11], v[186:187], 0, s[86:87]
	global_load_lds_dwordx4 v[10:11], off
	s_barrier
; #define PG8_STAGE(bufoff, gbase, voff) do { _Pragma("unroll") for (int _i = 0; _i < 2; ++_i) \
;         __builtin_amdgcn_global_load_lds((const unsigned*)((const char*)(gbase) + (voff)[_i]), (LAS unsigned*)(lds + (bufoff) + ldsw + _i * 8192), 16, 0, 0); } while (0)
; #define PG8_LDA(dst, b, h) do { _Pragma("unroll") for (int m = 0; m < 4; ++m) _Pragma("unroll") for (int k = 0; k < 2; ++k) dst[m][k] = *(const LAS bf16x8*)(lds + PG8_SA(b, h) + aoff + m * 2048 + k * 1024); } while (0)
; #define PG8_LDB(dst, b, h) do { _Pragma("unroll") for (int n = 0; n < 2; ++n) _Pragma("unroll") for (int k = 0; k < 2; ++k) dst[n][k] = *(const LAS bf16x8*)(lds + PG8_SB(b, h) + boff + n * 2048 + k * 1024); } while (0)
; #define PG8_MMA(ai, bj, At, Bt) do { __builtin_amdgcn_s_setprio(1); _Pragma("unroll") for (int m = 0; m < 4; ++m) _Pragma("unroll") for (int n = 0; n < 2; ++n) _Pragma("unroll") for (int k = 0; k < 2; ++k) \
;         acc[ai][bj][m][n] = __builtin_amdgcn_mfma_f32_16x16x32_bf16(Bt[n][k], At[m][k], acc[ai][bj][m][n], 0, 0, 0); __builtin_amdgcn_s_setprio(0); } while (0)
; #define PG8_WAIT_V(n) asm volatile("s_waitcnt vmcnt(" #n ")" ::: "memory")
; #define PG8_WAIT_L(n) asm volatile("s_waitcnt lgkmcnt(" #n ")" ::: "memory")
; #define PG8_BAR __builtin_amdgcn_s_barrier()
; #define PG8_SCHED __builtin_amdgcn_sched_barrier(0)
; template <class Epi>
; __device__ __forceinline__ void gemm_phase(LAS unsigned char* lds, const Gemm g, const StaticOrder& S, const Epi& E) {
;     ...
;             PG8_LDB(B1, 1, 1); PG8_STAGE(PG8_SB(1, 0), b3, voffB);
;             PG8_BAR; PG8_WAIT_L(0); PG8_MMA(0, 1, At, B1); PG8_BAR;
;             PG8_LDA(At, 1, 1); PG8_STAGE(PG8_SA(1, 0), a3, voffA);
;             PG8_BAR; PG8_WAIT_L(0); PG8_MMA(1, 0, At, B0); PG8_BAR; PG8_SCHED;
;             PG8_STAGE(PG8_SB(1, 1), b3 + hstep, voffB);
;             PG8_WAIT_V(6); PG8_BAR; PG8_MMA(1, 1, At, B1); PG8_BAR;
	s_waitcnt lgkmcnt(0)
	v_mfma_f32_16x16x32_bf16 v[64:67], v[202:205], v[148:151], v[64:67]
	v_mfma_f32_16x16x32_bf16 v[32:35], v[210:213], v[148:151], v[32:35]
	v_mfma_f32_16x16x32_bf16 v[60:63], v[202:205], v[156:159], v[60:63]
	v_mfma_f32_16x16x32_bf16 v[28:31], v[210:213], v[156:159], v[28:31]
	v_mfma_f32_16x16x32_bf16 v[56:59], v[202:205], v[172:175], v[56:59]
	v_mfma_f32_16x16x32_bf16 v[24:27], v[210:213], v[172:175], v[24:27]
	v_mfma_f32_16x16x32_bf16 v[52:55], v[202:205], v[194:197], v[52:55]
	v_mfma_f32_16x16x32_bf16 v[20:23], v[210:213], v[194:197], v[20:23]
	v_mfma_f32_16x16x32_bf16 v[64:67], v[206:209], v[152:155], v[64:67]
	v_mfma_f32_16x16x32_bf16 v[32:35], v[214:217], v[152:155], v[32:35]
	v_mfma_f32_16x16x32_bf16 v[60:63], v[206:209], v[168:171], v[60:63]
	v_mfma_f32_16x16x32_bf16 v[28:31], v[214:217], v[168:171], v[28:31]
	v_mfma_f32_16x16x32_bf16 v[56:59], v[206:209], v[190:193], v[56:59]
	v_mfma_f32_16x16x32_bf16 v[24:27], v[214:217], v[190:193], v[24:27]
	v_mfma_f32_16x16x32_bf16 v[52:55], v[206:209], v[198:201], v[52:55]
	v_mfma_f32_16x16x32_bf16 v[20:23], v[214:217], v[198:201], v[20:23]
	s_mov_b32 m0, s55
	v_lshl_add_u64 v[10:11], v[218:219], 0, s[86:87]
	s_barrier
	ds_read_b128 v[148:151], v249 offset:49152
	ds_read_b128 v[152:155], v249 offset:50176
	ds_read_b128 v[156:159], v249 offset:51200
	ds_read_b128 v[168:171], v249 offset:52224
	ds_read_b128 v[172:175], v249 offset:53248
	ds_read_b128 v[190:193], v249 offset:54272
	ds_read_b128 v[194:197], v249 offset:55296
	ds_read_b128 v[198:201], v249 offset:56320
	global_load_lds_dwordx4 v[10:11], off
	s_mov_b32 m0, s56
	v_lshl_add_u64 v[10:11], v[220:221], 0, s[86:87]
	global_load_lds_dwordx4 v[10:11], off
	s_barrier
	s_waitcnt lgkmcnt(0)
	v_mfma_f32_16x16x32_bf16 v[92:95], v[132:135], v[148:151], v[92:95]
	v_mfma_f32_16x16x32_bf16 v[84:87], v[140:143], v[148:151], v[84:87]
	v_mfma_f32_16x16x32_bf16 v[116:119], v[132:135], v[156:159], v[116:119]
	v_mfma_f32_16x16x32_bf16 v[76:79], v[140:143], v[156:159], v[76:79]
	v_mfma_f32_16x16x32_bf16 v[112:115], v[132:135], v[172:175], v[112:115]
	v_mfma_f32_16x16x32_bf16 v[72:75], v[140:143], v[172:175], v[72:75]
	v_mfma_f32_16x16x32_bf16 v[108:111], v[132:135], v[194:197], v[108:111]
	v_mfma_f32_16x16x32_bf16 v[68:71], v[140:143], v[194:197], v[68:71]
	v_mfma_f32_16x16x32_bf16 v[92:95], v[136:139], v[152:155], v[92:95]
	v_mfma_f32_16x16x32_bf16 v[84:87], v[144:147], v[152:155], v[84:87]
	v_mfma_f32_16x16x32_bf16 v[116:119], v[136:139], v[168:171], v[116:119]
	v_mfma_f32_16x16x32_bf16 v[76:79], v[144:147], v[168:171], v[76:79]
	v_mfma_f32_16x16x32_bf16 v[112:115], v[136:139], v[190:193], v[112:115]
	v_mfma_f32_16x16x32_bf16 v[72:75], v[144:147], v[190:193], v[72:75]
	v_mfma_f32_16x16x32_bf16 v[108:111], v[136:139], v[198:201], v[108:111]
	v_mfma_f32_16x16x32_bf16 v[68:71], v[144:147], v[198:201], v[68:71]
	s_barrier
	s_add_i32 s0, s0, s34
	s_mov_b32 m0, s0
	v_lshl_add_u64 v[10:11], v[222:223], 0, s[86:87]
	global_load_lds_dwordx4 v[10:11], off
	s_add_i32 m0, s0, 0x2000
	v_lshl_add_u64 v[10:11], v[224:225], 0, s[86:87]
	global_load_lds_dwordx4 v[10:11], off
	s_waitcnt vmcnt(6)
	s_barrier
	v_mfma_f32_16x16x32_bf16 v[48:51], v[202:205], v[148:151], v[48:51]
	v_mfma_f32_16x16x32_bf16 v[16:19], v[210:213], v[148:151], v[16:19]
	v_mfma_f32_16x16x32_bf16 v[44:47], v[202:205], v[156:159], v[44:47]
	v_mfma_f32_16x16x32_bf16 v[10:13], v[210:213], v[156:159], v[12:15]
	v_mfma_f32_16x16x32_bf16 v[40:43], v[202:205], v[172:175], v[40:43]
	v_mfma_f32_16x16x32_bf16 v[6:9], v[210:213], v[172:175], v[6:9]
	v_mfma_f32_16x16x32_bf16 v[36:39], v[202:205], v[194:197], v[36:39]
	v_mfma_f32_16x16x32_bf16 v[0:3], v[210:213], v[194:197], v[0:3]
	v_mfma_f32_16x16x32_bf16 v[48:51], v[206:209], v[152:155], v[48:51]
	v_mfma_f32_16x16x32_bf16 v[16:19], v[214:217], v[152:155], v[16:19]
	v_mfma_f32_16x16x32_bf16 v[44:47], v[206:209], v[168:171], v[44:47]
	v_mfma_f32_16x16x32_bf16 v[12:15], v[214:217], v[168:171], v[10:13]
	v_mfma_f32_16x16x32_bf16 v[40:43], v[206:209], v[190:193], v[40:43]
	v_mfma_f32_16x16x32_bf16 v[8:11], v[214:217], v[190:193], v[6:9]
	v_mfma_f32_16x16x32_bf16 v[36:39], v[206:209], v[198:201], v[36:39]
	v_mfma_f32_16x16x32_bf16 v[0:3], v[214:217], v[198:201], v[0:3]
	s_add_u32 s8, s8, 0x100
	s_addc_u32 s9, s9, 0
	s_add_u32 s62, s62, 0x100
	s_addc_u32 s63, s63, 0
	s_cmp_ge_u32 s64, s49
	s_mov_b32 s26, s64
	s_barrier
	s_cbranch_scc1 .Lpeel_exit_0

;     __device__ __forceinline__ void operator()(const f32x4 (&acc)[2][2][4][2], const Unit& u, int wr, int wc, int fr, int fq) const {
;         const int row0 = u.pm * 256 + wr * 64 + fr, col0 = u.pn * 256 + wc * 32 + 4 * fq;
;         const float* mvp = mv + (size_t)(u.pm >> 3) * 9216 + col0;
;         const float fac = __builtin_amdgcn_readfirstlane(ffn) ? 0.5f : 1.f;
;         const bool hb = __builtin_amdgcn_readfirstlane(has_next) != 0;
;         f32x4 rs0 = (f32x4){0.f, 0.f, 0.f, 0.f}, rs1 = rs0;
; #pragma unroll
;         for (int bj = 0; bj < 2; ++bj)
; #pragma unroll
;             for (int n = 0; n < 2; ++n) {
;                 const int co = bj * 128 + n * 16;
;                 const f32x4 mvv = *(const f32x4*)(mvp + co) * fac;
;                 f32x4 gn = (f32x4){0.f, 0.f, 0.f, 0.f};
;                 if (hb) gn = *(const f32x4*)(nwn + col0 + co) * (*(const f32x4*)(scn + (size_t)(u.pm >> 3) * 9216 + col0 + co) + 1.f);
.Lpeel_exit_0:
	s_setprio 0
	s_ashr_i32 s0, s60, 3
	s_mul_i32 s29, s0, 0x9000
	v_lshl_or_b32 v170, s61, 8, v248
	s_mul_hi_i32 s28, s0, 0x9000
	s_add_u32 s0, s50, s29
	s_addc_u32 s1, s51, s28
	v_ashrrev_i32_e32 v171, 31, v170
	v_lshl_add_u64 v[176:177], v[170:171], 2, s[0:1]
	global_load_dwordx4 v[132:135], v[176:177], off
	v_readfirstlane_b32 s0, v243
	s_cmp_lg_u32 s0, 0
	v_lshlrev_b64 v[168:169], 2, v[170:171]
	v_readfirstlane_b32 s8, v242
	s_cselect_b64 s[26:27], -1, 0
	s_cmp_eq_u32 s0, 0
	v_lshl_add_u64 v[190:191], s[18:19], 0, v[168:169]
	s_cbranch_scc1 .LBB0_2977
	s_add_u32 s0, s43, s29
	s_addc_u32 s1, s48, s28
	v_lshl_add_u64 v[6:7], s[0:1], 0, v[168:169]
	global_load_dwordx4 v[136:139], v[6:7], off
	global_load_dwordx4 v[140:143], v[190:191], off
	s_waitcnt vmcnt(0)
	v_pk_add_f32 v[6:7], v[138:139], 1.0 op_sel_hi:[1,0]
	v_pk_add_f32 v[136:137], v[136:137], 1.0 op_sel_hi:[1,0]
	v_pk_mul_f32 v[218:219], v[142:143], v[6:7]
	v_pk_mul_f32 v[216:217], v[140:141], v[136:137]
	s_branch .LBB0_2978
